# v16 + GEMM super-phases: s_setprio 1 before the opening barrier, redundant lgkmcnt(0) after it dropped, s_setprio 0 after the closing barrier (only MFMAs between the two barriers)
# speedup vs baseline: 1.0195x; 1.0195x over previous
.LBB0_394:
	s_add_u32 s0, s24, 0xfff80080
	s_addc_u32 s1, s25, -1
	s_add_i32 s33, 0, 0x10000
	s_cmp_eq_u32 s60, 28
	s_cselect_b32 s29, s7, s1
	s_cselect_b32 s28, s19, s0
	s_cselect_b32 s27, s17, s59
	s_cselect_b32 s26, s49, s58
	s_add_i32 s55, 0, 0x14000
	v_add_u32_e32 v158, s33, v151
	v_add_u32_e32 v174, s55, v151
	ds_read_b128 v[142:145], v158
	ds_read_b128 v[146:149], v158 offset:1024
	ds_read_b128 v[154:157], v158 offset:2048
	ds_read_b128 v[158:161], v158 offset:3072
	ds_read_b128 v[162:165], v174
	ds_read_b128 v[166:169], v174 offset:1024
	ds_read_b128 v[170:173], v174 offset:2048
	ds_read_b128 v[174:177], v174 offset:3072
	v_lshl_add_u64 v[204:205], s[24:25], 0, v[138:139]
	s_add_i32 m0, s9, 0xc000
	ds_read_b128 v[178:181], v153
	ds_read_b128 v[182:185], v153 offset:1024
	ds_read_b128 v[186:189], v153 offset:2048
	ds_read_b128 v[190:193], v153 offset:3072
	ds_read_b128 v[194:197], v153 offset:4096
	ds_read_b128 v[198:201], v153 offset:5120
	ds_read_b128 v[208:211], v153 offset:6144
	ds_read_b128 v[212:215], v153 offset:7168
	global_load_lds_dwordx4 v[204:205], off
	v_lshl_add_u64 v[204:205], s[24:25], 0, v[140:141]
	s_add_i32 m0, s9, 0xe000
	s_nop 0
	global_load_lds_dwordx4 v[204:205], off
	s_waitcnt vmcnt(8)
	s_waitcnt lgkmcnt(0)
	s_setprio 1
	s_barrier
	v_mfma_f32_16x16x32_bf16 v[126:129], v[142:145], v[178:181], v[126:129]
	v_mfma_f32_16x16x32_bf16 v[122:125], v[154:157], v[178:181], v[122:125]
	v_mfma_f32_16x16x32_bf16 v[110:113], v[142:145], v[186:189], v[110:113]
	v_mfma_f32_16x16x32_bf16 v[106:109], v[154:157], v[186:189], v[106:109]
	v_mfma_f32_16x16x32_bf16 v[94:97], v[142:145], v[194:197], v[94:97]
	v_mfma_f32_16x16x32_bf16 v[90:93], v[154:157], v[194:197], v[90:93]
	v_mfma_f32_16x16x32_bf16 v[78:81], v[142:145], v[208:211], v[78:81]
	v_mfma_f32_16x16x32_bf16 v[74:77], v[154:157], v[208:211], v[74:77]
	v_mfma_f32_16x16x32_bf16 v[126:129], v[146:149], v[182:185], v[126:129]
	v_mfma_f32_16x16x32_bf16 v[122:125], v[158:161], v[182:185], v[122:125]
	v_mfma_f32_16x16x32_bf16 v[110:113], v[146:149], v[190:193], v[110:113]
	v_mfma_f32_16x16x32_bf16 v[106:109], v[158:161], v[190:193], v[106:109]
	v_mfma_f32_16x16x32_bf16 v[94:97], v[146:149], v[198:201], v[94:97]
	v_mfma_f32_16x16x32_bf16 v[90:93], v[158:161], v[198:201], v[90:93]
	v_mfma_f32_16x16x32_bf16 v[78:81], v[146:149], v[212:215], v[78:81]
	v_mfma_f32_16x16x32_bf16 v[74:77], v[158:161], v[212:215], v[74:77]
	s_setprio 0
	s_setprio 1
	v_mfma_f32_16x16x32_bf16 v[118:121], v[162:165], v[178:181], v[118:121]
	v_mfma_f32_16x16x32_bf16 v[114:117], v[170:173], v[178:181], v[114:117]
	v_mfma_f32_16x16x32_bf16 v[102:105], v[162:165], v[186:189], v[102:105]
	v_mfma_f32_16x16x32_bf16 v[98:101], v[170:173], v[186:189], v[98:101]
	v_mfma_f32_16x16x32_bf16 v[86:89], v[162:165], v[194:197], v[86:89]
	v_mfma_f32_16x16x32_bf16 v[82:85], v[170:173], v[194:197], v[82:85]
	v_mfma_f32_16x16x32_bf16 v[70:73], v[162:165], v[208:211], v[70:73]
	v_mfma_f32_16x16x32_bf16 v[66:69], v[170:173], v[208:211], v[66:69]
	v_mfma_f32_16x16x32_bf16 v[118:121], v[166:169], v[182:185], v[118:121]
	v_mfma_f32_16x16x32_bf16 v[114:117], v[174:177], v[182:185], v[114:117]
	v_mfma_f32_16x16x32_bf16 v[102:105], v[166:169], v[190:193], v[102:105]
	v_mfma_f32_16x16x32_bf16 v[98:101], v[174:177], v[190:193], v[98:101]
	v_mfma_f32_16x16x32_bf16 v[86:89], v[166:169], v[198:201], v[86:89]
	v_mfma_f32_16x16x32_bf16 v[82:85], v[174:177], v[198:201], v[82:85]
	v_mfma_f32_16x16x32_bf16 v[70:73], v[166:169], v[212:215], v[70:73]
	v_mfma_f32_16x16x32_bf16 v[66:69], v[174:177], v[212:215], v[66:69]
	s_barrier
	s_setprio 0
	s_add_i32 s0, s33, s34
	v_lshl_add_u64 v[204:205], s[26:27], 0, v[132:133]
	s_mov_b32 m0, s0
	ds_read_b128 v[178:181], v153 offset:16384
	ds_read_b128 v[182:185], v153 offset:17408
	ds_read_b128 v[186:189], v153 offset:18432
	ds_read_b128 v[190:193], v153 offset:19456
	ds_read_b128 v[194:197], v153 offset:20480
	ds_read_b128 v[198:201], v153 offset:21504
	ds_read_b128 v[208:211], v153 offset:22528
	ds_read_b128 v[212:215], v153 offset:23552
	global_load_lds_dwordx4 v[204:205], off
	s_add_i32 m0, s0, 0x2000
	s_add_u32 s0, s26, 0x80000
	v_lshl_add_u64 v[216:217], s[26:27], 0, v[136:137]
	s_addc_u32 s1, s27, 0
	s_add_i32 s33, s55, s34
	global_load_lds_dwordx4 v[216:217], off
	v_lshl_add_u64 v[218:219], s[0:1], 0, v[132:133]
	s_mov_b32 m0, s33
	v_lshl_add_u64 v[220:221], s[28:29], 0, v[134:135]
	global_load_lds_dwordx4 v[218:219], off
	v_lshl_add_u64 v[218:219], s[0:1], 0, v[136:137]
	s_add_i32 m0, s33, 0x2000
	s_nop 0
	global_load_lds_dwordx4 v[218:219], off
	v_lshl_add_u64 v[218:219], s[28:29], 0, v[130:131]
	s_mov_b32 m0, s9
	s_nop 0
	global_load_lds_dwordx4 v[218:219], off
	s_mov_b32 m0, s35
	s_nop 0
	global_load_lds_dwordx4 v[220:221], off
	s_waitcnt vmcnt(8)
	s_waitcnt lgkmcnt(0)
	s_setprio 1
	s_barrier
	v_mfma_f32_16x16x32_bf16 v[62:65], v[142:145], v[178:181], v[62:65]
	v_mfma_f32_16x16x32_bf16 v[58:61], v[154:157], v[178:181], v[58:61]
	v_mfma_f32_16x16x32_bf16 v[46:49], v[142:145], v[186:189], v[46:49]
	v_mfma_f32_16x16x32_bf16 v[42:45], v[154:157], v[186:189], v[42:45]
	v_mfma_f32_16x16x32_bf16 v[30:33], v[142:145], v[194:197], v[30:33]
	v_mfma_f32_16x16x32_bf16 v[26:29], v[154:157], v[194:197], v[26:29]
	v_mfma_f32_16x16x32_bf16 v[14:17], v[142:145], v[208:211], v[14:17]
	v_mfma_f32_16x16x32_bf16 v[10:13], v[154:157], v[208:211], v[10:13]
	v_mfma_f32_16x16x32_bf16 v[62:65], v[146:149], v[182:185], v[62:65]
	v_mfma_f32_16x16x32_bf16 v[58:61], v[158:161], v[182:185], v[58:61]
	v_mfma_f32_16x16x32_bf16 v[46:49], v[146:149], v[190:193], v[46:49]
	v_mfma_f32_16x16x32_bf16 v[42:45], v[158:161], v[190:193], v[42:45]
	v_mfma_f32_16x16x32_bf16 v[30:33], v[146:149], v[198:201], v[30:33]
	v_mfma_f32_16x16x32_bf16 v[26:29], v[158:161], v[198:201], v[26:29]
	v_mfma_f32_16x16x32_bf16 v[14:17], v[146:149], v[212:215], v[14:17]
	v_mfma_f32_16x16x32_bf16 v[10:13], v[158:161], v[212:215], v[10:13]
	s_setprio 0
	s_setprio 1
	v_mfma_f32_16x16x32_bf16 v[54:57], v[162:165], v[178:181], v[54:57]
	v_mfma_f32_16x16x32_bf16 v[50:53], v[170:173], v[178:181], v[50:53]
	v_mfma_f32_16x16x32_bf16 v[38:41], v[162:165], v[186:189], v[38:41]
	v_mfma_f32_16x16x32_bf16 v[34:37], v[170:173], v[186:189], v[34:37]
	v_mfma_f32_16x16x32_bf16 v[22:25], v[162:165], v[194:197], v[22:25]
	v_mfma_f32_16x16x32_bf16 v[18:21], v[170:173], v[194:197], v[18:21]
	v_mfma_f32_16x16x32_bf16 v[6:9], v[162:165], v[208:211], v[6:9]
	v_mfma_f32_16x16x32_bf16 v[2:5], v[170:173], v[208:211], v[2:5]
	v_mfma_f32_16x16x32_bf16 v[54:57], v[166:169], v[182:185], v[54:57]
	v_mfma_f32_16x16x32_bf16 v[50:53], v[174:177], v[182:185], v[50:53]
	v_mfma_f32_16x16x32_bf16 v[38:41], v[166:169], v[190:193], v[38:41]
	v_mfma_f32_16x16x32_bf16 v[34:37], v[174:177], v[190:193], v[34:37]
	v_mfma_f32_16x16x32_bf16 v[22:25], v[166:169], v[198:201], v[22:25]
	v_mfma_f32_16x16x32_bf16 v[18:21], v[174:177], v[198:201], v[18:21]
	v_mfma_f32_16x16x32_bf16 v[6:9], v[166:169], v[212:215], v[6:9]
	v_mfma_f32_16x16x32_bf16 v[2:5], v[174:177], v[212:215], v[2:5]
	s_barrier
	s_setprio 0
	s_add_i32 s33, 0, 0x18000
	s_add_i32 s55, 0, 0x1c000
	v_add_u32_e32 v158, s33, v151
	v_add_u32_e32 v174, s55, v151
	ds_read_b128 v[142:145], v158
	ds_read_b128 v[146:149], v158 offset:1024
	ds_read_b128 v[154:157], v158 offset:2048
	ds_read_b128 v[158:161], v158 offset:3072
	ds_read_b128 v[162:165], v174
	ds_read_b128 v[166:169], v174 offset:1024
	ds_read_b128 v[170:173], v174 offset:2048
	ds_read_b128 v[174:177], v174 offset:3072
	s_add_u32 s0, s28, 0x80000
	s_addc_u32 s1, s29, 0
	s_mov_b32 m0, s36
	v_lshl_add_u64 v[222:223], s[0:1], 0, v[130:131]
	ds_read_b128 v[178:181], v153 offset:32768
	ds_read_b128 v[182:185], v153 offset:33792
	ds_read_b128 v[186:189], v153 offset:34816
	ds_read_b128 v[190:193], v153 offset:35840
	ds_read_b128 v[194:197], v153 offset:36864
	ds_read_b128 v[198:201], v153 offset:37888
	ds_read_b128 v[208:211], v153 offset:38912
	ds_read_b128 v[212:215], v153 offset:39936
	global_load_lds_dwordx4 v[222:223], off
	v_lshl_add_u64 v[222:223], s[0:1], 0, v[134:135]
	s_mov_b32 m0, s37
	s_nop 0
	global_load_lds_dwordx4 v[222:223], off
	s_waitcnt vmcnt(8)
	s_waitcnt lgkmcnt(0)
	s_setprio 1
	s_barrier
	v_mfma_f32_16x16x32_bf16 v[126:129], v[142:145], v[178:181], v[126:129]
	v_mfma_f32_16x16x32_bf16 v[122:125], v[154:157], v[178:181], v[122:125]
	v_mfma_f32_16x16x32_bf16 v[110:113], v[142:145], v[186:189], v[110:113]
	v_mfma_f32_16x16x32_bf16 v[106:109], v[154:157], v[186:189], v[106:109]
	v_mfma_f32_16x16x32_bf16 v[94:97], v[142:145], v[194:197], v[94:97]
	v_mfma_f32_16x16x32_bf16 v[90:93], v[154:157], v[194:197], v[90:93]
	v_mfma_f32_16x16x32_bf16 v[78:81], v[142:145], v[208:211], v[78:81]
	v_mfma_f32_16x16x32_bf16 v[74:77], v[154:157], v[208:211], v[74:77]
	v_mfma_f32_16x16x32_bf16 v[126:129], v[146:149], v[182:185], v[126:129]
	v_mfma_f32_16x16x32_bf16 v[122:125], v[158:161], v[182:185], v[122:125]
	v_mfma_f32_16x16x32_bf16 v[110:113], v[146:149], v[190:193], v[110:113]
	v_mfma_f32_16x16x32_bf16 v[106:109], v[158:161], v[190:193], v[106:109]
	v_mfma_f32_16x16x32_bf16 v[94:97], v[146:149], v[198:201], v[94:97]
	v_mfma_f32_16x16x32_bf16 v[90:93], v[158:161], v[198:201], v[90:93]
	v_mfma_f32_16x16x32_bf16 v[78:81], v[146:149], v[212:215], v[78:81]
	v_mfma_f32_16x16x32_bf16 v[74:77], v[158:161], v[212:215], v[74:77]
	s_setprio 0
	s_setprio 1
	v_mfma_f32_16x16x32_bf16 v[118:121], v[162:165], v[178:181], v[118:121]
	v_mfma_f32_16x16x32_bf16 v[114:117], v[170:173], v[178:181], v[114:117]
	v_mfma_f32_16x16x32_bf16 v[102:105], v[162:165], v[186:189], v[102:105]
	v_mfma_f32_16x16x32_bf16 v[98:101], v[170:173], v[186:189], v[98:101]
	v_mfma_f32_16x16x32_bf16 v[86:89], v[162:165], v[194:197], v[86:89]
	v_mfma_f32_16x16x32_bf16 v[82:85], v[170:173], v[194:197], v[82:85]
	v_mfma_f32_16x16x32_bf16 v[70:73], v[162:165], v[208:211], v[70:73]
	v_mfma_f32_16x16x32_bf16 v[66:69], v[170:173], v[208:211], v[66:69]
	v_mfma_f32_16x16x32_bf16 v[118:121], v[166:169], v[182:185], v[118:121]
	v_mfma_f32_16x16x32_bf16 v[114:117], v[174:177], v[182:185], v[114:117]
	v_mfma_f32_16x16x32_bf16 v[102:105], v[166:169], v[190:193], v[102:105]
	v_mfma_f32_16x16x32_bf16 v[98:101], v[174:177], v[190:193], v[98:101]
	v_mfma_f32_16x16x32_bf16 v[86:89], v[166:169], v[198:201], v[86:89]
	v_mfma_f32_16x16x32_bf16 v[82:85], v[174:177], v[198:201], v[82:85]
	v_mfma_f32_16x16x32_bf16 v[70:73], v[166:169], v[212:215], v[70:73]
	v_mfma_f32_16x16x32_bf16 v[66:69], v[174:177], v[212:215], v[66:69]
	s_barrier
	s_setprio 0
	s_add_i32 s0, s33, s34
	v_lshl_add_u64 v[204:205], v[204:205], 0, s[80:81]
	s_mov_b32 m0, s0
	ds_read_b128 v[178:181], v153 offset:49152
	ds_read_b128 v[182:185], v153 offset:50176
	ds_read_b128 v[186:189], v153 offset:51200
	ds_read_b128 v[190:193], v153 offset:52224
	ds_read_b128 v[194:197], v153 offset:53248
	ds_read_b128 v[198:201], v153 offset:54272
	ds_read_b128 v[208:211], v153 offset:55296
	ds_read_b128 v[212:215], v153 offset:56320
	global_load_lds_dwordx4 v[204:205], off
	s_add_i32 m0, s0, 0x2000
	s_add_u32 s0, s26, 0x80080
	v_lshl_add_u64 v[204:205], v[216:217], 0, s[80:81]
	s_addc_u32 s1, s27, 0
	s_add_i32 s26, s55, s34
	global_load_lds_dwordx4 v[204:205], off
	v_lshl_add_u64 v[204:205], s[0:1], 0, v[132:133]
	s_mov_b32 m0, s26
	s_nop 0
	global_load_lds_dwordx4 v[204:205], off
	v_lshl_add_u64 v[204:205], s[0:1], 0, v[136:137]
	s_add_i32 m0, s26, 0x2000
	s_nop 0
	global_load_lds_dwordx4 v[204:205], off
	v_lshl_add_u64 v[204:205], v[218:219], 0, s[80:81]
	s_mov_b32 m0, s39
	s_nop 0
	global_load_lds_dwordx4 v[204:205], off
	v_lshl_add_u64 v[204:205], v[220:221], 0, s[80:81]
	s_mov_b32 m0, s40
	s_nop 0
	global_load_lds_dwordx4 v[204:205], off
	s_waitcnt vmcnt(8)
	s_waitcnt lgkmcnt(0)
	s_setprio 1
	s_barrier
	v_mfma_f32_16x16x32_bf16 v[62:65], v[142:145], v[178:181], v[62:65]
	v_mfma_f32_16x16x32_bf16 v[58:61], v[154:157], v[178:181], v[58:61]
	v_mfma_f32_16x16x32_bf16 v[46:49], v[142:145], v[186:189], v[46:49]
	v_mfma_f32_16x16x32_bf16 v[42:45], v[154:157], v[186:189], v[42:45]
	v_mfma_f32_16x16x32_bf16 v[30:33], v[142:145], v[194:197], v[30:33]
	v_mfma_f32_16x16x32_bf16 v[26:29], v[154:157], v[194:197], v[26:29]
	v_mfma_f32_16x16x32_bf16 v[14:17], v[142:145], v[208:211], v[14:17]
	v_mfma_f32_16x16x32_bf16 v[10:13], v[154:157], v[208:211], v[10:13]
	v_mfma_f32_16x16x32_bf16 v[62:65], v[146:149], v[182:185], v[62:65]
	v_mfma_f32_16x16x32_bf16 v[58:61], v[158:161], v[182:185], v[58:61]
	v_mfma_f32_16x16x32_bf16 v[46:49], v[146:149], v[190:193], v[46:49]
	v_mfma_f32_16x16x32_bf16 v[42:45], v[158:161], v[190:193], v[42:45]
	v_mfma_f32_16x16x32_bf16 v[30:33], v[146:149], v[198:201], v[30:33]
	v_mfma_f32_16x16x32_bf16 v[26:29], v[158:161], v[198:201], v[26:29]
	v_mfma_f32_16x16x32_bf16 v[14:17], v[146:149], v[212:215], v[14:17]
	v_mfma_f32_16x16x32_bf16 v[10:13], v[158:161], v[212:215], v[10:13]
	s_setprio 0
	s_setprio 1
	v_mfma_f32_16x16x32_bf16 v[54:57], v[162:165], v[178:181], v[54:57]
	v_mfma_f32_16x16x32_bf16 v[50:53], v[170:173], v[178:181], v[50:53]
	v_mfma_f32_16x16x32_bf16 v[38:41], v[162:165], v[186:189], v[38:41]
	v_mfma_f32_16x16x32_bf16 v[34:37], v[170:173], v[186:189], v[34:37]
	v_mfma_f32_16x16x32_bf16 v[22:25], v[162:165], v[194:197], v[22:25]
	v_mfma_f32_16x16x32_bf16 v[18:21], v[170:173], v[194:197], v[18:21]
	v_mfma_f32_16x16x32_bf16 v[6:9], v[162:165], v[208:211], v[6:9]
	v_mfma_f32_16x16x32_bf16 v[2:5], v[170:173], v[208:211], v[2:5]
	v_mfma_f32_16x16x32_bf16 v[54:57], v[166:169], v[182:185], v[54:57]
	v_mfma_f32_16x16x32_bf16 v[50:53], v[174:177], v[182:185], v[50:53]
	v_mfma_f32_16x16x32_bf16 v[38:41], v[166:169], v[190:193], v[38:41]
	v_mfma_f32_16x16x32_bf16 v[34:37], v[174:177], v[190:193], v[34:37]
	v_mfma_f32_16x16x32_bf16 v[22:25], v[166:169], v[198:201], v[22:25]
	v_mfma_f32_16x16x32_bf16 v[18:21], v[174:177], v[198:201], v[18:21]
	v_mfma_f32_16x16x32_bf16 v[6:9], v[166:169], v[212:215], v[6:9]
	v_mfma_f32_16x16x32_bf16 v[2:5], v[174:177], v[212:215], v[2:5]
	s_barrier
	s_setprio 0
	s_add_i32 s60, s60, 2
	s_add_u32 s24, s24, 0x100
	s_addc_u32 s25, s25, 0
	s_add_u32 s58, s58, 0x100
	s_addc_u32 s59, s59, 0
	s_cmp_gt_u32 s60, 29
	s_cbranch_scc0 .LBB0_394
	s_and_b64 vcc, exec, s[14:15]
	s_cbranch_vccz .LBB0_397
	s_barrier

.LBB0_692:
	s_add_u32 s0, s18, 0xfff00080
	s_addc_u32 s1, s19, -1
	s_add_i32 s33, 0, 0x10000
	s_cmp_eq_u32 s61, 60
	s_cselect_b32 s23, s11, s1
	s_cselect_b32 s22, s49, s0
	s_cselect_b32 s21, s9, s60
	s_cselect_b32 s20, s58, s59
	s_add_i32 s55, 0, 0x14000
	v_add_u32_e32 v98, s33, v205
	v_add_u32_e32 v134, s55, v205
	ds_read_b128 v[78:81], v98
	ds_read_b128 v[86:89], v98 offset:1024
	ds_read_b128 v[94:97], v98 offset:2048
	ds_read_b128 v[98:101], v98 offset:3072
	ds_read_b128 v[106:109], v134
	ds_read_b128 v[110:113], v134 offset:1024
	ds_read_b128 v[126:129], v134 offset:2048
	ds_read_b128 v[134:137], v134 offset:3072
	v_lshl_add_u64 v[194:195], s[18:19], 0, v[214:215]
	s_add_i32 m0, s27, 0xc000
	ds_read_b128 v[146:149], v239
	ds_read_b128 v[158:161], v239 offset:1024
	ds_read_b128 v[166:169], v239 offset:2048
	ds_read_b128 v[174:177], v239 offset:3072
	ds_read_b128 v[178:181], v239 offset:4096
	ds_read_b128 v[182:185], v239 offset:5120
	ds_read_b128 v[186:189], v239 offset:6144
	ds_read_b128 v[190:193], v239 offset:7168
	global_load_lds_dwordx4 v[194:195], off
	v_lshl_add_u64 v[194:195], s[18:19], 0, v[216:217]
	s_add_i32 m0, s27, 0xe000
	s_nop 0
	global_load_lds_dwordx4 v[194:195], off
	s_waitcnt vmcnt(8)
	s_waitcnt lgkmcnt(0)
	s_setprio 1
	s_barrier
	v_mfma_f32_16x16x32_bf16 v[170:173], v[78:81], v[146:149], v[170:173]
	v_mfma_f32_16x16x32_bf16 v[162:165], v[94:97], v[146:149], v[162:165]
	v_mfma_f32_16x16x32_bf16 v[142:145], v[78:81], v[166:169], v[142:145]
	v_mfma_f32_16x16x32_bf16 v[138:141], v[94:97], v[166:169], v[138:141]
	v_mfma_f32_16x16x32_bf16 v[118:121], v[78:81], v[178:181], v[118:121]
	v_mfma_f32_16x16x32_bf16 v[114:117], v[94:97], v[178:181], v[114:117]
	v_mfma_f32_16x16x32_bf16 v[82:85], v[78:81], v[186:189], v[82:85]
	v_mfma_f32_16x16x32_bf16 v[74:77], v[94:97], v[186:189], v[74:77]
	v_mfma_f32_16x16x32_bf16 v[170:173], v[86:89], v[158:161], v[170:173]
	v_mfma_f32_16x16x32_bf16 v[162:165], v[98:101], v[158:161], v[162:165]
	v_mfma_f32_16x16x32_bf16 v[142:145], v[86:89], v[174:177], v[142:145]
	v_mfma_f32_16x16x32_bf16 v[138:141], v[98:101], v[174:177], v[138:141]
	v_mfma_f32_16x16x32_bf16 v[118:121], v[86:89], v[182:185], v[118:121]
	v_mfma_f32_16x16x32_bf16 v[114:117], v[98:101], v[182:185], v[114:117]
	v_mfma_f32_16x16x32_bf16 v[82:85], v[86:89], v[190:193], v[82:85]
	v_mfma_f32_16x16x32_bf16 v[74:77], v[98:101], v[190:193], v[74:77]
	s_setprio 0
	s_setprio 1
	v_mfma_f32_16x16x32_bf16 v[154:157], v[106:109], v[146:149], v[154:157]
	v_mfma_f32_16x16x32_bf16 v[130:133], v[106:109], v[166:169], v[130:133]
	v_mfma_f32_16x16x32_bf16 v[122:125], v[126:129], v[166:169], v[122:125]
	v_mfma_f32_16x16x32_bf16 v[102:105], v[106:109], v[178:181], v[102:105]
	v_mfma_f32_16x16x32_bf16 v[90:93], v[126:129], v[178:181], v[90:93]
	v_mfma_f32_16x16x32_bf16 v[70:73], v[106:109], v[186:189], v[70:73]
	v_mfma_f32_16x16x32_bf16 v[66:69], v[126:129], v[186:189], v[66:69]
	v_mfma_f32_16x16x32_bf16 v[154:157], v[110:113], v[158:161], v[154:157]
	v_mfma_f32_16x16x32_bf16 v[146:149], v[126:129], v[146:149], v[150:153]
	v_mfma_f32_16x16x32_bf16 v[130:133], v[110:113], v[174:177], v[130:133]
	v_mfma_f32_16x16x32_bf16 v[122:125], v[134:137], v[174:177], v[122:125]
	v_mfma_f32_16x16x32_bf16 v[102:105], v[110:113], v[182:185], v[102:105]
	v_mfma_f32_16x16x32_bf16 v[90:93], v[134:137], v[182:185], v[90:93]
	v_mfma_f32_16x16x32_bf16 v[70:73], v[110:113], v[190:193], v[70:73]
	v_mfma_f32_16x16x32_bf16 v[66:69], v[134:137], v[190:193], v[66:69]
	v_mfma_f32_16x16x32_bf16 v[146:149], v[134:137], v[158:161], v[146:149]
	s_barrier
	s_setprio 0
	s_add_i32 s0, s33, s26
	v_lshl_add_u64 v[194:195], s[20:21], 0, v[202:203]
	s_mov_b32 m0, s0
	ds_read_b128 v[150:153], v239 offset:16384
	ds_read_b128 v[158:161], v239 offset:17408
	ds_read_b128 v[166:169], v239 offset:18432
	ds_read_b128 v[174:177], v239 offset:19456
	ds_read_b128 v[178:181], v239 offset:20480
	ds_read_b128 v[182:185], v239 offset:21504
	ds_read_b128 v[186:189], v239 offset:22528
	ds_read_b128 v[190:193], v239 offset:23552
	global_load_lds_dwordx4 v[194:195], off
	s_add_i32 m0, s0, 0x2000
	s_add_u32 s0, s20, 0x100000
	v_lshl_add_u64 v[196:197], s[20:21], 0, v[208:209]
	s_addc_u32 s1, s21, 0
	s_add_i32 s33, s55, s26
	global_load_lds_dwordx4 v[196:197], off
	v_lshl_add_u64 v[198:199], s[0:1], 0, v[202:203]
	s_mov_b32 m0, s33
	v_lshl_add_u64 v[200:201], s[22:23], 0, v[210:211]
	global_load_lds_dwordx4 v[198:199], off
	v_lshl_add_u64 v[198:199], s[0:1], 0, v[208:209]
	s_add_i32 m0, s33, 0x2000
	s_nop 0
	global_load_lds_dwordx4 v[198:199], off
	v_lshl_add_u64 v[198:199], s[22:23], 0, v[212:213]
	s_mov_b32 m0, s27
	s_nop 0
	global_load_lds_dwordx4 v[198:199], off
	s_mov_b32 m0, s28
	s_nop 0
	global_load_lds_dwordx4 v[200:201], off
	s_waitcnt vmcnt(8)
	s_waitcnt lgkmcnt(0)
	s_setprio 1
	s_barrier
	v_mfma_f32_16x16x32_bf16 v[62:65], v[78:81], v[150:153], v[62:65]
	v_mfma_f32_16x16x32_bf16 v[58:61], v[94:97], v[150:153], v[58:61]
	v_mfma_f32_16x16x32_bf16 v[46:49], v[78:81], v[166:169], v[46:49]
	v_mfma_f32_16x16x32_bf16 v[42:45], v[94:97], v[166:169], v[42:45]
	v_mfma_f32_16x16x32_bf16 v[30:33], v[78:81], v[178:181], v[30:33]
	v_mfma_f32_16x16x32_bf16 v[26:29], v[94:97], v[178:181], v[26:29]
	v_mfma_f32_16x16x32_bf16 v[14:17], v[78:81], v[186:189], v[14:17]
	v_mfma_f32_16x16x32_bf16 v[10:13], v[94:97], v[186:189], v[10:13]
	v_mfma_f32_16x16x32_bf16 v[62:65], v[86:89], v[158:161], v[62:65]
	v_mfma_f32_16x16x32_bf16 v[58:61], v[98:101], v[158:161], v[58:61]
	v_mfma_f32_16x16x32_bf16 v[46:49], v[86:89], v[174:177], v[46:49]
	v_mfma_f32_16x16x32_bf16 v[42:45], v[98:101], v[174:177], v[42:45]
	v_mfma_f32_16x16x32_bf16 v[30:33], v[86:89], v[182:185], v[30:33]
	v_mfma_f32_16x16x32_bf16 v[26:29], v[98:101], v[182:185], v[26:29]
	v_mfma_f32_16x16x32_bf16 v[14:17], v[86:89], v[190:193], v[14:17]
	v_mfma_f32_16x16x32_bf16 v[10:13], v[98:101], v[190:193], v[10:13]
	s_setprio 0
	s_setprio 1
	v_mfma_f32_16x16x32_bf16 v[54:57], v[106:109], v[150:153], v[54:57]
	v_mfma_f32_16x16x32_bf16 v[50:53], v[126:129], v[150:153], v[50:53]
	v_mfma_f32_16x16x32_bf16 v[38:41], v[106:109], v[166:169], v[38:41]
	v_mfma_f32_16x16x32_bf16 v[34:37], v[126:129], v[166:169], v[34:37]
	v_mfma_f32_16x16x32_bf16 v[22:25], v[106:109], v[178:181], v[22:25]
	v_mfma_f32_16x16x32_bf16 v[18:21], v[126:129], v[178:181], v[18:21]
	v_mfma_f32_16x16x32_bf16 v[6:9], v[106:109], v[186:189], v[6:9]
	v_mfma_f32_16x16x32_bf16 v[2:5], v[126:129], v[186:189], v[2:5]
	v_mfma_f32_16x16x32_bf16 v[54:57], v[110:113], v[158:161], v[54:57]
	v_mfma_f32_16x16x32_bf16 v[50:53], v[134:137], v[158:161], v[50:53]
	v_mfma_f32_16x16x32_bf16 v[38:41], v[110:113], v[174:177], v[38:41]
	v_mfma_f32_16x16x32_bf16 v[34:37], v[134:137], v[174:177], v[34:37]
	v_mfma_f32_16x16x32_bf16 v[22:25], v[110:113], v[182:185], v[22:25]
	v_mfma_f32_16x16x32_bf16 v[18:21], v[134:137], v[182:185], v[18:21]
	v_mfma_f32_16x16x32_bf16 v[6:9], v[110:113], v[190:193], v[6:9]
	v_mfma_f32_16x16x32_bf16 v[2:5], v[134:137], v[190:193], v[2:5]
	s_barrier
	s_setprio 0
	s_add_i32 s33, 0, 0x18000
	s_add_i32 s55, 0, 0x1c000
	v_add_u32_e32 v98, s33, v205
	v_add_u32_e32 v134, s55, v205
	ds_read_b128 v[78:81], v98
	ds_read_b128 v[86:89], v98 offset:1024
	ds_read_b128 v[94:97], v98 offset:2048
	ds_read_b128 v[98:101], v98 offset:3072
	ds_read_b128 v[106:109], v134
	ds_read_b128 v[110:113], v134 offset:1024
	ds_read_b128 v[126:129], v134 offset:2048
	ds_read_b128 v[134:137], v134 offset:3072
	s_add_u32 s0, s22, 0x100000
	s_addc_u32 s1, s23, 0
	s_mov_b32 m0, s29
	v_lshl_add_u64 v[206:207], s[0:1], 0, v[212:213]
	ds_read_b128 v[150:153], v239 offset:32768
	ds_read_b128 v[158:161], v239 offset:33792
	ds_read_b128 v[166:169], v239 offset:34816
	ds_read_b128 v[174:177], v239 offset:35840
	ds_read_b128 v[178:181], v239 offset:36864
	ds_read_b128 v[182:185], v239 offset:37888
	ds_read_b128 v[186:189], v239 offset:38912
	ds_read_b128 v[190:193], v239 offset:39936
	global_load_lds_dwordx4 v[206:207], off
	v_lshl_add_u64 v[206:207], s[0:1], 0, v[210:211]
	s_mov_b32 m0, s30
	s_nop 0
	global_load_lds_dwordx4 v[206:207], off
	s_waitcnt vmcnt(8)
	s_waitcnt lgkmcnt(0)
	s_setprio 1
	s_barrier
	v_mfma_f32_16x16x32_bf16 v[170:173], v[78:81], v[150:153], v[170:173]
	v_mfma_f32_16x16x32_bf16 v[162:165], v[94:97], v[150:153], v[162:165]
	v_mfma_f32_16x16x32_bf16 v[142:145], v[78:81], v[166:169], v[142:145]
	v_mfma_f32_16x16x32_bf16 v[138:141], v[94:97], v[166:169], v[138:141]
	v_mfma_f32_16x16x32_bf16 v[118:121], v[78:81], v[178:181], v[118:121]
	v_mfma_f32_16x16x32_bf16 v[114:117], v[94:97], v[178:181], v[114:117]
	v_mfma_f32_16x16x32_bf16 v[82:85], v[78:81], v[186:189], v[82:85]
	v_mfma_f32_16x16x32_bf16 v[74:77], v[94:97], v[186:189], v[74:77]
	v_mfma_f32_16x16x32_bf16 v[170:173], v[86:89], v[158:161], v[170:173]
	v_mfma_f32_16x16x32_bf16 v[162:165], v[98:101], v[158:161], v[162:165]
	v_mfma_f32_16x16x32_bf16 v[142:145], v[86:89], v[174:177], v[142:145]
	v_mfma_f32_16x16x32_bf16 v[138:141], v[98:101], v[174:177], v[138:141]
	v_mfma_f32_16x16x32_bf16 v[118:121], v[86:89], v[182:185], v[118:121]
	v_mfma_f32_16x16x32_bf16 v[114:117], v[98:101], v[182:185], v[114:117]
	v_mfma_f32_16x16x32_bf16 v[82:85], v[86:89], v[190:193], v[82:85]
	v_mfma_f32_16x16x32_bf16 v[74:77], v[98:101], v[190:193], v[74:77]
	s_setprio 0
	s_setprio 1
	v_mfma_f32_16x16x32_bf16 v[154:157], v[106:109], v[150:153], v[154:157]
	v_mfma_f32_16x16x32_bf16 v[146:149], v[126:129], v[150:153], v[146:149]
	v_mfma_f32_16x16x32_bf16 v[130:133], v[106:109], v[166:169], v[130:133]
	v_mfma_f32_16x16x32_bf16 v[122:125], v[126:129], v[166:169], v[122:125]
	v_mfma_f32_16x16x32_bf16 v[102:105], v[106:109], v[178:181], v[102:105]
	v_mfma_f32_16x16x32_bf16 v[90:93], v[126:129], v[178:181], v[90:93]
	v_mfma_f32_16x16x32_bf16 v[70:73], v[106:109], v[186:189], v[70:73]
	v_mfma_f32_16x16x32_bf16 v[66:69], v[126:129], v[186:189], v[66:69]
	v_mfma_f32_16x16x32_bf16 v[154:157], v[110:113], v[158:161], v[154:157]
	v_mfma_f32_16x16x32_bf16 v[150:153], v[134:137], v[158:161], v[146:149]
	v_mfma_f32_16x16x32_bf16 v[130:133], v[110:113], v[174:177], v[130:133]
	v_mfma_f32_16x16x32_bf16 v[122:125], v[134:137], v[174:177], v[122:125]
	v_mfma_f32_16x16x32_bf16 v[102:105], v[110:113], v[182:185], v[102:105]
	v_mfma_f32_16x16x32_bf16 v[90:93], v[134:137], v[182:185], v[90:93]
	v_mfma_f32_16x16x32_bf16 v[70:73], v[110:113], v[190:193], v[70:73]
	v_mfma_f32_16x16x32_bf16 v[66:69], v[134:137], v[190:193], v[66:69]
	s_barrier
	s_setprio 0
	s_add_i32 s0, s33, s26
	v_lshl_add_u64 v[194:195], v[194:195], 0, s[80:81]
	s_mov_b32 m0, s0
	ds_read_b128 v[146:149], v239 offset:49152
	ds_read_b128 v[158:161], v239 offset:50176
	ds_read_b128 v[166:169], v239 offset:51200
	ds_read_b128 v[174:177], v239 offset:52224
	ds_read_b128 v[178:181], v239 offset:53248
	ds_read_b128 v[182:185], v239 offset:54272
	ds_read_b128 v[186:189], v239 offset:55296
	ds_read_b128 v[190:193], v239 offset:56320
	global_load_lds_dwordx4 v[194:195], off
	s_add_i32 m0, s0, 0x2000
	s_add_u32 s0, s20, 0x100080
	v_lshl_add_u64 v[194:195], v[196:197], 0, s[80:81]
	s_addc_u32 s1, s21, 0
	s_add_i32 s20, s55, s26
	global_load_lds_dwordx4 v[194:195], off
	v_lshl_add_u64 v[194:195], s[0:1], 0, v[202:203]
	s_mov_b32 m0, s20
	s_nop 0
	global_load_lds_dwordx4 v[194:195], off
	v_lshl_add_u64 v[194:195], s[0:1], 0, v[208:209]
	s_add_i32 m0, s20, 0x2000
	s_nop 0
	global_load_lds_dwordx4 v[194:195], off
	v_lshl_add_u64 v[194:195], v[198:199], 0, s[80:81]
	s_mov_b32 m0, s35
	s_nop 0
	global_load_lds_dwordx4 v[194:195], off
	v_lshl_add_u64 v[194:195], v[200:201], 0, s[80:81]
	s_mov_b32 m0, s36
	s_nop 0
	global_load_lds_dwordx4 v[194:195], off
	s_waitcnt vmcnt(8)
	s_waitcnt lgkmcnt(0)
	s_setprio 1
	s_barrier
	v_mfma_f32_16x16x32_bf16 v[62:65], v[78:81], v[146:149], v[62:65]
	v_mfma_f32_16x16x32_bf16 v[58:61], v[94:97], v[146:149], v[58:61]
	v_mfma_f32_16x16x32_bf16 v[46:49], v[78:81], v[166:169], v[46:49]
	v_mfma_f32_16x16x32_bf16 v[42:45], v[94:97], v[166:169], v[42:45]
	v_mfma_f32_16x16x32_bf16 v[30:33], v[78:81], v[178:181], v[30:33]
	v_mfma_f32_16x16x32_bf16 v[26:29], v[94:97], v[178:181], v[26:29]
	v_mfma_f32_16x16x32_bf16 v[14:17], v[78:81], v[186:189], v[14:17]
	v_mfma_f32_16x16x32_bf16 v[10:13], v[94:97], v[186:189], v[10:13]
	v_mfma_f32_16x16x32_bf16 v[62:65], v[86:89], v[158:161], v[62:65]
	v_mfma_f32_16x16x32_bf16 v[58:61], v[98:101], v[158:161], v[58:61]
	v_mfma_f32_16x16x32_bf16 v[46:49], v[86:89], v[174:177], v[46:49]
	v_mfma_f32_16x16x32_bf16 v[42:45], v[98:101], v[174:177], v[42:45]
	v_mfma_f32_16x16x32_bf16 v[30:33], v[86:89], v[182:185], v[30:33]
	v_mfma_f32_16x16x32_bf16 v[26:29], v[98:101], v[182:185], v[26:29]
	v_mfma_f32_16x16x32_bf16 v[14:17], v[86:89], v[190:193], v[14:17]
	v_mfma_f32_16x16x32_bf16 v[10:13], v[98:101], v[190:193], v[10:13]
	s_setprio 0
	s_setprio 1
	v_mfma_f32_16x16x32_bf16 v[54:57], v[106:109], v[146:149], v[54:57]
	v_mfma_f32_16x16x32_bf16 v[50:53], v[126:129], v[146:149], v[50:53]
	v_mfma_f32_16x16x32_bf16 v[38:41], v[106:109], v[166:169], v[38:41]
	v_mfma_f32_16x16x32_bf16 v[34:37], v[126:129], v[166:169], v[34:37]
	v_mfma_f32_16x16x32_bf16 v[22:25], v[106:109], v[178:181], v[22:25]
	v_mfma_f32_16x16x32_bf16 v[18:21], v[126:129], v[178:181], v[18:21]
	v_mfma_f32_16x16x32_bf16 v[6:9], v[106:109], v[186:189], v[6:9]
	v_mfma_f32_16x16x32_bf16 v[2:5], v[126:129], v[186:189], v[2:5]
	v_mfma_f32_16x16x32_bf16 v[54:57], v[110:113], v[158:161], v[54:57]
	v_mfma_f32_16x16x32_bf16 v[50:53], v[134:137], v[158:161], v[50:53]
	v_mfma_f32_16x16x32_bf16 v[38:41], v[110:113], v[174:177], v[38:41]
	v_mfma_f32_16x16x32_bf16 v[34:37], v[134:137], v[174:177], v[34:37]
	v_mfma_f32_16x16x32_bf16 v[22:25], v[110:113], v[182:185], v[22:25]
	v_mfma_f32_16x16x32_bf16 v[18:21], v[134:137], v[182:185], v[18:21]
	v_mfma_f32_16x16x32_bf16 v[6:9], v[110:113], v[190:193], v[6:9]
	v_mfma_f32_16x16x32_bf16 v[2:5], v[134:137], v[190:193], v[2:5]
	s_barrier
	s_setprio 0
	s_add_i32 s61, s61, 2
	s_add_u32 s18, s18, 0x100
	s_addc_u32 s19, s19, 0
	s_add_u32 s59, s59, 0x100
	s_addc_u32 s60, s60, 0
	s_cmp_gt_u32 s61, 61
	s_cbranch_scc0 .LBB0_692
	s_and_b64 vcc, exec, s[6:7]
	s_cbranch_vccz .LBB0_695
	s_barrier

.LBB0_712:
	s_add_u32 s0, s18, 0xfff00080
	s_addc_u32 s1, s19, -1
	s_add_i32 s33, 0, 0x10000
	s_cmp_eq_u32 s49, 4
	s_cselect_b32 s23, s15, s1
	s_cselect_b32 s22, s14, s0
	s_cselect_b32 s21, s17, s11
	s_cselect_b32 s20, s16, s9
	s_add_i32 s55, 0, 0x14000
	v_add_u32_e32 v152, s33, v136
	v_add_u32_e32 v168, s55, v136
	ds_read_b128 v[140:143], v152
	ds_read_b128 v[144:147], v152 offset:1024
	ds_read_b128 v[148:151], v152 offset:2048
	ds_read_b128 v[152:155], v152 offset:3072
	ds_read_b128 v[156:159], v168
	ds_read_b128 v[160:163], v168 offset:1024
	ds_read_b128 v[164:167], v168 offset:2048
	ds_read_b128 v[168:171], v168 offset:3072
	v_lshl_add_u64 v[200:201], s[18:19], 0, v[132:133]
	s_add_i32 m0, s27, 0xc000
	ds_read_b128 v[172:175], v139
	ds_read_b128 v[176:179], v139 offset:1024
	ds_read_b128 v[180:183], v139 offset:2048
	ds_read_b128 v[184:187], v139 offset:3072
	ds_read_b128 v[188:191], v139 offset:4096
	ds_read_b128 v[192:195], v139 offset:5120
	ds_read_b128 v[196:199], v139 offset:6144
	ds_read_b128 v[208:211], v139 offset:7168
	global_load_lds_dwordx4 v[200:201], off
	v_lshl_add_u64 v[200:201], s[18:19], 0, v[134:135]
	s_add_i32 m0, s27, 0xe000
	s_nop 0
	global_load_lds_dwordx4 v[200:201], off
	s_waitcnt vmcnt(8)
	s_waitcnt lgkmcnt(0)
	s_setprio 1
	s_barrier
	v_mfma_f32_16x16x32_bf16 v[126:129], v[140:143], v[172:175], v[126:129]
	v_mfma_f32_16x16x32_bf16 v[122:125], v[148:151], v[172:175], v[122:125]
	v_mfma_f32_16x16x32_bf16 v[118:121], v[140:143], v[180:183], v[118:121]
	v_mfma_f32_16x16x32_bf16 v[114:117], v[148:151], v[180:183], v[114:117]
	v_mfma_f32_16x16x32_bf16 v[106:109], v[140:143], v[188:191], v[106:109]
	v_mfma_f32_16x16x32_bf16 v[98:101], v[148:151], v[188:191], v[98:101]
	v_mfma_f32_16x16x32_bf16 v[90:93], v[140:143], v[196:199], v[90:93]
	v_mfma_f32_16x16x32_bf16 v[82:85], v[148:151], v[196:199], v[82:85]
	v_mfma_f32_16x16x32_bf16 v[126:129], v[144:147], v[176:179], v[126:129]
	v_mfma_f32_16x16x32_bf16 v[122:125], v[152:155], v[176:179], v[122:125]
	v_mfma_f32_16x16x32_bf16 v[118:121], v[144:147], v[184:187], v[118:121]
	v_mfma_f32_16x16x32_bf16 v[114:117], v[152:155], v[184:187], v[114:117]
	v_mfma_f32_16x16x32_bf16 v[106:109], v[144:147], v[192:195], v[106:109]
	v_mfma_f32_16x16x32_bf16 v[98:101], v[152:155], v[192:195], v[98:101]
	v_mfma_f32_16x16x32_bf16 v[90:93], v[144:147], v[208:211], v[90:93]
	v_mfma_f32_16x16x32_bf16 v[82:85], v[152:155], v[208:211], v[82:85]
	s_setprio 0
	s_setprio 1
	v_mfma_f32_16x16x32_bf16 v[110:113], v[156:159], v[172:175], v[110:113]
	v_mfma_f32_16x16x32_bf16 v[102:105], v[164:167], v[172:175], v[102:105]
	v_mfma_f32_16x16x32_bf16 v[94:97], v[156:159], v[180:183], v[94:97]
	v_mfma_f32_16x16x32_bf16 v[86:89], v[164:167], v[180:183], v[86:89]
	v_mfma_f32_16x16x32_bf16 v[78:81], v[156:159], v[188:191], v[78:81]
	v_mfma_f32_16x16x32_bf16 v[74:77], v[164:167], v[188:191], v[74:77]
	v_mfma_f32_16x16x32_bf16 v[70:73], v[156:159], v[196:199], v[70:73]
	v_mfma_f32_16x16x32_bf16 v[66:69], v[164:167], v[196:199], v[66:69]
	v_mfma_f32_16x16x32_bf16 v[110:113], v[160:163], v[176:179], v[110:113]
	v_mfma_f32_16x16x32_bf16 v[102:105], v[168:171], v[176:179], v[102:105]
	v_mfma_f32_16x16x32_bf16 v[94:97], v[160:163], v[184:187], v[94:97]
	v_mfma_f32_16x16x32_bf16 v[86:89], v[168:171], v[184:187], v[86:89]
	v_mfma_f32_16x16x32_bf16 v[78:81], v[160:163], v[192:195], v[78:81]
	v_mfma_f32_16x16x32_bf16 v[74:77], v[168:171], v[192:195], v[74:77]
	v_mfma_f32_16x16x32_bf16 v[70:73], v[160:163], v[208:211], v[70:73]
	v_mfma_f32_16x16x32_bf16 v[66:69], v[168:171], v[208:211], v[66:69]
	s_barrier
	s_setprio 0
	s_add_i32 s0, s33, s26
	v_lshl_add_u64 v[200:201], s[20:21], 0, v[202:203]
	s_mov_b32 m0, s0
	ds_read_b128 v[172:175], v139 offset:16384
	ds_read_b128 v[176:179], v139 offset:17408
	ds_read_b128 v[180:183], v139 offset:18432
	ds_read_b128 v[184:187], v139 offset:19456
	ds_read_b128 v[188:191], v139 offset:20480
	ds_read_b128 v[192:195], v139 offset:21504
	ds_read_b128 v[196:199], v139 offset:22528
	ds_read_b128 v[208:211], v139 offset:23552
	global_load_lds_dwordx4 v[200:201], off
	s_add_i32 m0, s0, 0x2000
	s_add_u32 s0, s20, 0x100000
	v_lshl_add_u64 v[204:205], s[20:21], 0, v[130:131]
	s_addc_u32 s1, s21, 0
	s_add_i32 s33, s55, s26
	global_load_lds_dwordx4 v[204:205], off
	v_lshl_add_u64 v[206:207], s[0:1], 0, v[202:203]
	s_mov_b32 m0, s33
	v_lshl_add_u64 v[212:213], s[22:23], 0, v[130:131]
	global_load_lds_dwordx4 v[206:207], off
	v_lshl_add_u64 v[206:207], s[0:1], 0, v[130:131]
	s_add_i32 m0, s33, 0x2000
	s_nop 0
	global_load_lds_dwordx4 v[206:207], off
	v_lshl_add_u64 v[206:207], s[22:23], 0, v[202:203]
	s_mov_b32 m0, s27
	s_nop 0
	global_load_lds_dwordx4 v[206:207], off
	s_mov_b32 m0, s28
	s_nop 0
	global_load_lds_dwordx4 v[212:213], off
	s_waitcnt vmcnt(8)
	s_waitcnt lgkmcnt(0)
	s_setprio 1
	s_barrier
	v_mfma_f32_16x16x32_bf16 v[62:65], v[140:143], v[172:175], v[62:65]
	v_mfma_f32_16x16x32_bf16 v[58:61], v[148:151], v[172:175], v[58:61]
	v_mfma_f32_16x16x32_bf16 v[54:57], v[140:143], v[180:183], v[54:57]
	v_mfma_f32_16x16x32_bf16 v[50:53], v[148:151], v[180:183], v[50:53]
	v_mfma_f32_16x16x32_bf16 v[38:41], v[140:143], v[188:191], v[38:41]
	v_mfma_f32_16x16x32_bf16 v[34:37], v[148:151], v[188:191], v[34:37]
	v_mfma_f32_16x16x32_bf16 v[22:25], v[140:143], v[196:199], v[22:25]
	v_mfma_f32_16x16x32_bf16 v[18:21], v[148:151], v[196:199], v[18:21]
	v_mfma_f32_16x16x32_bf16 v[62:65], v[144:147], v[176:179], v[62:65]
	v_mfma_f32_16x16x32_bf16 v[58:61], v[152:155], v[176:179], v[58:61]
	v_mfma_f32_16x16x32_bf16 v[54:57], v[144:147], v[184:187], v[54:57]
	v_mfma_f32_16x16x32_bf16 v[50:53], v[152:155], v[184:187], v[50:53]
	v_mfma_f32_16x16x32_bf16 v[38:41], v[144:147], v[192:195], v[38:41]
	v_mfma_f32_16x16x32_bf16 v[34:37], v[152:155], v[192:195], v[34:37]
	v_mfma_f32_16x16x32_bf16 v[22:25], v[144:147], v[208:211], v[22:25]
	v_mfma_f32_16x16x32_bf16 v[18:21], v[152:155], v[208:211], v[18:21]
	s_setprio 0
	s_setprio 1
	v_mfma_f32_16x16x32_bf16 v[46:49], v[156:159], v[172:175], v[46:49]
	v_mfma_f32_16x16x32_bf16 v[42:45], v[164:167], v[172:175], v[42:45]
	v_mfma_f32_16x16x32_bf16 v[30:33], v[156:159], v[180:183], v[30:33]
	v_mfma_f32_16x16x32_bf16 v[26:29], v[164:167], v[180:183], v[26:29]
	v_mfma_f32_16x16x32_bf16 v[14:17], v[156:159], v[188:191], v[14:17]
	v_mfma_f32_16x16x32_bf16 v[10:13], v[164:167], v[188:191], v[10:13]
	v_mfma_f32_16x16x32_bf16 v[6:9], v[156:159], v[196:199], v[6:9]
	v_mfma_f32_16x16x32_bf16 v[2:5], v[164:167], v[196:199], v[2:5]
	v_mfma_f32_16x16x32_bf16 v[46:49], v[160:163], v[176:179], v[46:49]
	v_mfma_f32_16x16x32_bf16 v[42:45], v[168:171], v[176:179], v[42:45]
	v_mfma_f32_16x16x32_bf16 v[30:33], v[160:163], v[184:187], v[30:33]
	v_mfma_f32_16x16x32_bf16 v[26:29], v[168:171], v[184:187], v[26:29]
	v_mfma_f32_16x16x32_bf16 v[14:17], v[160:163], v[192:195], v[14:17]
	v_mfma_f32_16x16x32_bf16 v[10:13], v[168:171], v[192:195], v[10:13]
	v_mfma_f32_16x16x32_bf16 v[6:9], v[160:163], v[208:211], v[6:9]
	v_mfma_f32_16x16x32_bf16 v[2:5], v[168:171], v[208:211], v[2:5]
	s_barrier
	s_setprio 0
	s_add_i32 s33, 0, 0x18000
	s_add_i32 s55, 0, 0x1c000
	v_add_u32_e32 v152, s33, v136
	v_add_u32_e32 v168, s55, v136
	ds_read_b128 v[140:143], v152
	ds_read_b128 v[144:147], v152 offset:1024
	ds_read_b128 v[148:151], v152 offset:2048
	ds_read_b128 v[152:155], v152 offset:3072
	ds_read_b128 v[156:159], v168
	ds_read_b128 v[160:163], v168 offset:1024
	ds_read_b128 v[164:167], v168 offset:2048
	ds_read_b128 v[168:171], v168 offset:3072
	s_add_u32 s0, s22, 0x100000
	s_addc_u32 s1, s23, 0
	s_mov_b32 m0, s29
	v_lshl_add_u64 v[214:215], s[0:1], 0, v[202:203]
	ds_read_b128 v[172:175], v139 offset:32768
	ds_read_b128 v[176:179], v139 offset:33792
	ds_read_b128 v[180:183], v139 offset:34816
	ds_read_b128 v[184:187], v139 offset:35840
	ds_read_b128 v[188:191], v139 offset:36864
	ds_read_b128 v[192:195], v139 offset:37888
	ds_read_b128 v[196:199], v139 offset:38912
	ds_read_b128 v[208:211], v139 offset:39936
	global_load_lds_dwordx4 v[214:215], off
	v_lshl_add_u64 v[214:215], s[0:1], 0, v[130:131]
	s_mov_b32 m0, s30
	s_nop 0
	global_load_lds_dwordx4 v[214:215], off
	s_waitcnt vmcnt(8)
	s_waitcnt lgkmcnt(0)
	s_setprio 1
	s_barrier
	v_mfma_f32_16x16x32_bf16 v[126:129], v[140:143], v[172:175], v[126:129]
	v_mfma_f32_16x16x32_bf16 v[122:125], v[148:151], v[172:175], v[122:125]
	v_mfma_f32_16x16x32_bf16 v[118:121], v[140:143], v[180:183], v[118:121]
	v_mfma_f32_16x16x32_bf16 v[114:117], v[148:151], v[180:183], v[114:117]
	v_mfma_f32_16x16x32_bf16 v[106:109], v[140:143], v[188:191], v[106:109]
	v_mfma_f32_16x16x32_bf16 v[98:101], v[148:151], v[188:191], v[98:101]
	v_mfma_f32_16x16x32_bf16 v[90:93], v[140:143], v[196:199], v[90:93]
	v_mfma_f32_16x16x32_bf16 v[82:85], v[148:151], v[196:199], v[82:85]
	v_mfma_f32_16x16x32_bf16 v[126:129], v[144:147], v[176:179], v[126:129]
	v_mfma_f32_16x16x32_bf16 v[122:125], v[152:155], v[176:179], v[122:125]
	v_mfma_f32_16x16x32_bf16 v[118:121], v[144:147], v[184:187], v[118:121]
	v_mfma_f32_16x16x32_bf16 v[114:117], v[152:155], v[184:187], v[114:117]
	v_mfma_f32_16x16x32_bf16 v[106:109], v[144:147], v[192:195], v[106:109]
	v_mfma_f32_16x16x32_bf16 v[98:101], v[152:155], v[192:195], v[98:101]
	v_mfma_f32_16x16x32_bf16 v[90:93], v[144:147], v[208:211], v[90:93]
	v_mfma_f32_16x16x32_bf16 v[82:85], v[152:155], v[208:211], v[82:85]
	s_setprio 0
	s_setprio 1
	v_mfma_f32_16x16x32_bf16 v[110:113], v[156:159], v[172:175], v[110:113]
	v_mfma_f32_16x16x32_bf16 v[102:105], v[164:167], v[172:175], v[102:105]
	v_mfma_f32_16x16x32_bf16 v[94:97], v[156:159], v[180:183], v[94:97]
	v_mfma_f32_16x16x32_bf16 v[86:89], v[164:167], v[180:183], v[86:89]
	v_mfma_f32_16x16x32_bf16 v[78:81], v[156:159], v[188:191], v[78:81]
	v_mfma_f32_16x16x32_bf16 v[74:77], v[164:167], v[188:191], v[74:77]
	v_mfma_f32_16x16x32_bf16 v[70:73], v[156:159], v[196:199], v[70:73]
	v_mfma_f32_16x16x32_bf16 v[66:69], v[164:167], v[196:199], v[66:69]
	v_mfma_f32_16x16x32_bf16 v[110:113], v[160:163], v[176:179], v[110:113]
	v_mfma_f32_16x16x32_bf16 v[102:105], v[168:171], v[176:179], v[102:105]
	v_mfma_f32_16x16x32_bf16 v[94:97], v[160:163], v[184:187], v[94:97]
	v_mfma_f32_16x16x32_bf16 v[86:89], v[168:171], v[184:187], v[86:89]
	v_mfma_f32_16x16x32_bf16 v[78:81], v[160:163], v[192:195], v[78:81]
	v_mfma_f32_16x16x32_bf16 v[74:77], v[168:171], v[192:195], v[74:77]
	v_mfma_f32_16x16x32_bf16 v[70:73], v[160:163], v[208:211], v[70:73]
	v_mfma_f32_16x16x32_bf16 v[66:69], v[168:171], v[208:211], v[66:69]
	s_barrier
	s_setprio 0
	s_add_i32 s0, s33, s26
	v_lshl_add_u64 v[200:201], v[200:201], 0, s[80:81]
	s_mov_b32 m0, s0
	ds_read_b128 v[172:175], v139 offset:49152
	ds_read_b128 v[176:179], v139 offset:50176
	ds_read_b128 v[180:183], v139 offset:51200
	ds_read_b128 v[184:187], v139 offset:52224
	ds_read_b128 v[188:191], v139 offset:53248
	ds_read_b128 v[192:195], v139 offset:54272
	ds_read_b128 v[196:199], v139 offset:55296
	ds_read_b128 v[208:211], v139 offset:56320
	global_load_lds_dwordx4 v[200:201], off
	s_add_i32 m0, s0, 0x2000
	s_add_u32 s0, s20, 0x100080
	v_lshl_add_u64 v[200:201], v[204:205], 0, s[80:81]
	s_addc_u32 s1, s21, 0
	s_add_i32 s20, s55, s26
	global_load_lds_dwordx4 v[200:201], off
	v_lshl_add_u64 v[200:201], s[0:1], 0, v[202:203]
	s_mov_b32 m0, s20
	s_nop 0
	global_load_lds_dwordx4 v[200:201], off
	v_lshl_add_u64 v[200:201], s[0:1], 0, v[130:131]
	s_add_i32 m0, s20, 0x2000
	s_nop 0
	global_load_lds_dwordx4 v[200:201], off
	v_lshl_add_u64 v[200:201], v[206:207], 0, s[80:81]
	s_mov_b32 m0, s31
	s_nop 0
	global_load_lds_dwordx4 v[200:201], off
	v_lshl_add_u64 v[200:201], v[212:213], 0, s[80:81]
	s_mov_b32 m0, s34
	s_nop 0
	global_load_lds_dwordx4 v[200:201], off
	s_waitcnt vmcnt(8)
	s_waitcnt lgkmcnt(0)
	s_setprio 1
	s_barrier
	v_mfma_f32_16x16x32_bf16 v[62:65], v[140:143], v[172:175], v[62:65]
	v_mfma_f32_16x16x32_bf16 v[58:61], v[148:151], v[172:175], v[58:61]
	v_mfma_f32_16x16x32_bf16 v[54:57], v[140:143], v[180:183], v[54:57]
	v_mfma_f32_16x16x32_bf16 v[50:53], v[148:151], v[180:183], v[50:53]
	v_mfma_f32_16x16x32_bf16 v[38:41], v[140:143], v[188:191], v[38:41]
	v_mfma_f32_16x16x32_bf16 v[34:37], v[148:151], v[188:191], v[34:37]
	v_mfma_f32_16x16x32_bf16 v[22:25], v[140:143], v[196:199], v[22:25]
	v_mfma_f32_16x16x32_bf16 v[18:21], v[148:151], v[196:199], v[18:21]
	v_mfma_f32_16x16x32_bf16 v[62:65], v[144:147], v[176:179], v[62:65]
	v_mfma_f32_16x16x32_bf16 v[58:61], v[152:155], v[176:179], v[58:61]
	v_mfma_f32_16x16x32_bf16 v[54:57], v[144:147], v[184:187], v[54:57]
	v_mfma_f32_16x16x32_bf16 v[50:53], v[152:155], v[184:187], v[50:53]
	v_mfma_f32_16x16x32_bf16 v[38:41], v[144:147], v[192:195], v[38:41]
	v_mfma_f32_16x16x32_bf16 v[34:37], v[152:155], v[192:195], v[34:37]
	v_mfma_f32_16x16x32_bf16 v[22:25], v[144:147], v[208:211], v[22:25]
	v_mfma_f32_16x16x32_bf16 v[18:21], v[152:155], v[208:211], v[18:21]
	s_setprio 0
	s_setprio 1
	v_mfma_f32_16x16x32_bf16 v[46:49], v[156:159], v[172:175], v[46:49]
	v_mfma_f32_16x16x32_bf16 v[42:45], v[164:167], v[172:175], v[42:45]
	v_mfma_f32_16x16x32_bf16 v[30:33], v[156:159], v[180:183], v[30:33]
	v_mfma_f32_16x16x32_bf16 v[26:29], v[164:167], v[180:183], v[26:29]
	v_mfma_f32_16x16x32_bf16 v[14:17], v[156:159], v[188:191], v[14:17]
	v_mfma_f32_16x16x32_bf16 v[10:13], v[164:167], v[188:191], v[10:13]
	v_mfma_f32_16x16x32_bf16 v[6:9], v[156:159], v[196:199], v[6:9]
	v_mfma_f32_16x16x32_bf16 v[2:5], v[164:167], v[196:199], v[2:5]
	v_mfma_f32_16x16x32_bf16 v[46:49], v[160:163], v[176:179], v[46:49]
	v_mfma_f32_16x16x32_bf16 v[42:45], v[168:171], v[176:179], v[42:45]
	v_mfma_f32_16x16x32_bf16 v[30:33], v[160:163], v[184:187], v[30:33]
	v_mfma_f32_16x16x32_bf16 v[26:29], v[168:171], v[184:187], v[26:29]
	v_mfma_f32_16x16x32_bf16 v[14:17], v[160:163], v[192:195], v[14:17]
	v_mfma_f32_16x16x32_bf16 v[10:13], v[168:171], v[192:195], v[10:13]
	v_mfma_f32_16x16x32_bf16 v[6:9], v[160:163], v[208:211], v[6:9]
	v_mfma_f32_16x16x32_bf16 v[2:5], v[168:171], v[208:211], v[2:5]
	s_barrier
	s_setprio 0
	s_add_i32 s49, s49, 2
	s_add_u32 s18, s18, 0x100
	s_addc_u32 s19, s19, 0
	s_add_u32 s9, s9, 0x100
	s_addc_u32 s11, s11, 0
	s_cmp_gt_u32 s49, 5
	s_cbranch_scc0 .LBB0_712
	s_and_b64 vcc, exec, s[6:7]
	s_cbranch_vccz .LBB0_715
	s_barrier

.LBB0_837:
	s_add_u32 s0, s18, 0xfff80080
	s_addc_u32 s1, s19, -1
	s_add_i32 s33, 0, 0x10000
	s_cmp_eq_u32 s59, 28
	s_cselect_b32 s23, s11, s1
	s_cselect_b32 s22, s38, s0
	v_add_u32_e32 v140, s33, v143
	s_cselect_b32 s21, s9, s58
	s_cselect_b32 s20, s39, s49
	s_add_i32 s55, 0, 0x14000
	ds_read_b128 v[146:149], v140
	ds_read_b128 v[150:153], v140 offset:1024
	ds_read_b128 v[154:157], v140 offset:2048
	ds_read_b128 v[158:161], v140 offset:3072
	v_add_u32_e32 v140, s55, v143
	ds_read_b128 v[162:165], v140
	ds_read_b128 v[166:169], v140 offset:1024
	ds_read_b128 v[170:173], v140 offset:2048
	ds_read_b128 v[174:177], v140 offset:3072
	v_lshl_add_u64 v[140:141], s[18:19], 0, v[136:137]
	s_add_i32 m0, s27, 0xc000
	ds_read_b128 v[178:181], v145
	ds_read_b128 v[182:185], v145 offset:1024
	ds_read_b128 v[186:189], v145 offset:2048
	ds_read_b128 v[190:193], v145 offset:3072
	ds_read_b128 v[194:197], v145 offset:4096
	ds_read_b128 v[198:201], v145 offset:5120
	ds_read_b128 v[208:211], v145 offset:6144
	ds_read_b128 v[212:215], v145 offset:7168
	global_load_lds_dwordx4 v[140:141], off
	v_lshl_add_u64 v[140:141], s[18:19], 0, v[138:139]
	s_add_i32 m0, s27, 0xe000
	s_nop 0
	global_load_lds_dwordx4 v[140:141], off
	s_waitcnt vmcnt(8)
	s_waitcnt lgkmcnt(0)
	s_setprio 1
	s_barrier
	v_mfma_f32_16x16x32_bf16 v[126:129], v[146:149], v[178:181], v[126:129]
	v_mfma_f32_16x16x32_bf16 v[118:121], v[154:157], v[178:181], v[118:121]
	v_mfma_f32_16x16x32_bf16 v[110:113], v[146:149], v[186:189], v[110:113]
	v_mfma_f32_16x16x32_bf16 v[102:105], v[154:157], v[186:189], v[102:105]
	v_mfma_f32_16x16x32_bf16 v[94:97], v[146:149], v[194:197], v[94:97]
	v_mfma_f32_16x16x32_bf16 v[86:89], v[154:157], v[194:197], v[86:89]
	v_mfma_f32_16x16x32_bf16 v[78:81], v[146:149], v[208:211], v[78:81]
	v_mfma_f32_16x16x32_bf16 v[70:73], v[154:157], v[208:211], v[70:73]
	v_mfma_f32_16x16x32_bf16 v[126:129], v[150:153], v[182:185], v[126:129]
	v_mfma_f32_16x16x32_bf16 v[118:121], v[158:161], v[182:185], v[118:121]
	v_mfma_f32_16x16x32_bf16 v[110:113], v[150:153], v[190:193], v[110:113]
	v_mfma_f32_16x16x32_bf16 v[102:105], v[158:161], v[190:193], v[102:105]
	v_mfma_f32_16x16x32_bf16 v[94:97], v[150:153], v[198:201], v[94:97]
	v_mfma_f32_16x16x32_bf16 v[86:89], v[158:161], v[198:201], v[86:89]
	v_mfma_f32_16x16x32_bf16 v[78:81], v[150:153], v[212:215], v[78:81]
	v_mfma_f32_16x16x32_bf16 v[70:73], v[158:161], v[212:215], v[70:73]
	s_setprio 0
	s_setprio 1
	v_mfma_f32_16x16x32_bf16 v[122:125], v[162:165], v[178:181], v[122:125]
	v_mfma_f32_16x16x32_bf16 v[114:117], v[170:173], v[178:181], v[114:117]
	v_mfma_f32_16x16x32_bf16 v[106:109], v[162:165], v[186:189], v[106:109]
	v_mfma_f32_16x16x32_bf16 v[98:101], v[170:173], v[186:189], v[98:101]
	v_mfma_f32_16x16x32_bf16 v[90:93], v[162:165], v[194:197], v[90:93]
	v_mfma_f32_16x16x32_bf16 v[82:85], v[170:173], v[194:197], v[82:85]
	v_mfma_f32_16x16x32_bf16 v[74:77], v[162:165], v[208:211], v[74:77]
	v_mfma_f32_16x16x32_bf16 v[66:69], v[170:173], v[208:211], v[66:69]
	v_mfma_f32_16x16x32_bf16 v[122:125], v[166:169], v[182:185], v[122:125]
	v_mfma_f32_16x16x32_bf16 v[114:117], v[174:177], v[182:185], v[114:117]
	v_mfma_f32_16x16x32_bf16 v[106:109], v[166:169], v[190:193], v[106:109]
	v_mfma_f32_16x16x32_bf16 v[98:101], v[174:177], v[190:193], v[98:101]
	v_mfma_f32_16x16x32_bf16 v[90:93], v[166:169], v[198:201], v[90:93]
	v_mfma_f32_16x16x32_bf16 v[82:85], v[174:177], v[198:201], v[82:85]
	v_mfma_f32_16x16x32_bf16 v[74:77], v[166:169], v[212:215], v[74:77]
	v_mfma_f32_16x16x32_bf16 v[66:69], v[174:177], v[212:215], v[66:69]
	s_barrier
	s_setprio 0
	s_add_i32 s0, s33, s26
	v_lshl_add_u64 v[140:141], s[20:21], 0, v[202:203]
	s_mov_b32 m0, s0
	ds_read_b128 v[178:181], v145 offset:16384
	ds_read_b128 v[182:185], v145 offset:17408
	ds_read_b128 v[186:189], v145 offset:18432
	ds_read_b128 v[190:193], v145 offset:19456
	ds_read_b128 v[194:197], v145 offset:20480
	ds_read_b128 v[198:201], v145 offset:21504
	ds_read_b128 v[208:211], v145 offset:22528
	ds_read_b128 v[212:215], v145 offset:23552
	global_load_lds_dwordx4 v[140:141], off
	s_add_i32 m0, s0, 0x2000
	s_add_u32 s0, s20, 0x80000
	v_lshl_add_u64 v[204:205], s[20:21], 0, v[130:131]
	s_addc_u32 s1, s21, 0
	s_add_i32 s33, s55, s26
	global_load_lds_dwordx4 v[204:205], off
	v_lshl_add_u64 v[206:207], s[0:1], 0, v[202:203]
	s_mov_b32 m0, s33
	v_lshl_add_u64 v[216:217], s[22:23], 0, v[132:133]
	global_load_lds_dwordx4 v[206:207], off
	v_lshl_add_u64 v[206:207], s[0:1], 0, v[130:131]
	s_add_i32 m0, s33, 0x2000
	s_nop 0
	global_load_lds_dwordx4 v[206:207], off
	v_lshl_add_u64 v[206:207], s[22:23], 0, v[134:135]
	s_mov_b32 m0, s27
	s_nop 0
	global_load_lds_dwordx4 v[206:207], off
	s_mov_b32 m0, s28
	s_nop 0
	global_load_lds_dwordx4 v[216:217], off
	s_waitcnt vmcnt(8)
	s_waitcnt lgkmcnt(0)
	s_setprio 1
	s_barrier
	v_mfma_f32_16x16x32_bf16 v[62:65], v[146:149], v[178:181], v[62:65]
	v_mfma_f32_16x16x32_bf16 v[54:57], v[154:157], v[178:181], v[54:57]
	v_mfma_f32_16x16x32_bf16 v[46:49], v[146:149], v[186:189], v[46:49]
	v_mfma_f32_16x16x32_bf16 v[38:41], v[154:157], v[186:189], v[38:41]
	v_mfma_f32_16x16x32_bf16 v[30:33], v[146:149], v[194:197], v[30:33]
	v_mfma_f32_16x16x32_bf16 v[22:25], v[154:157], v[194:197], v[22:25]
	v_mfma_f32_16x16x32_bf16 v[14:17], v[146:149], v[208:211], v[14:17]
	v_mfma_f32_16x16x32_bf16 v[6:9], v[154:157], v[208:211], v[6:9]
	v_mfma_f32_16x16x32_bf16 v[62:65], v[150:153], v[182:185], v[62:65]
	v_mfma_f32_16x16x32_bf16 v[54:57], v[158:161], v[182:185], v[54:57]
	v_mfma_f32_16x16x32_bf16 v[46:49], v[150:153], v[190:193], v[46:49]
	v_mfma_f32_16x16x32_bf16 v[38:41], v[158:161], v[190:193], v[38:41]
	v_mfma_f32_16x16x32_bf16 v[30:33], v[150:153], v[198:201], v[30:33]
	v_mfma_f32_16x16x32_bf16 v[22:25], v[158:161], v[198:201], v[22:25]
	v_mfma_f32_16x16x32_bf16 v[14:17], v[150:153], v[212:215], v[14:17]
	v_mfma_f32_16x16x32_bf16 v[6:9], v[158:161], v[212:215], v[6:9]
	s_setprio 0
	s_setprio 1
	v_mfma_f32_16x16x32_bf16 v[58:61], v[162:165], v[178:181], v[58:61]
	v_mfma_f32_16x16x32_bf16 v[50:53], v[170:173], v[178:181], v[50:53]
	v_mfma_f32_16x16x32_bf16 v[42:45], v[162:165], v[186:189], v[42:45]
	v_mfma_f32_16x16x32_bf16 v[34:37], v[170:173], v[186:189], v[34:37]
	v_mfma_f32_16x16x32_bf16 v[26:29], v[162:165], v[194:197], v[26:29]
	v_mfma_f32_16x16x32_bf16 v[18:21], v[170:173], v[194:197], v[18:21]
	v_mfma_f32_16x16x32_bf16 v[10:13], v[162:165], v[208:211], v[10:13]
	v_mfma_f32_16x16x32_bf16 v[2:5], v[170:173], v[208:211], v[2:5]
	v_mfma_f32_16x16x32_bf16 v[58:61], v[166:169], v[182:185], v[58:61]
	v_mfma_f32_16x16x32_bf16 v[50:53], v[174:177], v[182:185], v[50:53]
	v_mfma_f32_16x16x32_bf16 v[42:45], v[166:169], v[190:193], v[42:45]
	v_mfma_f32_16x16x32_bf16 v[34:37], v[174:177], v[190:193], v[34:37]
	v_mfma_f32_16x16x32_bf16 v[26:29], v[166:169], v[198:201], v[26:29]
	v_mfma_f32_16x16x32_bf16 v[18:21], v[174:177], v[198:201], v[18:21]
	v_mfma_f32_16x16x32_bf16 v[10:13], v[166:169], v[212:215], v[10:13]
	v_mfma_f32_16x16x32_bf16 v[2:5], v[174:177], v[212:215], v[2:5]
	s_barrier
	s_setprio 0
	s_add_i32 s33, 0, 0x18000
	s_add_i32 s55, 0, 0x1c000
	v_add_u32_e32 v158, s33, v143
	v_add_u32_e32 v174, s55, v143
	ds_read_b128 v[146:149], v158
	ds_read_b128 v[150:153], v158 offset:1024
	ds_read_b128 v[154:157], v158 offset:2048
	ds_read_b128 v[158:161], v158 offset:3072
	ds_read_b128 v[162:165], v174
	ds_read_b128 v[166:169], v174 offset:1024
	ds_read_b128 v[170:173], v174 offset:2048
	ds_read_b128 v[174:177], v174 offset:3072
	s_add_u32 s0, s22, 0x80000
	s_addc_u32 s1, s23, 0
	s_mov_b32 m0, s29
	v_lshl_add_u64 v[218:219], s[0:1], 0, v[134:135]
	ds_read_b128 v[178:181], v145 offset:32768
	ds_read_b128 v[182:185], v145 offset:33792
	ds_read_b128 v[186:189], v145 offset:34816
	ds_read_b128 v[190:193], v145 offset:35840
	ds_read_b128 v[194:197], v145 offset:36864
	ds_read_b128 v[198:201], v145 offset:37888
	ds_read_b128 v[208:211], v145 offset:38912
	ds_read_b128 v[212:215], v145 offset:39936
	global_load_lds_dwordx4 v[218:219], off
	v_lshl_add_u64 v[218:219], s[0:1], 0, v[132:133]
	s_mov_b32 m0, s30
	s_nop 0
	global_load_lds_dwordx4 v[218:219], off
	s_waitcnt vmcnt(8)
	s_waitcnt lgkmcnt(0)
	s_setprio 1
	s_barrier
	v_mfma_f32_16x16x32_bf16 v[126:129], v[146:149], v[178:181], v[126:129]
	v_mfma_f32_16x16x32_bf16 v[118:121], v[154:157], v[178:181], v[118:121]
	v_mfma_f32_16x16x32_bf16 v[110:113], v[146:149], v[186:189], v[110:113]
	v_mfma_f32_16x16x32_bf16 v[102:105], v[154:157], v[186:189], v[102:105]
	v_mfma_f32_16x16x32_bf16 v[94:97], v[146:149], v[194:197], v[94:97]
	v_mfma_f32_16x16x32_bf16 v[86:89], v[154:157], v[194:197], v[86:89]
	v_mfma_f32_16x16x32_bf16 v[78:81], v[146:149], v[208:211], v[78:81]
	v_mfma_f32_16x16x32_bf16 v[70:73], v[154:157], v[208:211], v[70:73]
	v_mfma_f32_16x16x32_bf16 v[126:129], v[150:153], v[182:185], v[126:129]
	v_mfma_f32_16x16x32_bf16 v[118:121], v[158:161], v[182:185], v[118:121]
	v_mfma_f32_16x16x32_bf16 v[110:113], v[150:153], v[190:193], v[110:113]
	v_mfma_f32_16x16x32_bf16 v[102:105], v[158:161], v[190:193], v[102:105]
	v_mfma_f32_16x16x32_bf16 v[94:97], v[150:153], v[198:201], v[94:97]
	v_mfma_f32_16x16x32_bf16 v[86:89], v[158:161], v[198:201], v[86:89]
	v_mfma_f32_16x16x32_bf16 v[78:81], v[150:153], v[212:215], v[78:81]
	v_mfma_f32_16x16x32_bf16 v[70:73], v[158:161], v[212:215], v[70:73]
	s_setprio 0
	s_setprio 1
	v_mfma_f32_16x16x32_bf16 v[122:125], v[162:165], v[178:181], v[122:125]
	v_mfma_f32_16x16x32_bf16 v[114:117], v[170:173], v[178:181], v[114:117]
	v_mfma_f32_16x16x32_bf16 v[106:109], v[162:165], v[186:189], v[106:109]
	v_mfma_f32_16x16x32_bf16 v[98:101], v[170:173], v[186:189], v[98:101]
	v_mfma_f32_16x16x32_bf16 v[90:93], v[162:165], v[194:197], v[90:93]
	v_mfma_f32_16x16x32_bf16 v[82:85], v[170:173], v[194:197], v[82:85]
	v_mfma_f32_16x16x32_bf16 v[74:77], v[162:165], v[208:211], v[74:77]
	v_mfma_f32_16x16x32_bf16 v[66:69], v[170:173], v[208:211], v[66:69]
	v_mfma_f32_16x16x32_bf16 v[122:125], v[166:169], v[182:185], v[122:125]
	v_mfma_f32_16x16x32_bf16 v[114:117], v[174:177], v[182:185], v[114:117]
	v_mfma_f32_16x16x32_bf16 v[106:109], v[166:169], v[190:193], v[106:109]
	v_mfma_f32_16x16x32_bf16 v[98:101], v[174:177], v[190:193], v[98:101]
	v_mfma_f32_16x16x32_bf16 v[90:93], v[166:169], v[198:201], v[90:93]
	v_mfma_f32_16x16x32_bf16 v[82:85], v[174:177], v[198:201], v[82:85]
	v_mfma_f32_16x16x32_bf16 v[74:77], v[166:169], v[212:215], v[74:77]
	v_mfma_f32_16x16x32_bf16 v[66:69], v[174:177], v[212:215], v[66:69]
	s_barrier
	s_setprio 0
	s_add_i32 s0, s33, s26
	v_lshl_add_u64 v[140:141], v[140:141], 0, s[80:81]
	s_mov_b32 m0, s0
	ds_read_b128 v[178:181], v145 offset:49152
	ds_read_b128 v[182:185], v145 offset:50176
	ds_read_b128 v[186:189], v145 offset:51200
	ds_read_b128 v[190:193], v145 offset:52224
	ds_read_b128 v[194:197], v145 offset:53248
	ds_read_b128 v[198:201], v145 offset:54272
	ds_read_b128 v[208:211], v145 offset:55296
	ds_read_b128 v[212:215], v145 offset:56320
	global_load_lds_dwordx4 v[140:141], off
	s_add_i32 m0, s0, 0x2000
	s_add_u32 s0, s20, 0x80080
	v_lshl_add_u64 v[140:141], v[204:205], 0, s[80:81]
	s_addc_u32 s1, s21, 0
	s_add_i32 s20, s55, s26
	global_load_lds_dwordx4 v[140:141], off
	v_lshl_add_u64 v[140:141], s[0:1], 0, v[202:203]
	s_mov_b32 m0, s20
	s_nop 0
	global_load_lds_dwordx4 v[140:141], off
	v_lshl_add_u64 v[140:141], s[0:1], 0, v[130:131]
	s_add_i32 m0, s20, 0x2000
	s_nop 0
	global_load_lds_dwordx4 v[140:141], off
	v_lshl_add_u64 v[140:141], v[206:207], 0, s[80:81]
	s_mov_b32 m0, s31
	s_nop 0
	global_load_lds_dwordx4 v[140:141], off
	v_lshl_add_u64 v[140:141], v[216:217], 0, s[80:81]
	s_mov_b32 m0, s34
	s_nop 0
	global_load_lds_dwordx4 v[140:141], off
	s_waitcnt vmcnt(8)
	s_waitcnt lgkmcnt(0)
	s_setprio 1
	s_barrier
	v_mfma_f32_16x16x32_bf16 v[62:65], v[146:149], v[178:181], v[62:65]
	v_mfma_f32_16x16x32_bf16 v[54:57], v[154:157], v[178:181], v[54:57]
	v_mfma_f32_16x16x32_bf16 v[46:49], v[146:149], v[186:189], v[46:49]
	v_mfma_f32_16x16x32_bf16 v[38:41], v[154:157], v[186:189], v[38:41]
	v_mfma_f32_16x16x32_bf16 v[30:33], v[146:149], v[194:197], v[30:33]
	v_mfma_f32_16x16x32_bf16 v[22:25], v[154:157], v[194:197], v[22:25]
	v_mfma_f32_16x16x32_bf16 v[14:17], v[146:149], v[208:211], v[14:17]
	v_mfma_f32_16x16x32_bf16 v[6:9], v[154:157], v[208:211], v[6:9]
	v_mfma_f32_16x16x32_bf16 v[62:65], v[150:153], v[182:185], v[62:65]
	v_mfma_f32_16x16x32_bf16 v[54:57], v[158:161], v[182:185], v[54:57]
	v_mfma_f32_16x16x32_bf16 v[46:49], v[150:153], v[190:193], v[46:49]
	v_mfma_f32_16x16x32_bf16 v[38:41], v[158:161], v[190:193], v[38:41]
	v_mfma_f32_16x16x32_bf16 v[30:33], v[150:153], v[198:201], v[30:33]
	v_mfma_f32_16x16x32_bf16 v[22:25], v[158:161], v[198:201], v[22:25]
	v_mfma_f32_16x16x32_bf16 v[14:17], v[150:153], v[212:215], v[14:17]
	v_mfma_f32_16x16x32_bf16 v[6:9], v[158:161], v[212:215], v[6:9]
	s_setprio 0
	s_setprio 1
	v_mfma_f32_16x16x32_bf16 v[58:61], v[162:165], v[178:181], v[58:61]
	v_mfma_f32_16x16x32_bf16 v[50:53], v[170:173], v[178:181], v[50:53]
	v_mfma_f32_16x16x32_bf16 v[42:45], v[162:165], v[186:189], v[42:45]
	v_mfma_f32_16x16x32_bf16 v[34:37], v[170:173], v[186:189], v[34:37]
	v_mfma_f32_16x16x32_bf16 v[26:29], v[162:165], v[194:197], v[26:29]
	v_mfma_f32_16x16x32_bf16 v[18:21], v[170:173], v[194:197], v[18:21]
	v_mfma_f32_16x16x32_bf16 v[10:13], v[162:165], v[208:211], v[10:13]
	v_mfma_f32_16x16x32_bf16 v[2:5], v[170:173], v[208:211], v[2:5]
	v_mfma_f32_16x16x32_bf16 v[58:61], v[166:169], v[182:185], v[58:61]
	v_mfma_f32_16x16x32_bf16 v[50:53], v[174:177], v[182:185], v[50:53]
	v_mfma_f32_16x16x32_bf16 v[42:45], v[166:169], v[190:193], v[42:45]
	v_mfma_f32_16x16x32_bf16 v[34:37], v[174:177], v[190:193], v[34:37]
	v_mfma_f32_16x16x32_bf16 v[26:29], v[166:169], v[198:201], v[26:29]
	v_mfma_f32_16x16x32_bf16 v[18:21], v[174:177], v[198:201], v[18:21]
	v_mfma_f32_16x16x32_bf16 v[10:13], v[166:169], v[212:215], v[10:13]
	v_mfma_f32_16x16x32_bf16 v[2:5], v[174:177], v[212:215], v[2:5]
	s_barrier
	s_setprio 0
	s_add_i32 s59, s59, 2
	s_add_u32 s18, s18, 0x100
	s_addc_u32 s19, s19, 0
	s_add_u32 s49, s49, 0x100
	s_addc_u32 s58, s58, 0
	s_cmp_gt_u32 s59, 29
	s_cbranch_scc0 .LBB0_837
	s_and_b64 vcc, exec, s[6:7]
	s_cbranch_vccz .LBB0_840
	s_barrier

.LBB0_970:
	s_add_u32 s16, s2, 0x100
	s_addc_u32 s17, s3, 0
	s_add_i32 s0, 0, 0x10000
	s_cmpk_eq_i32 s59, 0x54
	s_cselect_b32 s21, s7, s17
	s_cselect_b32 s20, s6, s16
	s_cselect_b32 s19, s15, s58
	s_cselect_b32 s18, s14, s49
	s_add_i32 s33, 0, 0x14000
	v_add_u32_e32 v98, s0, v205
	v_add_u32_e32 v134, s33, v205
	ds_read_b128 v[78:81], v98
	ds_read_b128 v[82:85], v98 offset:1024
	ds_read_b128 v[94:97], v98 offset:2048
	ds_read_b128 v[98:101], v98 offset:3072
	ds_read_b128 v[106:109], v134
	ds_read_b128 v[110:113], v134 offset:1024
	ds_read_b128 v[126:129], v134 offset:2048
	ds_read_b128 v[134:137], v134 offset:3072
	v_lshl_add_u64 v[194:195], s[2:3], 0, v[214:215]
	s_add_i32 m0, s25, 0xc000
	ds_read_b128 v[146:149], v239
	ds_read_b128 v[158:161], v239 offset:1024
	ds_read_b128 v[166:169], v239 offset:2048
	ds_read_b128 v[174:177], v239 offset:3072
	ds_read_b128 v[178:181], v239 offset:4096
	ds_read_b128 v[182:185], v239 offset:5120
	ds_read_b128 v[186:189], v239 offset:6144
	ds_read_b128 v[190:193], v239 offset:7168
	global_load_lds_dwordx4 v[194:195], off
	v_lshl_add_u64 v[194:195], s[2:3], 0, v[216:217]
	s_add_i32 m0, s25, 0xe000
	s_nop 0
	global_load_lds_dwordx4 v[194:195], off
	s_waitcnt vmcnt(8)
	s_waitcnt lgkmcnt(0)
	s_setprio 1
	s_barrier
	v_mfma_f32_16x16x32_bf16 v[170:173], v[78:81], v[146:149], v[170:173]
	v_mfma_f32_16x16x32_bf16 v[162:165], v[94:97], v[146:149], v[162:165]
	v_mfma_f32_16x16x32_bf16 v[142:145], v[78:81], v[166:169], v[142:145]
	v_mfma_f32_16x16x32_bf16 v[138:141], v[94:97], v[166:169], v[138:141]
	v_mfma_f32_16x16x32_bf16 v[118:121], v[78:81], v[178:181], v[118:121]
	v_mfma_f32_16x16x32_bf16 v[114:117], v[94:97], v[178:181], v[114:117]
	v_mfma_f32_16x16x32_bf16 v[86:89], v[78:81], v[186:189], v[86:89]
	v_mfma_f32_16x16x32_bf16 v[74:77], v[94:97], v[186:189], v[74:77]
	v_mfma_f32_16x16x32_bf16 v[170:173], v[82:85], v[158:161], v[170:173]
	v_mfma_f32_16x16x32_bf16 v[162:165], v[98:101], v[158:161], v[162:165]
	v_mfma_f32_16x16x32_bf16 v[142:145], v[82:85], v[174:177], v[142:145]
	v_mfma_f32_16x16x32_bf16 v[138:141], v[98:101], v[174:177], v[138:141]
	v_mfma_f32_16x16x32_bf16 v[118:121], v[82:85], v[182:185], v[118:121]
	v_mfma_f32_16x16x32_bf16 v[114:117], v[98:101], v[182:185], v[114:117]
	v_mfma_f32_16x16x32_bf16 v[86:89], v[82:85], v[190:193], v[86:89]
	v_mfma_f32_16x16x32_bf16 v[74:77], v[98:101], v[190:193], v[74:77]
	s_setprio 0
	s_setprio 1
	v_mfma_f32_16x16x32_bf16 v[154:157], v[106:109], v[146:149], v[154:157]
	v_mfma_f32_16x16x32_bf16 v[130:133], v[106:109], v[166:169], v[130:133]
	v_mfma_f32_16x16x32_bf16 v[122:125], v[126:129], v[166:169], v[122:125]
	v_mfma_f32_16x16x32_bf16 v[102:105], v[106:109], v[178:181], v[102:105]
	v_mfma_f32_16x16x32_bf16 v[90:93], v[126:129], v[178:181], v[90:93]
	v_mfma_f32_16x16x32_bf16 v[70:73], v[106:109], v[186:189], v[70:73]
	v_mfma_f32_16x16x32_bf16 v[66:69], v[126:129], v[186:189], v[66:69]
	v_mfma_f32_16x16x32_bf16 v[154:157], v[110:113], v[158:161], v[154:157]
	v_mfma_f32_16x16x32_bf16 v[146:149], v[126:129], v[146:149], v[150:153]
	v_mfma_f32_16x16x32_bf16 v[130:133], v[110:113], v[174:177], v[130:133]
	v_mfma_f32_16x16x32_bf16 v[122:125], v[134:137], v[174:177], v[122:125]
	v_mfma_f32_16x16x32_bf16 v[102:105], v[110:113], v[182:185], v[102:105]
	v_mfma_f32_16x16x32_bf16 v[90:93], v[134:137], v[182:185], v[90:93]
	v_mfma_f32_16x16x32_bf16 v[70:73], v[110:113], v[190:193], v[70:73]
	v_mfma_f32_16x16x32_bf16 v[66:69], v[134:137], v[190:193], v[66:69]
	v_mfma_f32_16x16x32_bf16 v[146:149], v[134:137], v[158:161], v[146:149]
	s_barrier
	s_setprio 0
	s_add_i32 s0, s0, s24
	v_lshl_add_u64 v[194:195], s[18:19], 0, v[202:203]
	s_mov_b32 m0, s0
	ds_read_b128 v[150:153], v239 offset:16384
	ds_read_b128 v[158:161], v239 offset:17408
	ds_read_b128 v[166:169], v239 offset:18432
	ds_read_b128 v[174:177], v239 offset:19456
	ds_read_b128 v[178:181], v239 offset:20480
	ds_read_b128 v[182:185], v239 offset:21504
	ds_read_b128 v[186:189], v239 offset:22528
	ds_read_b128 v[190:193], v239 offset:23552
	global_load_lds_dwordx4 v[194:195], off
	s_add_i32 m0, s0, 0x2000
	s_add_u32 s0, s18, 0x160000
	v_lshl_add_u64 v[196:197], s[18:19], 0, v[208:209]
	s_addc_u32 s1, s19, 0
	s_add_i32 s2, s33, s24
	global_load_lds_dwordx4 v[196:197], off
	v_lshl_add_u64 v[198:199], s[0:1], 0, v[202:203]
	s_mov_b32 m0, s2
	v_lshl_add_u64 v[200:201], s[20:21], 0, v[210:211]
	global_load_lds_dwordx4 v[198:199], off
	v_lshl_add_u64 v[198:199], s[0:1], 0, v[208:209]
	s_add_i32 m0, s2, 0x2000
	s_nop 0
	global_load_lds_dwordx4 v[198:199], off
	v_lshl_add_u64 v[198:199], s[20:21], 0, v[212:213]
	s_mov_b32 m0, s25
	s_nop 0
	global_load_lds_dwordx4 v[198:199], off
	s_mov_b32 m0, s26
	s_nop 0
	global_load_lds_dwordx4 v[200:201], off
	s_waitcnt vmcnt(8)
	s_waitcnt lgkmcnt(0)
	s_setprio 1
	s_barrier
	v_mfma_f32_16x16x32_bf16 v[62:65], v[78:81], v[150:153], v[62:65]
	v_mfma_f32_16x16x32_bf16 v[58:61], v[94:97], v[150:153], v[58:61]
	v_mfma_f32_16x16x32_bf16 v[46:49], v[78:81], v[166:169], v[46:49]
	v_mfma_f32_16x16x32_bf16 v[42:45], v[94:97], v[166:169], v[42:45]
	v_mfma_f32_16x16x32_bf16 v[30:33], v[78:81], v[178:181], v[30:33]
	v_mfma_f32_16x16x32_bf16 v[26:29], v[94:97], v[178:181], v[26:29]
	v_mfma_f32_16x16x32_bf16 v[14:17], v[78:81], v[186:189], v[14:17]
	v_mfma_f32_16x16x32_bf16 v[10:13], v[94:97], v[186:189], v[10:13]
	v_mfma_f32_16x16x32_bf16 v[62:65], v[82:85], v[158:161], v[62:65]
	v_mfma_f32_16x16x32_bf16 v[58:61], v[98:101], v[158:161], v[58:61]
	v_mfma_f32_16x16x32_bf16 v[46:49], v[82:85], v[174:177], v[46:49]
	v_mfma_f32_16x16x32_bf16 v[42:45], v[98:101], v[174:177], v[42:45]
	v_mfma_f32_16x16x32_bf16 v[30:33], v[82:85], v[182:185], v[30:33]
	v_mfma_f32_16x16x32_bf16 v[26:29], v[98:101], v[182:185], v[26:29]
	v_mfma_f32_16x16x32_bf16 v[14:17], v[82:85], v[190:193], v[14:17]
	v_mfma_f32_16x16x32_bf16 v[10:13], v[98:101], v[190:193], v[10:13]
	s_setprio 0
	s_setprio 1
	v_mfma_f32_16x16x32_bf16 v[54:57], v[106:109], v[150:153], v[54:57]
	v_mfma_f32_16x16x32_bf16 v[50:53], v[126:129], v[150:153], v[50:53]
	v_mfma_f32_16x16x32_bf16 v[38:41], v[106:109], v[166:169], v[38:41]
	v_mfma_f32_16x16x32_bf16 v[34:37], v[126:129], v[166:169], v[34:37]
	v_mfma_f32_16x16x32_bf16 v[22:25], v[106:109], v[178:181], v[22:25]
	v_mfma_f32_16x16x32_bf16 v[18:21], v[126:129], v[178:181], v[18:21]
	v_mfma_f32_16x16x32_bf16 v[6:9], v[106:109], v[186:189], v[6:9]
	v_mfma_f32_16x16x32_bf16 v[2:5], v[126:129], v[186:189], v[2:5]
	v_mfma_f32_16x16x32_bf16 v[54:57], v[110:113], v[158:161], v[54:57]
	v_mfma_f32_16x16x32_bf16 v[50:53], v[134:137], v[158:161], v[50:53]
	v_mfma_f32_16x16x32_bf16 v[38:41], v[110:113], v[174:177], v[38:41]
	v_mfma_f32_16x16x32_bf16 v[34:37], v[134:137], v[174:177], v[34:37]
	v_mfma_f32_16x16x32_bf16 v[22:25], v[110:113], v[182:185], v[22:25]
	v_mfma_f32_16x16x32_bf16 v[18:21], v[134:137], v[182:185], v[18:21]
	v_mfma_f32_16x16x32_bf16 v[6:9], v[110:113], v[190:193], v[6:9]
	v_mfma_f32_16x16x32_bf16 v[2:5], v[134:137], v[190:193], v[2:5]
	s_barrier
	s_setprio 0
	s_add_i32 s2, 0, 0x18000
	s_add_i32 s3, 0, 0x1c000
	v_add_u32_e32 v98, s2, v205
	v_add_u32_e32 v134, s3, v205
	ds_read_b128 v[78:81], v98
	ds_read_b128 v[82:85], v98 offset:1024
	ds_read_b128 v[94:97], v98 offset:2048
	ds_read_b128 v[98:101], v98 offset:3072
	ds_read_b128 v[106:109], v134
	ds_read_b128 v[110:113], v134 offset:1024
	ds_read_b128 v[126:129], v134 offset:2048
	ds_read_b128 v[134:137], v134 offset:3072
	s_add_u32 s0, s20, 0x160000
	s_addc_u32 s1, s21, 0
	s_mov_b32 m0, s27
	v_lshl_add_u64 v[206:207], s[0:1], 0, v[212:213]
	ds_read_b128 v[150:153], v239 offset:32768
	ds_read_b128 v[158:161], v239 offset:33792
	ds_read_b128 v[166:169], v239 offset:34816
	ds_read_b128 v[174:177], v239 offset:35840
	ds_read_b128 v[178:181], v239 offset:36864
	ds_read_b128 v[182:185], v239 offset:37888
	ds_read_b128 v[186:189], v239 offset:38912
	ds_read_b128 v[190:193], v239 offset:39936
	global_load_lds_dwordx4 v[206:207], off
	v_lshl_add_u64 v[206:207], s[0:1], 0, v[210:211]
	s_mov_b32 m0, s28
	s_nop 0
	global_load_lds_dwordx4 v[206:207], off
	s_waitcnt vmcnt(8)
	s_waitcnt lgkmcnt(0)
	s_setprio 1
	s_barrier
	v_mfma_f32_16x16x32_bf16 v[170:173], v[78:81], v[150:153], v[170:173]
	v_mfma_f32_16x16x32_bf16 v[162:165], v[94:97], v[150:153], v[162:165]
	v_mfma_f32_16x16x32_bf16 v[142:145], v[78:81], v[166:169], v[142:145]
	v_mfma_f32_16x16x32_bf16 v[138:141], v[94:97], v[166:169], v[138:141]
	v_mfma_f32_16x16x32_bf16 v[118:121], v[78:81], v[178:181], v[118:121]
	v_mfma_f32_16x16x32_bf16 v[114:117], v[94:97], v[178:181], v[114:117]
	v_mfma_f32_16x16x32_bf16 v[86:89], v[78:81], v[186:189], v[86:89]
	v_mfma_f32_16x16x32_bf16 v[74:77], v[94:97], v[186:189], v[74:77]
	v_mfma_f32_16x16x32_bf16 v[170:173], v[82:85], v[158:161], v[170:173]
	v_mfma_f32_16x16x32_bf16 v[162:165], v[98:101], v[158:161], v[162:165]
	v_mfma_f32_16x16x32_bf16 v[142:145], v[82:85], v[174:177], v[142:145]
	v_mfma_f32_16x16x32_bf16 v[138:141], v[98:101], v[174:177], v[138:141]
	v_mfma_f32_16x16x32_bf16 v[118:121], v[82:85], v[182:185], v[118:121]
	v_mfma_f32_16x16x32_bf16 v[114:117], v[98:101], v[182:185], v[114:117]
	v_mfma_f32_16x16x32_bf16 v[86:89], v[82:85], v[190:193], v[86:89]
	v_mfma_f32_16x16x32_bf16 v[74:77], v[98:101], v[190:193], v[74:77]
	s_setprio 0
	s_setprio 1
	v_mfma_f32_16x16x32_bf16 v[154:157], v[106:109], v[150:153], v[154:157]
	v_mfma_f32_16x16x32_bf16 v[146:149], v[126:129], v[150:153], v[146:149]
	v_mfma_f32_16x16x32_bf16 v[130:133], v[106:109], v[166:169], v[130:133]
	v_mfma_f32_16x16x32_bf16 v[122:125], v[126:129], v[166:169], v[122:125]
	v_mfma_f32_16x16x32_bf16 v[102:105], v[106:109], v[178:181], v[102:105]
	v_mfma_f32_16x16x32_bf16 v[90:93], v[126:129], v[178:181], v[90:93]
	v_mfma_f32_16x16x32_bf16 v[70:73], v[106:109], v[186:189], v[70:73]
	v_mfma_f32_16x16x32_bf16 v[66:69], v[126:129], v[186:189], v[66:69]
	v_mfma_f32_16x16x32_bf16 v[154:157], v[110:113], v[158:161], v[154:157]
	v_mfma_f32_16x16x32_bf16 v[150:153], v[134:137], v[158:161], v[146:149]
	v_mfma_f32_16x16x32_bf16 v[130:133], v[110:113], v[174:177], v[130:133]
	v_mfma_f32_16x16x32_bf16 v[122:125], v[134:137], v[174:177], v[122:125]
	v_mfma_f32_16x16x32_bf16 v[102:105], v[110:113], v[182:185], v[102:105]
	v_mfma_f32_16x16x32_bf16 v[90:93], v[134:137], v[182:185], v[90:93]
	v_mfma_f32_16x16x32_bf16 v[70:73], v[110:113], v[190:193], v[70:73]
	v_mfma_f32_16x16x32_bf16 v[66:69], v[134:137], v[190:193], v[66:69]
	s_barrier
	s_setprio 0
	s_add_i32 s0, s2, s24
	v_lshl_add_u64 v[194:195], v[194:195], 0, s[80:81]
	s_mov_b32 m0, s0
	ds_read_b128 v[146:149], v239 offset:49152
	ds_read_b128 v[158:161], v239 offset:50176
	ds_read_b128 v[166:169], v239 offset:51200
	ds_read_b128 v[174:177], v239 offset:52224
	ds_read_b128 v[178:181], v239 offset:53248
	ds_read_b128 v[182:185], v239 offset:54272
	ds_read_b128 v[186:189], v239 offset:55296
	ds_read_b128 v[190:193], v239 offset:56320
	global_load_lds_dwordx4 v[194:195], off
	s_add_i32 m0, s0, 0x2000
	s_add_u32 s0, s18, 0x160080
	v_lshl_add_u64 v[194:195], v[196:197], 0, s[80:81]
	s_addc_u32 s1, s19, 0
	s_add_i32 s2, s3, s24
	global_load_lds_dwordx4 v[194:195], off
	v_lshl_add_u64 v[194:195], s[0:1], 0, v[202:203]
	s_mov_b32 m0, s2
	s_nop 0
	global_load_lds_dwordx4 v[194:195], off
	v_lshl_add_u64 v[194:195], s[0:1], 0, v[208:209]
	s_add_i32 m0, s2, 0x2000
	s_nop 0
	global_load_lds_dwordx4 v[194:195], off
	v_lshl_add_u64 v[194:195], v[198:199], 0, s[80:81]
	s_mov_b32 m0, s31
	s_nop 0
	global_load_lds_dwordx4 v[194:195], off
	v_lshl_add_u64 v[194:195], v[200:201], 0, s[80:81]
	s_mov_b32 m0, s34
	s_nop 0
	global_load_lds_dwordx4 v[194:195], off
	s_waitcnt vmcnt(8)
	s_waitcnt lgkmcnt(0)
	s_setprio 1
	s_barrier
	v_mfma_f32_16x16x32_bf16 v[62:65], v[78:81], v[146:149], v[62:65]
	v_mfma_f32_16x16x32_bf16 v[58:61], v[94:97], v[146:149], v[58:61]
	v_mfma_f32_16x16x32_bf16 v[46:49], v[78:81], v[166:169], v[46:49]
	v_mfma_f32_16x16x32_bf16 v[42:45], v[94:97], v[166:169], v[42:45]
	v_mfma_f32_16x16x32_bf16 v[30:33], v[78:81], v[178:181], v[30:33]
	v_mfma_f32_16x16x32_bf16 v[26:29], v[94:97], v[178:181], v[26:29]
	v_mfma_f32_16x16x32_bf16 v[14:17], v[78:81], v[186:189], v[14:17]
	v_mfma_f32_16x16x32_bf16 v[10:13], v[94:97], v[186:189], v[10:13]
	v_mfma_f32_16x16x32_bf16 v[62:65], v[82:85], v[158:161], v[62:65]
	v_mfma_f32_16x16x32_bf16 v[58:61], v[98:101], v[158:161], v[58:61]
	v_mfma_f32_16x16x32_bf16 v[46:49], v[82:85], v[174:177], v[46:49]
	v_mfma_f32_16x16x32_bf16 v[42:45], v[98:101], v[174:177], v[42:45]
	v_mfma_f32_16x16x32_bf16 v[30:33], v[82:85], v[182:185], v[30:33]
	v_mfma_f32_16x16x32_bf16 v[26:29], v[98:101], v[182:185], v[26:29]
	v_mfma_f32_16x16x32_bf16 v[14:17], v[82:85], v[190:193], v[14:17]
	v_mfma_f32_16x16x32_bf16 v[10:13], v[98:101], v[190:193], v[10:13]
	s_setprio 0
	s_setprio 1
	v_mfma_f32_16x16x32_bf16 v[54:57], v[106:109], v[146:149], v[54:57]
	v_mfma_f32_16x16x32_bf16 v[50:53], v[126:129], v[146:149], v[50:53]
	v_mfma_f32_16x16x32_bf16 v[38:41], v[106:109], v[166:169], v[38:41]
	v_mfma_f32_16x16x32_bf16 v[34:37], v[126:129], v[166:169], v[34:37]
	v_mfma_f32_16x16x32_bf16 v[22:25], v[106:109], v[178:181], v[22:25]
	v_mfma_f32_16x16x32_bf16 v[18:21], v[126:129], v[178:181], v[18:21]
	v_mfma_f32_16x16x32_bf16 v[6:9], v[106:109], v[186:189], v[6:9]
	v_mfma_f32_16x16x32_bf16 v[2:5], v[126:129], v[186:189], v[2:5]
	v_mfma_f32_16x16x32_bf16 v[54:57], v[110:113], v[158:161], v[54:57]
	v_mfma_f32_16x16x32_bf16 v[50:53], v[134:137], v[158:161], v[50:53]
	v_mfma_f32_16x16x32_bf16 v[38:41], v[110:113], v[174:177], v[38:41]
	v_mfma_f32_16x16x32_bf16 v[34:37], v[134:137], v[174:177], v[34:37]
	v_mfma_f32_16x16x32_bf16 v[22:25], v[110:113], v[182:185], v[22:25]
	v_mfma_f32_16x16x32_bf16 v[18:21], v[134:137], v[182:185], v[18:21]
	v_mfma_f32_16x16x32_bf16 v[6:9], v[110:113], v[190:193], v[6:9]
	v_mfma_f32_16x16x32_bf16 v[2:5], v[134:137], v[190:193], v[2:5]
	s_barrier
	s_setprio 0
	s_add_i32 s59, s59, 2
	s_add_u32 s49, s49, 0x100
	s_addc_u32 s58, s58, 0
	s_cmpk_gt_u32 s59, 0x55
	s_mov_b64 s[2:3], s[16:17]
	s_cbranch_scc0 .LBB0_970
	s_and_b64 vcc, exec, s[10:11]
	s_cbranch_vccz .LBB0_973
	s_barrier

.LBB0_990:
	s_add_u32 s4, s2, 0x100
	s_addc_u32 s5, s3, 0
	s_add_i32 s0, 0, 0x10000
	s_cmp_eq_u32 s59, 4
	s_cselect_b32 s21, s15, s5
	s_cselect_b32 s20, s14, s4
	s_cselect_b32 s19, s17, s58
	s_cselect_b32 s18, s16, s49
	s_add_i32 s33, 0, 0x14000
	v_add_u32_e32 v152, s0, v136
	v_add_u32_e32 v168, s33, v136
	ds_read_b128 v[140:143], v152
	ds_read_b128 v[144:147], v152 offset:1024
	ds_read_b128 v[148:151], v152 offset:2048
	ds_read_b128 v[152:155], v152 offset:3072
	ds_read_b128 v[156:159], v168
	ds_read_b128 v[160:163], v168 offset:1024
	ds_read_b128 v[164:167], v168 offset:2048
	ds_read_b128 v[168:171], v168 offset:3072
	v_lshl_add_u64 v[200:201], s[2:3], 0, v[132:133]
	s_add_i32 m0, s25, 0xc000
	ds_read_b128 v[172:175], v139
	ds_read_b128 v[176:179], v139 offset:1024
	ds_read_b128 v[180:183], v139 offset:2048
	ds_read_b128 v[184:187], v139 offset:3072
	ds_read_b128 v[188:191], v139 offset:4096
	ds_read_b128 v[192:195], v139 offset:5120
	ds_read_b128 v[196:199], v139 offset:6144
	ds_read_b128 v[208:211], v139 offset:7168
	global_load_lds_dwordx4 v[200:201], off
	v_lshl_add_u64 v[200:201], s[2:3], 0, v[134:135]
	s_add_i32 m0, s25, 0xe000
	s_nop 0
	global_load_lds_dwordx4 v[200:201], off
	s_waitcnt vmcnt(8)
	s_waitcnt lgkmcnt(0)
	s_setprio 1
	s_barrier
	v_mfma_f32_16x16x32_bf16 v[126:129], v[140:143], v[172:175], v[126:129]
	v_mfma_f32_16x16x32_bf16 v[122:125], v[148:151], v[172:175], v[122:125]
	v_mfma_f32_16x16x32_bf16 v[118:121], v[140:143], v[180:183], v[118:121]
	v_mfma_f32_16x16x32_bf16 v[114:117], v[148:151], v[180:183], v[114:117]
	v_mfma_f32_16x16x32_bf16 v[106:109], v[140:143], v[188:191], v[106:109]
	v_mfma_f32_16x16x32_bf16 v[98:101], v[148:151], v[188:191], v[98:101]
	v_mfma_f32_16x16x32_bf16 v[90:93], v[140:143], v[196:199], v[90:93]
	v_mfma_f32_16x16x32_bf16 v[82:85], v[148:151], v[196:199], v[82:85]
	v_mfma_f32_16x16x32_bf16 v[126:129], v[144:147], v[176:179], v[126:129]
	v_mfma_f32_16x16x32_bf16 v[122:125], v[152:155], v[176:179], v[122:125]
	v_mfma_f32_16x16x32_bf16 v[118:121], v[144:147], v[184:187], v[118:121]
	v_mfma_f32_16x16x32_bf16 v[114:117], v[152:155], v[184:187], v[114:117]
	v_mfma_f32_16x16x32_bf16 v[106:109], v[144:147], v[192:195], v[106:109]
	v_mfma_f32_16x16x32_bf16 v[98:101], v[152:155], v[192:195], v[98:101]
	v_mfma_f32_16x16x32_bf16 v[90:93], v[144:147], v[208:211], v[90:93]
	v_mfma_f32_16x16x32_bf16 v[82:85], v[152:155], v[208:211], v[82:85]
	s_setprio 0
	s_setprio 1
	v_mfma_f32_16x16x32_bf16 v[110:113], v[156:159], v[172:175], v[110:113]
	v_mfma_f32_16x16x32_bf16 v[102:105], v[164:167], v[172:175], v[102:105]
	v_mfma_f32_16x16x32_bf16 v[94:97], v[156:159], v[180:183], v[94:97]
	v_mfma_f32_16x16x32_bf16 v[86:89], v[164:167], v[180:183], v[86:89]
	v_mfma_f32_16x16x32_bf16 v[78:81], v[156:159], v[188:191], v[78:81]
	v_mfma_f32_16x16x32_bf16 v[74:77], v[164:167], v[188:191], v[74:77]
	v_mfma_f32_16x16x32_bf16 v[70:73], v[156:159], v[196:199], v[70:73]
	v_mfma_f32_16x16x32_bf16 v[66:69], v[164:167], v[196:199], v[66:69]
	v_mfma_f32_16x16x32_bf16 v[110:113], v[160:163], v[176:179], v[110:113]
	v_mfma_f32_16x16x32_bf16 v[102:105], v[168:171], v[176:179], v[102:105]
	v_mfma_f32_16x16x32_bf16 v[94:97], v[160:163], v[184:187], v[94:97]
	v_mfma_f32_16x16x32_bf16 v[86:89], v[168:171], v[184:187], v[86:89]
	v_mfma_f32_16x16x32_bf16 v[78:81], v[160:163], v[192:195], v[78:81]
	v_mfma_f32_16x16x32_bf16 v[74:77], v[168:171], v[192:195], v[74:77]
	v_mfma_f32_16x16x32_bf16 v[70:73], v[160:163], v[208:211], v[70:73]
	v_mfma_f32_16x16x32_bf16 v[66:69], v[168:171], v[208:211], v[66:69]
	s_barrier
	s_setprio 0
	s_add_i32 s0, s0, s24
	v_lshl_add_u64 v[200:201], s[18:19], 0, v[202:203]
	s_mov_b32 m0, s0
	ds_read_b128 v[172:175], v139 offset:16384
	ds_read_b128 v[176:179], v139 offset:17408
	ds_read_b128 v[180:183], v139 offset:18432
	ds_read_b128 v[184:187], v139 offset:19456
	ds_read_b128 v[188:191], v139 offset:20480
	ds_read_b128 v[192:195], v139 offset:21504
	ds_read_b128 v[196:199], v139 offset:22528
	ds_read_b128 v[208:211], v139 offset:23552
	global_load_lds_dwordx4 v[200:201], off
	s_add_i32 m0, s0, 0x2000
	s_add_u32 s0, s18, 0x160000
	v_lshl_add_u64 v[204:205], s[18:19], 0, v[130:131]
	s_addc_u32 s1, s19, 0
	s_add_i32 s2, s33, s24
	global_load_lds_dwordx4 v[204:205], off
	v_lshl_add_u64 v[206:207], s[0:1], 0, v[202:203]
	s_mov_b32 m0, s2
	v_lshl_add_u64 v[212:213], s[20:21], 0, v[130:131]
	global_load_lds_dwordx4 v[206:207], off
	v_lshl_add_u64 v[206:207], s[0:1], 0, v[130:131]
	s_add_i32 m0, s2, 0x2000
	s_nop 0
	global_load_lds_dwordx4 v[206:207], off
	v_lshl_add_u64 v[206:207], s[20:21], 0, v[202:203]
	s_mov_b32 m0, s25
	s_nop 0
	global_load_lds_dwordx4 v[206:207], off
	s_mov_b32 m0, s26
	s_nop 0
	global_load_lds_dwordx4 v[212:213], off
	s_waitcnt vmcnt(8)
	s_waitcnt lgkmcnt(0)
	s_setprio 1
	s_barrier
	v_mfma_f32_16x16x32_bf16 v[62:65], v[140:143], v[172:175], v[62:65]
	v_mfma_f32_16x16x32_bf16 v[58:61], v[148:151], v[172:175], v[58:61]
	v_mfma_f32_16x16x32_bf16 v[54:57], v[140:143], v[180:183], v[54:57]
	v_mfma_f32_16x16x32_bf16 v[50:53], v[148:151], v[180:183], v[50:53]
	v_mfma_f32_16x16x32_bf16 v[38:41], v[140:143], v[188:191], v[38:41]
	v_mfma_f32_16x16x32_bf16 v[34:37], v[148:151], v[188:191], v[34:37]
	v_mfma_f32_16x16x32_bf16 v[22:25], v[140:143], v[196:199], v[22:25]
	v_mfma_f32_16x16x32_bf16 v[18:21], v[148:151], v[196:199], v[18:21]
	v_mfma_f32_16x16x32_bf16 v[62:65], v[144:147], v[176:179], v[62:65]
	v_mfma_f32_16x16x32_bf16 v[58:61], v[152:155], v[176:179], v[58:61]
	v_mfma_f32_16x16x32_bf16 v[54:57], v[144:147], v[184:187], v[54:57]
	v_mfma_f32_16x16x32_bf16 v[50:53], v[152:155], v[184:187], v[50:53]
	v_mfma_f32_16x16x32_bf16 v[38:41], v[144:147], v[192:195], v[38:41]
	v_mfma_f32_16x16x32_bf16 v[34:37], v[152:155], v[192:195], v[34:37]
	v_mfma_f32_16x16x32_bf16 v[22:25], v[144:147], v[208:211], v[22:25]
	v_mfma_f32_16x16x32_bf16 v[18:21], v[152:155], v[208:211], v[18:21]
	s_setprio 0
	s_setprio 1
	v_mfma_f32_16x16x32_bf16 v[46:49], v[156:159], v[172:175], v[46:49]
	v_mfma_f32_16x16x32_bf16 v[42:45], v[164:167], v[172:175], v[42:45]
	v_mfma_f32_16x16x32_bf16 v[30:33], v[156:159], v[180:183], v[30:33]
	v_mfma_f32_16x16x32_bf16 v[26:29], v[164:167], v[180:183], v[26:29]
	v_mfma_f32_16x16x32_bf16 v[14:17], v[156:159], v[188:191], v[14:17]
	v_mfma_f32_16x16x32_bf16 v[10:13], v[164:167], v[188:191], v[10:13]
	v_mfma_f32_16x16x32_bf16 v[6:9], v[156:159], v[196:199], v[6:9]
	v_mfma_f32_16x16x32_bf16 v[2:5], v[164:167], v[196:199], v[2:5]
	v_mfma_f32_16x16x32_bf16 v[46:49], v[160:163], v[176:179], v[46:49]
	v_mfma_f32_16x16x32_bf16 v[42:45], v[168:171], v[176:179], v[42:45]
	v_mfma_f32_16x16x32_bf16 v[30:33], v[160:163], v[184:187], v[30:33]
	v_mfma_f32_16x16x32_bf16 v[26:29], v[168:171], v[184:187], v[26:29]
	v_mfma_f32_16x16x32_bf16 v[14:17], v[160:163], v[192:195], v[14:17]
	v_mfma_f32_16x16x32_bf16 v[10:13], v[168:171], v[192:195], v[10:13]
	v_mfma_f32_16x16x32_bf16 v[6:9], v[160:163], v[208:211], v[6:9]
	v_mfma_f32_16x16x32_bf16 v[2:5], v[168:171], v[208:211], v[2:5]
	s_barrier
	s_setprio 0
	s_add_i32 s2, 0, 0x18000
	s_add_i32 s3, 0, 0x1c000
	v_add_u32_e32 v152, s2, v136
	v_add_u32_e32 v168, s3, v136
	ds_read_b128 v[140:143], v152
	ds_read_b128 v[144:147], v152 offset:1024
	ds_read_b128 v[148:151], v152 offset:2048
	ds_read_b128 v[152:155], v152 offset:3072
	ds_read_b128 v[156:159], v168
	ds_read_b128 v[160:163], v168 offset:1024
	ds_read_b128 v[164:167], v168 offset:2048
	ds_read_b128 v[168:171], v168 offset:3072
	s_add_u32 s0, s20, 0x160000
	s_addc_u32 s1, s21, 0
	s_mov_b32 m0, s27
	v_lshl_add_u64 v[214:215], s[0:1], 0, v[202:203]
	ds_read_b128 v[172:175], v139 offset:32768
	ds_read_b128 v[176:179], v139 offset:33792
	ds_read_b128 v[180:183], v139 offset:34816
	ds_read_b128 v[184:187], v139 offset:35840
	ds_read_b128 v[188:191], v139 offset:36864
	ds_read_b128 v[192:195], v139 offset:37888
	ds_read_b128 v[196:199], v139 offset:38912
	ds_read_b128 v[208:211], v139 offset:39936
	global_load_lds_dwordx4 v[214:215], off
	v_lshl_add_u64 v[214:215], s[0:1], 0, v[130:131]
	s_mov_b32 m0, s28
	s_nop 0
	global_load_lds_dwordx4 v[214:215], off
	s_waitcnt vmcnt(8)
	s_waitcnt lgkmcnt(0)
	s_setprio 1
	s_barrier
	v_mfma_f32_16x16x32_bf16 v[126:129], v[140:143], v[172:175], v[126:129]
	v_mfma_f32_16x16x32_bf16 v[122:125], v[148:151], v[172:175], v[122:125]
	v_mfma_f32_16x16x32_bf16 v[118:121], v[140:143], v[180:183], v[118:121]
	v_mfma_f32_16x16x32_bf16 v[114:117], v[148:151], v[180:183], v[114:117]
	v_mfma_f32_16x16x32_bf16 v[106:109], v[140:143], v[188:191], v[106:109]
	v_mfma_f32_16x16x32_bf16 v[98:101], v[148:151], v[188:191], v[98:101]
	v_mfma_f32_16x16x32_bf16 v[90:93], v[140:143], v[196:199], v[90:93]
	v_mfma_f32_16x16x32_bf16 v[82:85], v[148:151], v[196:199], v[82:85]
	v_mfma_f32_16x16x32_bf16 v[126:129], v[144:147], v[176:179], v[126:129]
	v_mfma_f32_16x16x32_bf16 v[122:125], v[152:155], v[176:179], v[122:125]
	v_mfma_f32_16x16x32_bf16 v[118:121], v[144:147], v[184:187], v[118:121]
	v_mfma_f32_16x16x32_bf16 v[114:117], v[152:155], v[184:187], v[114:117]
	v_mfma_f32_16x16x32_bf16 v[106:109], v[144:147], v[192:195], v[106:109]
	v_mfma_f32_16x16x32_bf16 v[98:101], v[152:155], v[192:195], v[98:101]
	v_mfma_f32_16x16x32_bf16 v[90:93], v[144:147], v[208:211], v[90:93]
	v_mfma_f32_16x16x32_bf16 v[82:85], v[152:155], v[208:211], v[82:85]
	s_setprio 0
	s_setprio 1
	v_mfma_f32_16x16x32_bf16 v[110:113], v[156:159], v[172:175], v[110:113]
	v_mfma_f32_16x16x32_bf16 v[102:105], v[164:167], v[172:175], v[102:105]
	v_mfma_f32_16x16x32_bf16 v[94:97], v[156:159], v[180:183], v[94:97]
	v_mfma_f32_16x16x32_bf16 v[86:89], v[164:167], v[180:183], v[86:89]
	v_mfma_f32_16x16x32_bf16 v[78:81], v[156:159], v[188:191], v[78:81]
	v_mfma_f32_16x16x32_bf16 v[74:77], v[164:167], v[188:191], v[74:77]
	v_mfma_f32_16x16x32_bf16 v[70:73], v[156:159], v[196:199], v[70:73]
	v_mfma_f32_16x16x32_bf16 v[66:69], v[164:167], v[196:199], v[66:69]
	v_mfma_f32_16x16x32_bf16 v[110:113], v[160:163], v[176:179], v[110:113]
	v_mfma_f32_16x16x32_bf16 v[102:105], v[168:171], v[176:179], v[102:105]
	v_mfma_f32_16x16x32_bf16 v[94:97], v[160:163], v[184:187], v[94:97]
	v_mfma_f32_16x16x32_bf16 v[86:89], v[168:171], v[184:187], v[86:89]
	v_mfma_f32_16x16x32_bf16 v[78:81], v[160:163], v[192:195], v[78:81]
	v_mfma_f32_16x16x32_bf16 v[74:77], v[168:171], v[192:195], v[74:77]
	v_mfma_f32_16x16x32_bf16 v[70:73], v[160:163], v[208:211], v[70:73]
	v_mfma_f32_16x16x32_bf16 v[66:69], v[168:171], v[208:211], v[66:69]
	s_barrier
	s_setprio 0
	s_add_i32 s0, s2, s24
	v_lshl_add_u64 v[200:201], v[200:201], 0, s[80:81]
	s_mov_b32 m0, s0
	ds_read_b128 v[172:175], v139 offset:49152
	ds_read_b128 v[176:179], v139 offset:50176
	ds_read_b128 v[180:183], v139 offset:51200
	ds_read_b128 v[184:187], v139 offset:52224
	ds_read_b128 v[188:191], v139 offset:53248
	ds_read_b128 v[192:195], v139 offset:54272
	ds_read_b128 v[196:199], v139 offset:55296
	ds_read_b128 v[208:211], v139 offset:56320
	global_load_lds_dwordx4 v[200:201], off
	s_add_i32 m0, s0, 0x2000
	s_add_u32 s0, s18, 0x160080
	v_lshl_add_u64 v[200:201], v[204:205], 0, s[80:81]
	s_addc_u32 s1, s19, 0
	s_add_i32 s2, s3, s24
	global_load_lds_dwordx4 v[200:201], off
	v_lshl_add_u64 v[200:201], s[0:1], 0, v[202:203]
	s_mov_b32 m0, s2
	s_nop 0
	global_load_lds_dwordx4 v[200:201], off
	v_lshl_add_u64 v[200:201], s[0:1], 0, v[130:131]
	s_add_i32 m0, s2, 0x2000
	s_nop 0
	global_load_lds_dwordx4 v[200:201], off
	v_lshl_add_u64 v[200:201], v[206:207], 0, s[80:81]
	s_mov_b32 m0, s29
	s_nop 0
	global_load_lds_dwordx4 v[200:201], off
	v_lshl_add_u64 v[200:201], v[212:213], 0, s[80:81]
	s_mov_b32 m0, s30
	s_nop 0
	global_load_lds_dwordx4 v[200:201], off
	s_waitcnt vmcnt(8)
	s_waitcnt lgkmcnt(0)
	s_setprio 1
	s_barrier
	v_mfma_f32_16x16x32_bf16 v[62:65], v[140:143], v[172:175], v[62:65]
	v_mfma_f32_16x16x32_bf16 v[58:61], v[148:151], v[172:175], v[58:61]
	v_mfma_f32_16x16x32_bf16 v[54:57], v[140:143], v[180:183], v[54:57]
	v_mfma_f32_16x16x32_bf16 v[50:53], v[148:151], v[180:183], v[50:53]
	v_mfma_f32_16x16x32_bf16 v[38:41], v[140:143], v[188:191], v[38:41]
	v_mfma_f32_16x16x32_bf16 v[34:37], v[148:151], v[188:191], v[34:37]
	v_mfma_f32_16x16x32_bf16 v[22:25], v[140:143], v[196:199], v[22:25]
	v_mfma_f32_16x16x32_bf16 v[18:21], v[148:151], v[196:199], v[18:21]
	v_mfma_f32_16x16x32_bf16 v[62:65], v[144:147], v[176:179], v[62:65]
	v_mfma_f32_16x16x32_bf16 v[58:61], v[152:155], v[176:179], v[58:61]
	v_mfma_f32_16x16x32_bf16 v[54:57], v[144:147], v[184:187], v[54:57]
	v_mfma_f32_16x16x32_bf16 v[50:53], v[152:155], v[184:187], v[50:53]
	v_mfma_f32_16x16x32_bf16 v[38:41], v[144:147], v[192:195], v[38:41]
	v_mfma_f32_16x16x32_bf16 v[34:37], v[152:155], v[192:195], v[34:37]
	v_mfma_f32_16x16x32_bf16 v[22:25], v[144:147], v[208:211], v[22:25]
	v_mfma_f32_16x16x32_bf16 v[18:21], v[152:155], v[208:211], v[18:21]
	s_setprio 0
	s_setprio 1
	v_mfma_f32_16x16x32_bf16 v[46:49], v[156:159], v[172:175], v[46:49]
	v_mfma_f32_16x16x32_bf16 v[42:45], v[164:167], v[172:175], v[42:45]
	v_mfma_f32_16x16x32_bf16 v[30:33], v[156:159], v[180:183], v[30:33]
	v_mfma_f32_16x16x32_bf16 v[26:29], v[164:167], v[180:183], v[26:29]
	v_mfma_f32_16x16x32_bf16 v[14:17], v[156:159], v[188:191], v[14:17]
	v_mfma_f32_16x16x32_bf16 v[10:13], v[164:167], v[188:191], v[10:13]
	v_mfma_f32_16x16x32_bf16 v[6:9], v[156:159], v[196:199], v[6:9]
	v_mfma_f32_16x16x32_bf16 v[2:5], v[164:167], v[196:199], v[2:5]
	v_mfma_f32_16x16x32_bf16 v[46:49], v[160:163], v[176:179], v[46:49]
	v_mfma_f32_16x16x32_bf16 v[42:45], v[168:171], v[176:179], v[42:45]
	v_mfma_f32_16x16x32_bf16 v[30:33], v[160:163], v[184:187], v[30:33]
	v_mfma_f32_16x16x32_bf16 v[26:29], v[168:171], v[184:187], v[26:29]
	v_mfma_f32_16x16x32_bf16 v[14:17], v[160:163], v[192:195], v[14:17]
	v_mfma_f32_16x16x32_bf16 v[10:13], v[168:171], v[192:195], v[10:13]
	v_mfma_f32_16x16x32_bf16 v[6:9], v[160:163], v[208:211], v[6:9]
	v_mfma_f32_16x16x32_bf16 v[2:5], v[168:171], v[208:211], v[2:5]
	s_barrier
	s_setprio 0
	s_add_i32 s59, s59, 2
	s_add_u32 s49, s49, 0x100
	s_addc_u32 s58, s58, 0
	s_cmp_gt_u32 s59, 5
	s_mov_b64 s[2:3], s[4:5]
	s_cbranch_scc0 .LBB0_990
	s_and_b64 vcc, exec, s[10:11]
	s_cbranch_vccz .LBB0_993
	s_barrier

.LBB0_1115:
	s_add_u32 s0, s22, 0xfff80080
	s_addc_u32 s1, s23, -1
	s_add_i32 s33, 0, 0x10000
	s_cmp_eq_u32 s58, 28
	s_cselect_b32 s5, s17, s1
	s_cselect_b32 s4, s39, s0
	v_add_u32_e32 v143, s33, v145
	s_cselect_b32 s3, s15, s49
	s_cselect_b32 s2, s40, s41
	s_add_i32 s55, 0, 0x14000
	ds_read_b128 v[148:151], v143
	ds_read_b128 v[152:155], v143 offset:1024
	ds_read_b128 v[156:159], v143 offset:2048
	ds_read_b128 v[160:163], v143 offset:3072
	v_add_u32_e32 v143, s55, v145
	ds_read_b128 v[164:167], v143
	ds_read_b128 v[168:171], v143 offset:1024
	ds_read_b128 v[172:175], v143 offset:2048
	ds_read_b128 v[176:179], v143 offset:3072
	v_lshl_add_u64 v[200:201], s[22:23], 0, v[138:139]
	s_add_i32 m0, s27, 0xc000
	ds_read_b128 v[180:183], v147
	ds_read_b128 v[184:187], v147 offset:1024
	ds_read_b128 v[188:191], v147 offset:2048
	ds_read_b128 v[192:195], v147 offset:3072
	ds_read_b128 v[196:199], v147 offset:4096
	ds_read_b128 v[208:211], v147 offset:5120
	ds_read_b128 v[212:215], v147 offset:6144
	ds_read_b128 v[216:219], v147 offset:7168
	global_load_lds_dwordx4 v[200:201], off
	v_lshl_add_u64 v[200:201], s[22:23], 0, v[140:141]
	s_add_i32 m0, s27, 0xe000
	s_nop 0
	global_load_lds_dwordx4 v[200:201], off
	s_waitcnt vmcnt(8)
	s_waitcnt lgkmcnt(0)
	s_setprio 1
	s_barrier
	v_mfma_f32_16x16x32_bf16 v[126:129], v[148:151], v[180:183], v[126:129]
	v_mfma_f32_16x16x32_bf16 v[122:125], v[156:159], v[180:183], v[122:125]
	v_mfma_f32_16x16x32_bf16 v[110:113], v[148:151], v[188:191], v[110:113]
	v_mfma_f32_16x16x32_bf16 v[106:109], v[156:159], v[188:191], v[106:109]
	v_mfma_f32_16x16x32_bf16 v[94:97], v[148:151], v[196:199], v[94:97]
	v_mfma_f32_16x16x32_bf16 v[90:93], v[156:159], v[196:199], v[90:93]
	v_mfma_f32_16x16x32_bf16 v[78:81], v[148:151], v[212:215], v[78:81]
	v_mfma_f32_16x16x32_bf16 v[74:77], v[156:159], v[212:215], v[74:77]
	v_mfma_f32_16x16x32_bf16 v[126:129], v[152:155], v[184:187], v[126:129]
	v_mfma_f32_16x16x32_bf16 v[122:125], v[160:163], v[184:187], v[122:125]
	v_mfma_f32_16x16x32_bf16 v[110:113], v[152:155], v[192:195], v[110:113]
	v_mfma_f32_16x16x32_bf16 v[106:109], v[160:163], v[192:195], v[106:109]
	v_mfma_f32_16x16x32_bf16 v[94:97], v[152:155], v[208:211], v[94:97]
	v_mfma_f32_16x16x32_bf16 v[90:93], v[160:163], v[208:211], v[90:93]
	v_mfma_f32_16x16x32_bf16 v[78:81], v[152:155], v[216:219], v[78:81]
	v_mfma_f32_16x16x32_bf16 v[74:77], v[160:163], v[216:219], v[74:77]
	s_setprio 0
	s_setprio 1
	v_mfma_f32_16x16x32_bf16 v[118:121], v[164:167], v[180:183], v[118:121]
	v_mfma_f32_16x16x32_bf16 v[114:117], v[172:175], v[180:183], v[114:117]
	v_mfma_f32_16x16x32_bf16 v[102:105], v[164:167], v[188:191], v[102:105]
	v_mfma_f32_16x16x32_bf16 v[98:101], v[172:175], v[188:191], v[98:101]
	v_mfma_f32_16x16x32_bf16 v[86:89], v[164:167], v[196:199], v[86:89]
	v_mfma_f32_16x16x32_bf16 v[82:85], v[172:175], v[196:199], v[82:85]
	v_mfma_f32_16x16x32_bf16 v[70:73], v[164:167], v[212:215], v[70:73]
	v_mfma_f32_16x16x32_bf16 v[66:69], v[172:175], v[212:215], v[66:69]
	v_mfma_f32_16x16x32_bf16 v[118:121], v[168:171], v[184:187], v[118:121]
	v_mfma_f32_16x16x32_bf16 v[114:117], v[176:179], v[184:187], v[114:117]
	v_mfma_f32_16x16x32_bf16 v[102:105], v[168:171], v[192:195], v[102:105]
	v_mfma_f32_16x16x32_bf16 v[98:101], v[176:179], v[192:195], v[98:101]
	v_mfma_f32_16x16x32_bf16 v[86:89], v[168:171], v[208:211], v[86:89]
	v_mfma_f32_16x16x32_bf16 v[82:85], v[176:179], v[208:211], v[82:85]
	v_mfma_f32_16x16x32_bf16 v[70:73], v[168:171], v[216:219], v[70:73]
	v_mfma_f32_16x16x32_bf16 v[66:69], v[176:179], v[216:219], v[66:69]
	s_barrier
	s_setprio 0
	s_add_i32 s0, s33, s26
	v_lshl_add_u64 v[200:201], s[2:3], 0, v[134:135]
	s_mov_b32 m0, s0
	ds_read_b128 v[180:183], v147 offset:16384
	ds_read_b128 v[184:187], v147 offset:17408
	ds_read_b128 v[188:191], v147 offset:18432
	ds_read_b128 v[192:195], v147 offset:19456
	ds_read_b128 v[196:199], v147 offset:20480
	ds_read_b128 v[208:211], v147 offset:21504
	ds_read_b128 v[212:215], v147 offset:22528
	ds_read_b128 v[216:219], v147 offset:23552
	global_load_lds_dwordx4 v[200:201], off
	s_add_i32 m0, s0, 0x2000
	s_add_u32 s0, s2, 0x80000
	v_lshl_add_u64 v[204:205], s[2:3], 0, v[130:131]
	s_addc_u32 s1, s3, 0
	s_add_i32 s33, s55, s26
	global_load_lds_dwordx4 v[204:205], off
	v_lshl_add_u64 v[206:207], s[0:1], 0, v[134:135]
	s_mov_b32 m0, s33
	v_lshl_add_u64 v[220:221], s[4:5], 0, v[132:133]
	global_load_lds_dwordx4 v[206:207], off
	v_lshl_add_u64 v[206:207], s[0:1], 0, v[130:131]
	s_add_i32 m0, s33, 0x2000
	s_nop 0
	global_load_lds_dwordx4 v[206:207], off
	v_lshl_add_u64 v[206:207], s[4:5], 0, v[136:137]
	s_mov_b32 m0, s27
	s_nop 0
	global_load_lds_dwordx4 v[206:207], off
	s_mov_b32 m0, s28
	s_nop 0
	global_load_lds_dwordx4 v[220:221], off
	s_waitcnt vmcnt(8)
	s_waitcnt lgkmcnt(0)
	s_setprio 1
	s_barrier
	v_mfma_f32_16x16x32_bf16 v[62:65], v[148:151], v[180:183], v[62:65]
	v_mfma_f32_16x16x32_bf16 v[58:61], v[156:159], v[180:183], v[58:61]
	v_mfma_f32_16x16x32_bf16 v[46:49], v[148:151], v[188:191], v[46:49]
	v_mfma_f32_16x16x32_bf16 v[42:45], v[156:159], v[188:191], v[42:45]
	v_mfma_f32_16x16x32_bf16 v[30:33], v[148:151], v[196:199], v[30:33]
	v_mfma_f32_16x16x32_bf16 v[26:29], v[156:159], v[196:199], v[26:29]
	v_mfma_f32_16x16x32_bf16 v[14:17], v[148:151], v[212:215], v[14:17]
	v_mfma_f32_16x16x32_bf16 v[10:13], v[156:159], v[212:215], v[10:13]
	v_mfma_f32_16x16x32_bf16 v[62:65], v[152:155], v[184:187], v[62:65]
	v_mfma_f32_16x16x32_bf16 v[58:61], v[160:163], v[184:187], v[58:61]
	v_mfma_f32_16x16x32_bf16 v[46:49], v[152:155], v[192:195], v[46:49]
	v_mfma_f32_16x16x32_bf16 v[42:45], v[160:163], v[192:195], v[42:45]
	v_mfma_f32_16x16x32_bf16 v[30:33], v[152:155], v[208:211], v[30:33]
	v_mfma_f32_16x16x32_bf16 v[26:29], v[160:163], v[208:211], v[26:29]
	v_mfma_f32_16x16x32_bf16 v[14:17], v[152:155], v[216:219], v[14:17]
	v_mfma_f32_16x16x32_bf16 v[10:13], v[160:163], v[216:219], v[10:13]
	s_setprio 0
	s_setprio 1
	v_mfma_f32_16x16x32_bf16 v[54:57], v[164:167], v[180:183], v[54:57]
	v_mfma_f32_16x16x32_bf16 v[50:53], v[172:175], v[180:183], v[50:53]
	v_mfma_f32_16x16x32_bf16 v[38:41], v[164:167], v[188:191], v[38:41]
	v_mfma_f32_16x16x32_bf16 v[34:37], v[172:175], v[188:191], v[34:37]
	v_mfma_f32_16x16x32_bf16 v[22:25], v[164:167], v[196:199], v[22:25]
	v_mfma_f32_16x16x32_bf16 v[18:21], v[172:175], v[196:199], v[18:21]
	v_mfma_f32_16x16x32_bf16 v[6:9], v[164:167], v[212:215], v[6:9]
	v_mfma_f32_16x16x32_bf16 v[2:5], v[172:175], v[212:215], v[2:5]
	v_mfma_f32_16x16x32_bf16 v[54:57], v[168:171], v[184:187], v[54:57]
	v_mfma_f32_16x16x32_bf16 v[50:53], v[176:179], v[184:187], v[50:53]
	v_mfma_f32_16x16x32_bf16 v[38:41], v[168:171], v[192:195], v[38:41]
	v_mfma_f32_16x16x32_bf16 v[34:37], v[176:179], v[192:195], v[34:37]
	v_mfma_f32_16x16x32_bf16 v[22:25], v[168:171], v[208:211], v[22:25]
	v_mfma_f32_16x16x32_bf16 v[18:21], v[176:179], v[208:211], v[18:21]
	v_mfma_f32_16x16x32_bf16 v[6:9], v[168:171], v[216:219], v[6:9]
	v_mfma_f32_16x16x32_bf16 v[2:5], v[176:179], v[216:219], v[2:5]
	s_barrier
	s_setprio 0
	s_add_i32 s33, 0, 0x18000
	v_add_u32_e32 v143, s33, v145
	s_add_i32 s55, 0, 0x1c000
	ds_read_b128 v[148:151], v143
	ds_read_b128 v[152:155], v143 offset:1024
	ds_read_b128 v[156:159], v143 offset:2048
	ds_read_b128 v[160:163], v143 offset:3072
	v_add_u32_e32 v143, s55, v145
	ds_read_b128 v[164:167], v143
	ds_read_b128 v[168:171], v143 offset:1024
	ds_read_b128 v[172:175], v143 offset:2048
	ds_read_b128 v[176:179], v143 offset:3072
	s_add_u32 s0, s4, 0x80000
	s_addc_u32 s1, s5, 0
	s_mov_b32 m0, s29
	v_lshl_add_u64 v[222:223], s[0:1], 0, v[136:137]
	ds_read_b128 v[180:183], v147 offset:32768
	ds_read_b128 v[184:187], v147 offset:33792
	ds_read_b128 v[188:191], v147 offset:34816
	ds_read_b128 v[192:195], v147 offset:35840
	ds_read_b128 v[196:199], v147 offset:36864
	ds_read_b128 v[208:211], v147 offset:37888
	ds_read_b128 v[212:215], v147 offset:38912
	ds_read_b128 v[216:219], v147 offset:39936
	global_load_lds_dwordx4 v[222:223], off
	v_lshl_add_u64 v[222:223], s[0:1], 0, v[132:133]
	s_mov_b32 m0, s30
	s_nop 0
	global_load_lds_dwordx4 v[222:223], off
	s_waitcnt vmcnt(8)
	s_waitcnt lgkmcnt(0)
	s_setprio 1
	s_barrier
	v_mfma_f32_16x16x32_bf16 v[126:129], v[148:151], v[180:183], v[126:129]
	v_mfma_f32_16x16x32_bf16 v[122:125], v[156:159], v[180:183], v[122:125]
	v_mfma_f32_16x16x32_bf16 v[110:113], v[148:151], v[188:191], v[110:113]
	v_mfma_f32_16x16x32_bf16 v[106:109], v[156:159], v[188:191], v[106:109]
	v_mfma_f32_16x16x32_bf16 v[94:97], v[148:151], v[196:199], v[94:97]
	v_mfma_f32_16x16x32_bf16 v[90:93], v[156:159], v[196:199], v[90:93]
	v_mfma_f32_16x16x32_bf16 v[78:81], v[148:151], v[212:215], v[78:81]
	v_mfma_f32_16x16x32_bf16 v[74:77], v[156:159], v[212:215], v[74:77]
	v_mfma_f32_16x16x32_bf16 v[126:129], v[152:155], v[184:187], v[126:129]
	v_mfma_f32_16x16x32_bf16 v[122:125], v[160:163], v[184:187], v[122:125]
	v_mfma_f32_16x16x32_bf16 v[110:113], v[152:155], v[192:195], v[110:113]
	v_mfma_f32_16x16x32_bf16 v[106:109], v[160:163], v[192:195], v[106:109]
	v_mfma_f32_16x16x32_bf16 v[94:97], v[152:155], v[208:211], v[94:97]
	v_mfma_f32_16x16x32_bf16 v[90:93], v[160:163], v[208:211], v[90:93]
	v_mfma_f32_16x16x32_bf16 v[78:81], v[152:155], v[216:219], v[78:81]
	v_mfma_f32_16x16x32_bf16 v[74:77], v[160:163], v[216:219], v[74:77]
	s_setprio 0
	s_setprio 1
	v_mfma_f32_16x16x32_bf16 v[118:121], v[164:167], v[180:183], v[118:121]
	v_mfma_f32_16x16x32_bf16 v[114:117], v[172:175], v[180:183], v[114:117]
	v_mfma_f32_16x16x32_bf16 v[102:105], v[164:167], v[188:191], v[102:105]
	v_mfma_f32_16x16x32_bf16 v[98:101], v[172:175], v[188:191], v[98:101]
	v_mfma_f32_16x16x32_bf16 v[86:89], v[164:167], v[196:199], v[86:89]
	v_mfma_f32_16x16x32_bf16 v[82:85], v[172:175], v[196:199], v[82:85]
	v_mfma_f32_16x16x32_bf16 v[70:73], v[164:167], v[212:215], v[70:73]
	v_mfma_f32_16x16x32_bf16 v[66:69], v[172:175], v[212:215], v[66:69]
	v_mfma_f32_16x16x32_bf16 v[118:121], v[168:171], v[184:187], v[118:121]
	v_mfma_f32_16x16x32_bf16 v[114:117], v[176:179], v[184:187], v[114:117]
	v_mfma_f32_16x16x32_bf16 v[102:105], v[168:171], v[192:195], v[102:105]
	v_mfma_f32_16x16x32_bf16 v[98:101], v[176:179], v[192:195], v[98:101]
	v_mfma_f32_16x16x32_bf16 v[86:89], v[168:171], v[208:211], v[86:89]
	v_mfma_f32_16x16x32_bf16 v[82:85], v[176:179], v[208:211], v[82:85]
	v_mfma_f32_16x16x32_bf16 v[70:73], v[168:171], v[216:219], v[70:73]
	v_mfma_f32_16x16x32_bf16 v[66:69], v[176:179], v[216:219], v[66:69]
	s_barrier
	s_setprio 0
	s_add_i32 s0, s33, s26
	v_lshl_add_u64 v[200:201], v[200:201], 0, s[80:81]
	s_mov_b32 m0, s0
	ds_read_b128 v[180:183], v147 offset:49152
	ds_read_b128 v[184:187], v147 offset:50176
	ds_read_b128 v[188:191], v147 offset:51200
	ds_read_b128 v[192:195], v147 offset:52224
	ds_read_b128 v[196:199], v147 offset:53248
	ds_read_b128 v[208:211], v147 offset:54272
	ds_read_b128 v[212:215], v147 offset:55296
	ds_read_b128 v[216:219], v147 offset:56320
	global_load_lds_dwordx4 v[200:201], off
	s_add_i32 m0, s0, 0x2000
	s_add_u32 s0, s2, 0x80080
	v_lshl_add_u64 v[200:201], v[204:205], 0, s[80:81]
	s_addc_u32 s1, s3, 0
	s_add_i32 s2, s55, s26
	global_load_lds_dwordx4 v[200:201], off
	v_lshl_add_u64 v[200:201], s[0:1], 0, v[134:135]
	s_mov_b32 m0, s2
	s_nop 0
	global_load_lds_dwordx4 v[200:201], off
	v_lshl_add_u64 v[200:201], s[0:1], 0, v[130:131]
	s_add_i32 m0, s2, 0x2000
	s_nop 0
	global_load_lds_dwordx4 v[200:201], off
	v_lshl_add_u64 v[200:201], v[206:207], 0, s[80:81]
	s_mov_b32 m0, s34
	s_nop 0
	global_load_lds_dwordx4 v[200:201], off
	v_lshl_add_u64 v[200:201], v[220:221], 0, s[80:81]
	s_mov_b32 m0, s35
	s_nop 0
	global_load_lds_dwordx4 v[200:201], off
	s_waitcnt vmcnt(8)
	s_waitcnt lgkmcnt(0)
	s_setprio 1
	s_barrier
	v_mfma_f32_16x16x32_bf16 v[62:65], v[148:151], v[180:183], v[62:65]
	v_mfma_f32_16x16x32_bf16 v[58:61], v[156:159], v[180:183], v[58:61]
	v_mfma_f32_16x16x32_bf16 v[46:49], v[148:151], v[188:191], v[46:49]
	v_mfma_f32_16x16x32_bf16 v[42:45], v[156:159], v[188:191], v[42:45]
	v_mfma_f32_16x16x32_bf16 v[30:33], v[148:151], v[196:199], v[30:33]
	v_mfma_f32_16x16x32_bf16 v[26:29], v[156:159], v[196:199], v[26:29]
	v_mfma_f32_16x16x32_bf16 v[14:17], v[148:151], v[212:215], v[14:17]
	v_mfma_f32_16x16x32_bf16 v[10:13], v[156:159], v[212:215], v[10:13]
	v_mfma_f32_16x16x32_bf16 v[62:65], v[152:155], v[184:187], v[62:65]
	v_mfma_f32_16x16x32_bf16 v[58:61], v[160:163], v[184:187], v[58:61]
	v_mfma_f32_16x16x32_bf16 v[46:49], v[152:155], v[192:195], v[46:49]
	v_mfma_f32_16x16x32_bf16 v[42:45], v[160:163], v[192:195], v[42:45]
	v_mfma_f32_16x16x32_bf16 v[30:33], v[152:155], v[208:211], v[30:33]
	v_mfma_f32_16x16x32_bf16 v[26:29], v[160:163], v[208:211], v[26:29]
	v_mfma_f32_16x16x32_bf16 v[14:17], v[152:155], v[216:219], v[14:17]
	v_mfma_f32_16x16x32_bf16 v[10:13], v[160:163], v[216:219], v[10:13]
	s_setprio 0
	s_setprio 1
	v_mfma_f32_16x16x32_bf16 v[54:57], v[164:167], v[180:183], v[54:57]
	v_mfma_f32_16x16x32_bf16 v[50:53], v[172:175], v[180:183], v[50:53]
	v_mfma_f32_16x16x32_bf16 v[38:41], v[164:167], v[188:191], v[38:41]
	v_mfma_f32_16x16x32_bf16 v[34:37], v[172:175], v[188:191], v[34:37]
	v_mfma_f32_16x16x32_bf16 v[22:25], v[164:167], v[196:199], v[22:25]
	v_mfma_f32_16x16x32_bf16 v[18:21], v[172:175], v[196:199], v[18:21]
	v_mfma_f32_16x16x32_bf16 v[6:9], v[164:167], v[212:215], v[6:9]
	v_mfma_f32_16x16x32_bf16 v[2:5], v[172:175], v[212:215], v[2:5]
	v_mfma_f32_16x16x32_bf16 v[54:57], v[168:171], v[184:187], v[54:57]
	v_mfma_f32_16x16x32_bf16 v[50:53], v[176:179], v[184:187], v[50:53]
	v_mfma_f32_16x16x32_bf16 v[38:41], v[168:171], v[192:195], v[38:41]
	v_mfma_f32_16x16x32_bf16 v[34:37], v[176:179], v[192:195], v[34:37]
	v_mfma_f32_16x16x32_bf16 v[22:25], v[168:171], v[208:211], v[22:25]
	v_mfma_f32_16x16x32_bf16 v[18:21], v[176:179], v[208:211], v[18:21]
	v_mfma_f32_16x16x32_bf16 v[6:9], v[168:171], v[216:219], v[6:9]
	v_mfma_f32_16x16x32_bf16 v[2:5], v[176:179], v[216:219], v[2:5]
	s_barrier
	s_setprio 0
	s_add_i32 s58, s58, 2
	s_add_u32 s22, s22, 0x100
	s_addc_u32 s23, s23, 0
	s_add_u32 s41, s41, 0x100
	s_addc_u32 s49, s49, 0
	s_cmp_gt_u32 s58, 29
	s_cbranch_scc0 .LBB0_1115
	s_and_b64 vcc, exec, s[10:11]
	s_cbranch_vccz .LBB0_1118
	s_barrier

.LBB0_1242:
	s_add_u32 s28, s18, s4
	s_addc_u32 s29, s19, s5
	s_add_u32 s24, s28, 0x100
	s_addc_u32 s25, s29, 0
	s_and_b64 s[0:1], s[2:3], exec
	s_cselect_b32 s25, s49, s25
	s_cselect_b32 s24, s58, s24
	s_add_u32 s0, s20, s4
	s_addc_u32 s1, s21, s5
	s_add_u32 s4, s0, 0x100
	s_addc_u32 s5, s1, 0
	s_add_i32 s55, 0, 0x10000
	s_and_b64 s[0:1], s[2:3], exec
	s_cselect_b32 s27, s59, s5
	s_cselect_b32 s26, s60, s4
	s_add_i32 s0, 0, 0x14000
	s_add_u32 s30, s28, 0x20080
	s_addc_u32 s31, s29, 0
	s_add_i32 s57, s55, s36
	s_add_i32 m0, s37, 0xc000
	s_add_i32 s1, s37, 0xe000
	s_add_i32 s63, s57, 0x2000
	v_add_u32_e32 v138, s55, v141
	s_add_u32 s28, s26, 0x10000
	ds_read_b128 v[144:147], v138
	ds_read_b128 v[148:151], v138 offset:1024
	ds_read_b128 v[152:155], v138 offset:2048
	ds_read_b128 v[156:159], v138 offset:3072
	v_add_u32_e32 v138, s0, v141
	s_addc_u32 s29, s27, 0
	s_add_i32 s33, s0, s36
	ds_read_b128 v[160:163], v138
	ds_read_b128 v[164:167], v138 offset:1024
	ds_read_b128 v[168:171], v138 offset:2048
	ds_read_b128 v[172:175], v138 offset:3072
	s_add_i32 s56, s33, 0x2000
	s_add_i32 vcc_lo, 0, 0x18000
	s_add_i32 vcc_hi, 0, 0x1c000
	s_add_u32 s4, s24, 0x20000
	s_addc_u32 s5, s25, 0
	s_add_i32 s61, vcc_lo, s36
	s_add_i32 s62, s61, 0x2000
	s_add_u32 s2, s26, 0x10080
	s_addc_u32 s3, s27, 0
	s_add_i32 s55, vcc_hi, s36
	s_add_i32 s0, s55, 0x2000
	v_lshl_add_u64 v[138:139], s[30:31], 0, v[134:135]
	ds_read_b128 v[176:179], v142
	ds_read_b128 v[180:183], v142 offset:1024
	ds_read_b128 v[184:187], v142 offset:2048
	ds_read_b128 v[188:191], v142 offset:3072
	ds_read_b128 v[192:195], v142 offset:4096
	ds_read_b128 v[196:199], v142 offset:5120
	ds_read_b128 v[208:211], v142 offset:6144
	ds_read_b128 v[212:215], v142 offset:7168
	global_load_lds_dwordx4 v[138:139], off
	v_lshl_add_u64 v[138:139], s[30:31], 0, v[132:133]
	s_mov_b32 m0, s1
	s_nop 0
	global_load_lds_dwordx4 v[138:139], off
	s_waitcnt vmcnt(8)
	s_waitcnt lgkmcnt(0)
	s_setprio 1
	s_barrier
	v_mfma_f32_16x16x32_bf16 v[126:129], v[144:147], v[176:179], v[126:129]
	v_mfma_f32_16x16x32_bf16 v[122:125], v[152:155], v[176:179], v[122:125]
	v_mfma_f32_16x16x32_bf16 v[118:121], v[144:147], v[184:187], v[118:121]
	v_mfma_f32_16x16x32_bf16 v[110:113], v[152:155], v[184:187], v[110:113]
	v_mfma_f32_16x16x32_bf16 v[102:105], v[144:147], v[192:195], v[102:105]
	v_mfma_f32_16x16x32_bf16 v[94:97], v[152:155], v[192:195], v[94:97]
	v_mfma_f32_16x16x32_bf16 v[86:89], v[144:147], v[208:211], v[86:89]
	v_mfma_f32_16x16x32_bf16 v[78:81], v[152:155], v[208:211], v[78:81]
	v_mfma_f32_16x16x32_bf16 v[126:129], v[148:151], v[180:183], v[126:129]
	v_mfma_f32_16x16x32_bf16 v[122:125], v[156:159], v[180:183], v[122:125]
	v_mfma_f32_16x16x32_bf16 v[118:121], v[148:151], v[188:191], v[118:121]
	v_mfma_f32_16x16x32_bf16 v[110:113], v[156:159], v[188:191], v[110:113]
	v_mfma_f32_16x16x32_bf16 v[102:105], v[148:151], v[196:199], v[102:105]
	v_mfma_f32_16x16x32_bf16 v[94:97], v[156:159], v[196:199], v[94:97]
	v_mfma_f32_16x16x32_bf16 v[86:89], v[148:151], v[212:215], v[86:89]
	v_mfma_f32_16x16x32_bf16 v[78:81], v[156:159], v[212:215], v[78:81]
	s_setprio 0
	s_setprio 1
	v_mfma_f32_16x16x32_bf16 v[114:117], v[160:163], v[176:179], v[114:117]
	v_mfma_f32_16x16x32_bf16 v[106:109], v[168:171], v[176:179], v[106:109]
	v_mfma_f32_16x16x32_bf16 v[98:101], v[160:163], v[184:187], v[98:101]
	v_mfma_f32_16x16x32_bf16 v[90:93], v[168:171], v[184:187], v[90:93]
	v_mfma_f32_16x16x32_bf16 v[82:85], v[160:163], v[192:195], v[82:85]
	v_mfma_f32_16x16x32_bf16 v[74:77], v[168:171], v[192:195], v[74:77]
	v_mfma_f32_16x16x32_bf16 v[70:73], v[160:163], v[208:211], v[70:73]
	v_mfma_f32_16x16x32_bf16 v[66:69], v[168:171], v[208:211], v[66:69]
	v_mfma_f32_16x16x32_bf16 v[114:117], v[164:167], v[180:183], v[114:117]
	v_mfma_f32_16x16x32_bf16 v[106:109], v[172:175], v[180:183], v[106:109]
	v_mfma_f32_16x16x32_bf16 v[98:101], v[164:167], v[188:191], v[98:101]
	v_mfma_f32_16x16x32_bf16 v[90:93], v[172:175], v[188:191], v[90:93]
	v_mfma_f32_16x16x32_bf16 v[82:85], v[164:167], v[196:199], v[82:85]
	v_mfma_f32_16x16x32_bf16 v[74:77], v[172:175], v[196:199], v[74:77]
	v_mfma_f32_16x16x32_bf16 v[70:73], v[164:167], v[212:215], v[70:73]
	v_mfma_f32_16x16x32_bf16 v[66:69], v[172:175], v[212:215], v[66:69]
	s_barrier
	s_setprio 0
	s_mov_b32 m0, s57
	v_lshl_add_u64 v[138:139], s[26:27], 0, v[202:203]
	ds_read_b128 v[176:179], v142 offset:16384
	ds_read_b128 v[180:183], v142 offset:17408
	ds_read_b128 v[184:187], v142 offset:18432
	ds_read_b128 v[188:191], v142 offset:19456
	ds_read_b128 v[192:195], v142 offset:20480
	ds_read_b128 v[196:199], v142 offset:21504
	ds_read_b128 v[208:211], v142 offset:22528
	ds_read_b128 v[212:215], v142 offset:23552
	global_load_lds_dwordx4 v[138:139], off
	v_lshl_add_u64 v[200:201], s[26:27], 0, v[130:131]
	s_mov_b32 m0, s63
	v_lshl_add_u64 v[204:205], s[28:29], 0, v[202:203]
	global_load_lds_dwordx4 v[200:201], off
	s_mov_b32 m0, s33
	v_lshl_add_u64 v[206:207], s[24:25], 0, v[132:133]
	global_load_lds_dwordx4 v[204:205], off
	v_lshl_add_u64 v[204:205], s[28:29], 0, v[130:131]
	s_mov_b32 m0, s56
	s_nop 0
	global_load_lds_dwordx4 v[204:205], off
	v_lshl_add_u64 v[204:205], s[24:25], 0, v[134:135]
	s_mov_b32 m0, s37
	s_nop 0
	global_load_lds_dwordx4 v[204:205], off
	s_mov_b32 m0, s38
	s_nop 0
	global_load_lds_dwordx4 v[206:207], off
	s_waitcnt vmcnt(8)
	s_waitcnt lgkmcnt(0)
	s_setprio 1
	s_barrier
	v_mfma_f32_16x16x32_bf16 v[62:65], v[144:147], v[176:179], v[62:65]
	v_mfma_f32_16x16x32_bf16 v[58:61], v[152:155], v[176:179], v[58:61]
	v_mfma_f32_16x16x32_bf16 v[54:57], v[144:147], v[184:187], v[54:57]
	v_mfma_f32_16x16x32_bf16 v[46:49], v[152:155], v[184:187], v[46:49]
	v_mfma_f32_16x16x32_bf16 v[38:41], v[144:147], v[192:195], v[38:41]
	v_mfma_f32_16x16x32_bf16 v[30:33], v[152:155], v[192:195], v[30:33]
	v_mfma_f32_16x16x32_bf16 v[22:25], v[144:147], v[208:211], v[22:25]
	v_mfma_f32_16x16x32_bf16 v[14:17], v[152:155], v[208:211], v[14:17]
	v_mfma_f32_16x16x32_bf16 v[62:65], v[148:151], v[180:183], v[62:65]
	v_mfma_f32_16x16x32_bf16 v[58:61], v[156:159], v[180:183], v[58:61]
	v_mfma_f32_16x16x32_bf16 v[54:57], v[148:151], v[188:191], v[54:57]
	v_mfma_f32_16x16x32_bf16 v[46:49], v[156:159], v[188:191], v[46:49]
	v_mfma_f32_16x16x32_bf16 v[38:41], v[148:151], v[196:199], v[38:41]
	v_mfma_f32_16x16x32_bf16 v[30:33], v[156:159], v[196:199], v[30:33]
	v_mfma_f32_16x16x32_bf16 v[22:25], v[148:151], v[212:215], v[22:25]
	v_mfma_f32_16x16x32_bf16 v[14:17], v[156:159], v[212:215], v[14:17]
	s_setprio 0
	s_setprio 1
	v_mfma_f32_16x16x32_bf16 v[50:53], v[160:163], v[176:179], v[50:53]
	v_mfma_f32_16x16x32_bf16 v[42:45], v[168:171], v[176:179], v[42:45]
	v_mfma_f32_16x16x32_bf16 v[34:37], v[160:163], v[184:187], v[34:37]
	v_mfma_f32_16x16x32_bf16 v[26:29], v[168:171], v[184:187], v[26:29]
	v_mfma_f32_16x16x32_bf16 v[18:21], v[160:163], v[192:195], v[18:21]
	v_mfma_f32_16x16x32_bf16 v[10:13], v[168:171], v[192:195], v[10:13]
	v_mfma_f32_16x16x32_bf16 v[6:9], v[160:163], v[208:211], v[6:9]
	v_mfma_f32_16x16x32_bf16 v[2:5], v[168:171], v[208:211], v[2:5]
	v_mfma_f32_16x16x32_bf16 v[50:53], v[164:167], v[180:183], v[50:53]
	v_mfma_f32_16x16x32_bf16 v[42:45], v[172:175], v[180:183], v[42:45]
	v_mfma_f32_16x16x32_bf16 v[34:37], v[164:167], v[188:191], v[34:37]
	v_mfma_f32_16x16x32_bf16 v[26:29], v[172:175], v[188:191], v[26:29]
	v_mfma_f32_16x16x32_bf16 v[18:21], v[164:167], v[196:199], v[18:21]
	v_mfma_f32_16x16x32_bf16 v[10:13], v[172:175], v[196:199], v[10:13]
	v_mfma_f32_16x16x32_bf16 v[6:9], v[164:167], v[212:215], v[6:9]
	v_mfma_f32_16x16x32_bf16 v[2:5], v[172:175], v[212:215], v[2:5]
	s_barrier
	s_setprio 0
	v_add_u32_e32 v143, vcc_lo, v141
	ds_read_b128 v[144:147], v143
	ds_read_b128 v[148:151], v143 offset:1024
	ds_read_b128 v[152:155], v143 offset:2048
	ds_read_b128 v[156:159], v143 offset:3072
	v_add_u32_e32 v143, vcc_hi, v141
	ds_read_b128 v[160:163], v143
	ds_read_b128 v[164:167], v143 offset:1024
	ds_read_b128 v[168:171], v143 offset:2048
	ds_read_b128 v[172:175], v143 offset:3072
	s_mov_b32 m0, s39
	v_lshl_add_u64 v[216:217], s[4:5], 0, v[134:135]
	ds_read_b128 v[176:179], v142 offset:32768
	ds_read_b128 v[180:183], v142 offset:33792
	ds_read_b128 v[184:187], v142 offset:34816
	ds_read_b128 v[188:191], v142 offset:35840
	ds_read_b128 v[192:195], v142 offset:36864
	ds_read_b128 v[196:199], v142 offset:37888
	ds_read_b128 v[208:211], v142 offset:38912
	ds_read_b128 v[212:215], v142 offset:39936
	global_load_lds_dwordx4 v[216:217], off
	v_lshl_add_u64 v[216:217], s[4:5], 0, v[132:133]
	s_mov_b32 m0, s40
	s_nop 0
	global_load_lds_dwordx4 v[216:217], off
	s_waitcnt vmcnt(8)
	s_waitcnt lgkmcnt(0)
	s_setprio 1
	s_barrier
	v_mfma_f32_16x16x32_bf16 v[126:129], v[144:147], v[176:179], v[126:129]
	v_mfma_f32_16x16x32_bf16 v[122:125], v[152:155], v[176:179], v[122:125]
	v_mfma_f32_16x16x32_bf16 v[118:121], v[144:147], v[184:187], v[118:121]
	v_mfma_f32_16x16x32_bf16 v[110:113], v[152:155], v[184:187], v[110:113]
	v_mfma_f32_16x16x32_bf16 v[102:105], v[144:147], v[192:195], v[102:105]
	v_mfma_f32_16x16x32_bf16 v[94:97], v[152:155], v[192:195], v[94:97]
	v_mfma_f32_16x16x32_bf16 v[86:89], v[144:147], v[208:211], v[86:89]
	v_mfma_f32_16x16x32_bf16 v[78:81], v[152:155], v[208:211], v[78:81]
	v_mfma_f32_16x16x32_bf16 v[126:129], v[148:151], v[180:183], v[126:129]
	v_mfma_f32_16x16x32_bf16 v[122:125], v[156:159], v[180:183], v[122:125]
	v_mfma_f32_16x16x32_bf16 v[118:121], v[148:151], v[188:191], v[118:121]
	v_mfma_f32_16x16x32_bf16 v[110:113], v[156:159], v[188:191], v[110:113]
	v_mfma_f32_16x16x32_bf16 v[102:105], v[148:151], v[196:199], v[102:105]
	v_mfma_f32_16x16x32_bf16 v[94:97], v[156:159], v[196:199], v[94:97]
	v_mfma_f32_16x16x32_bf16 v[86:89], v[148:151], v[212:215], v[86:89]
	v_mfma_f32_16x16x32_bf16 v[78:81], v[156:159], v[212:215], v[78:81]
	s_setprio 0
	s_setprio 1
	v_mfma_f32_16x16x32_bf16 v[114:117], v[160:163], v[176:179], v[114:117]
	v_mfma_f32_16x16x32_bf16 v[106:109], v[168:171], v[176:179], v[106:109]
	v_mfma_f32_16x16x32_bf16 v[98:101], v[160:163], v[184:187], v[98:101]
	v_mfma_f32_16x16x32_bf16 v[90:93], v[168:171], v[184:187], v[90:93]
	v_mfma_f32_16x16x32_bf16 v[82:85], v[160:163], v[192:195], v[82:85]
	v_mfma_f32_16x16x32_bf16 v[74:77], v[168:171], v[192:195], v[74:77]
	v_mfma_f32_16x16x32_bf16 v[70:73], v[160:163], v[208:211], v[70:73]
	v_mfma_f32_16x16x32_bf16 v[66:69], v[168:171], v[208:211], v[66:69]
	v_mfma_f32_16x16x32_bf16 v[114:117], v[164:167], v[180:183], v[114:117]
	v_mfma_f32_16x16x32_bf16 v[106:109], v[172:175], v[180:183], v[106:109]
	v_mfma_f32_16x16x32_bf16 v[98:101], v[164:167], v[188:191], v[98:101]
	v_mfma_f32_16x16x32_bf16 v[90:93], v[172:175], v[188:191], v[90:93]
	v_mfma_f32_16x16x32_bf16 v[82:85], v[164:167], v[196:199], v[82:85]
	v_mfma_f32_16x16x32_bf16 v[74:77], v[172:175], v[196:199], v[74:77]
	v_mfma_f32_16x16x32_bf16 v[70:73], v[164:167], v[212:215], v[70:73]
	v_mfma_f32_16x16x32_bf16 v[66:69], v[172:175], v[212:215], v[66:69]
	s_barrier
	s_setprio 0
	s_mov_b32 m0, s61
	v_lshl_add_u64 v[138:139], v[138:139], 0, s[80:81]
	ds_read_b128 v[176:179], v142 offset:49152
	ds_read_b128 v[180:183], v142 offset:50176
	ds_read_b128 v[184:187], v142 offset:51200
	ds_read_b128 v[188:191], v142 offset:52224
	ds_read_b128 v[192:195], v142 offset:53248
	ds_read_b128 v[196:199], v142 offset:54272
	ds_read_b128 v[208:211], v142 offset:55296
	ds_read_b128 v[212:215], v142 offset:56320
	global_load_lds_dwordx4 v[138:139], off
	v_lshl_add_u64 v[138:139], v[200:201], 0, s[80:81]
	s_mov_b32 m0, s62
	s_nop 0
	global_load_lds_dwordx4 v[138:139], off
	v_lshl_add_u64 v[138:139], s[2:3], 0, v[202:203]
	s_mov_b32 m0, s55
	s_nop 0
	global_load_lds_dwordx4 v[138:139], off
	v_lshl_add_u64 v[138:139], s[2:3], 0, v[130:131]
	s_mov_b32 m0, s0
	s_nop 0
	global_load_lds_dwordx4 v[138:139], off
	v_lshl_add_u64 v[138:139], v[204:205], 0, s[80:81]
	s_mov_b32 m0, s41
	s_nop 0
	global_load_lds_dwordx4 v[138:139], off
	v_lshl_add_u64 v[138:139], v[206:207], 0, s[80:81]
	s_mov_b32 m0, s86
	s_nop 0
	global_load_lds_dwordx4 v[138:139], off
	s_waitcnt vmcnt(8)
	s_waitcnt lgkmcnt(0)
	s_setprio 1
	s_barrier
	v_mfma_f32_16x16x32_bf16 v[62:65], v[144:147], v[176:179], v[62:65]
	v_mfma_f32_16x16x32_bf16 v[58:61], v[152:155], v[176:179], v[58:61]
	v_mfma_f32_16x16x32_bf16 v[54:57], v[144:147], v[184:187], v[54:57]
	v_mfma_f32_16x16x32_bf16 v[46:49], v[152:155], v[184:187], v[46:49]
	v_mfma_f32_16x16x32_bf16 v[38:41], v[144:147], v[192:195], v[38:41]
	v_mfma_f32_16x16x32_bf16 v[30:33], v[152:155], v[192:195], v[30:33]
	v_mfma_f32_16x16x32_bf16 v[22:25], v[144:147], v[208:211], v[22:25]
	v_mfma_f32_16x16x32_bf16 v[14:17], v[152:155], v[208:211], v[14:17]
	v_mfma_f32_16x16x32_bf16 v[62:65], v[148:151], v[180:183], v[62:65]
	v_mfma_f32_16x16x32_bf16 v[58:61], v[156:159], v[180:183], v[58:61]
	v_mfma_f32_16x16x32_bf16 v[54:57], v[148:151], v[188:191], v[54:57]
	v_mfma_f32_16x16x32_bf16 v[46:49], v[156:159], v[188:191], v[46:49]
	v_mfma_f32_16x16x32_bf16 v[38:41], v[148:151], v[196:199], v[38:41]
	v_mfma_f32_16x16x32_bf16 v[30:33], v[156:159], v[196:199], v[30:33]
	v_mfma_f32_16x16x32_bf16 v[22:25], v[148:151], v[212:215], v[22:25]
	v_mfma_f32_16x16x32_bf16 v[14:17], v[156:159], v[212:215], v[14:17]
	s_setprio 0
	s_setprio 1
	v_mfma_f32_16x16x32_bf16 v[50:53], v[160:163], v[176:179], v[50:53]
	v_mfma_f32_16x16x32_bf16 v[42:45], v[168:171], v[176:179], v[42:45]
	v_mfma_f32_16x16x32_bf16 v[34:37], v[160:163], v[184:187], v[34:37]
	v_mfma_f32_16x16x32_bf16 v[26:29], v[168:171], v[184:187], v[26:29]
	v_mfma_f32_16x16x32_bf16 v[18:21], v[160:163], v[192:195], v[18:21]
	v_mfma_f32_16x16x32_bf16 v[10:13], v[168:171], v[192:195], v[10:13]
	v_mfma_f32_16x16x32_bf16 v[6:9], v[160:163], v[208:211], v[6:9]
	v_mfma_f32_16x16x32_bf16 v[2:5], v[168:171], v[208:211], v[2:5]
	v_mfma_f32_16x16x32_bf16 v[50:53], v[164:167], v[180:183], v[50:53]
	v_mfma_f32_16x16x32_bf16 v[42:45], v[172:175], v[180:183], v[42:45]
	v_mfma_f32_16x16x32_bf16 v[34:37], v[164:167], v[188:191], v[34:37]
	v_mfma_f32_16x16x32_bf16 v[26:29], v[172:175], v[188:191], v[26:29]
	v_mfma_f32_16x16x32_bf16 v[18:21], v[164:167], v[196:199], v[18:21]
	v_mfma_f32_16x16x32_bf16 v[10:13], v[172:175], v[196:199], v[10:13]
	v_mfma_f32_16x16x32_bf16 v[6:9], v[164:167], v[212:215], v[6:9]
	v_mfma_f32_16x16x32_bf16 v[2:5], v[172:175], v[212:215], v[2:5]
	s_barrier
	s_setprio 0
	s_andn2_b64 vcc, exec, s[22:23]
	s_mov_b64 s[2:3], -1
	s_mov_b64 s[22:23], 0
	s_mov_b64 s[4:5], 0x100
	s_cbranch_vccz .LBB0_1242
	s_and_b64 vcc, exec, s[10:11]
	s_cbranch_vccz .LBB0_1245
	s_barrier

.LBB0_1363:
	s_add_u32 s0, s20, 0xfffe0080
	s_addc_u32 s1, s21, -1
	s_add_i32 s33, 0, 0x10000
	s_cmp_eq_u32 s59, 4
	s_cselect_b32 s5, s38, s1
	s_cselect_b32 s4, s39, s0
	v_add_u32_e32 v147, s33, v143
	s_cselect_b32 s3, s40, s58
	s_cselect_b32 s2, s41, s49
	s_add_i32 s55, 0, 0x14000
	ds_read_b128 v[148:151], v147
	ds_read_b128 v[152:155], v147 offset:1024
	ds_read_b128 v[156:159], v147 offset:2048
	ds_read_b128 v[160:163], v147 offset:3072
	v_add_u32_e32 v147, s55, v143
	ds_read_b128 v[164:167], v147
	ds_read_b128 v[168:171], v147 offset:1024
	ds_read_b128 v[172:175], v147 offset:2048
	ds_read_b128 v[176:179], v147 offset:3072
	v_lshl_add_u64 v[200:201], s[20:21], 0, v[138:139]
	s_add_i32 m0, s25, 0xc000
	ds_read_b128 v[180:183], v146
	ds_read_b128 v[184:187], v146 offset:1024
	ds_read_b128 v[188:191], v146 offset:2048
	ds_read_b128 v[192:195], v146 offset:3072
	ds_read_b128 v[196:199], v146 offset:4096
	ds_read_b128 v[208:211], v146 offset:5120
	ds_read_b128 v[212:215], v146 offset:6144
	ds_read_b128 v[216:219], v146 offset:7168
	global_load_lds_dwordx4 v[200:201], off
	v_lshl_add_u64 v[200:201], s[20:21], 0, v[140:141]
	s_add_i32 m0, s25, 0xe000
	s_nop 0
	global_load_lds_dwordx4 v[200:201], off
	s_waitcnt vmcnt(8)
	s_waitcnt lgkmcnt(0)
	s_setprio 1
	s_barrier
	v_mfma_f32_16x16x32_bf16 v[126:129], v[148:151], v[180:183], v[126:129]
	v_mfma_f32_16x16x32_bf16 v[122:125], v[156:159], v[180:183], v[122:125]
	v_mfma_f32_16x16x32_bf16 v[110:113], v[148:151], v[188:191], v[110:113]
	v_mfma_f32_16x16x32_bf16 v[106:109], v[156:159], v[188:191], v[106:109]
	v_mfma_f32_16x16x32_bf16 v[94:97], v[148:151], v[196:199], v[94:97]
	v_mfma_f32_16x16x32_bf16 v[90:93], v[156:159], v[196:199], v[90:93]
	v_mfma_f32_16x16x32_bf16 v[78:81], v[148:151], v[212:215], v[78:81]
	v_mfma_f32_16x16x32_bf16 v[74:77], v[156:159], v[212:215], v[74:77]
	v_mfma_f32_16x16x32_bf16 v[126:129], v[152:155], v[184:187], v[126:129]
	v_mfma_f32_16x16x32_bf16 v[122:125], v[160:163], v[184:187], v[122:125]
	v_mfma_f32_16x16x32_bf16 v[110:113], v[152:155], v[192:195], v[110:113]
	v_mfma_f32_16x16x32_bf16 v[106:109], v[160:163], v[192:195], v[106:109]
	v_mfma_f32_16x16x32_bf16 v[94:97], v[152:155], v[208:211], v[94:97]
	v_mfma_f32_16x16x32_bf16 v[90:93], v[160:163], v[208:211], v[90:93]
	v_mfma_f32_16x16x32_bf16 v[78:81], v[152:155], v[216:219], v[78:81]
	v_mfma_f32_16x16x32_bf16 v[74:77], v[160:163], v[216:219], v[74:77]
	s_setprio 0
	s_setprio 1
	v_mfma_f32_16x16x32_bf16 v[118:121], v[164:167], v[180:183], v[118:121]
	v_mfma_f32_16x16x32_bf16 v[114:117], v[172:175], v[180:183], v[114:117]
	v_mfma_f32_16x16x32_bf16 v[102:105], v[164:167], v[188:191], v[102:105]
	v_mfma_f32_16x16x32_bf16 v[98:101], v[172:175], v[188:191], v[98:101]
	v_mfma_f32_16x16x32_bf16 v[86:89], v[164:167], v[196:199], v[86:89]
	v_mfma_f32_16x16x32_bf16 v[82:85], v[172:175], v[196:199], v[82:85]
	v_mfma_f32_16x16x32_bf16 v[70:73], v[164:167], v[212:215], v[70:73]
	v_mfma_f32_16x16x32_bf16 v[66:69], v[172:175], v[212:215], v[66:69]
	v_mfma_f32_16x16x32_bf16 v[118:121], v[168:171], v[184:187], v[118:121]
	v_mfma_f32_16x16x32_bf16 v[114:117], v[176:179], v[184:187], v[114:117]
	v_mfma_f32_16x16x32_bf16 v[102:105], v[168:171], v[192:195], v[102:105]
	v_mfma_f32_16x16x32_bf16 v[98:101], v[176:179], v[192:195], v[98:101]
	v_mfma_f32_16x16x32_bf16 v[86:89], v[168:171], v[208:211], v[86:89]
	v_mfma_f32_16x16x32_bf16 v[82:85], v[176:179], v[208:211], v[82:85]
	v_mfma_f32_16x16x32_bf16 v[70:73], v[168:171], v[216:219], v[70:73]
	v_mfma_f32_16x16x32_bf16 v[66:69], v[176:179], v[216:219], v[66:69]
	s_barrier
	s_setprio 0
	s_add_i32 s0, s33, s24
	v_lshl_add_u64 v[200:201], s[2:3], 0, v[134:135]
	s_mov_b32 m0, s0
	ds_read_b128 v[180:183], v146 offset:16384
	ds_read_b128 v[184:187], v146 offset:17408
	ds_read_b128 v[188:191], v146 offset:18432
	ds_read_b128 v[192:195], v146 offset:19456
	ds_read_b128 v[196:199], v146 offset:20480
	ds_read_b128 v[208:211], v146 offset:21504
	ds_read_b128 v[212:215], v146 offset:22528
	ds_read_b128 v[216:219], v146 offset:23552
	global_load_lds_dwordx4 v[200:201], off
	s_add_i32 m0, s0, 0x2000
	s_add_u32 s0, s2, 0x20000
	v_lshl_add_u64 v[204:205], s[2:3], 0, v[130:131]
	s_addc_u32 s1, s3, 0
	s_add_i32 s33, s55, s24
	global_load_lds_dwordx4 v[204:205], off
	v_lshl_add_u64 v[206:207], s[0:1], 0, v[134:135]
	s_mov_b32 m0, s33
	v_lshl_add_u64 v[220:221], s[4:5], 0, v[132:133]
	global_load_lds_dwordx4 v[206:207], off
	v_lshl_add_u64 v[206:207], s[0:1], 0, v[130:131]
	s_add_i32 m0, s33, 0x2000
	s_nop 0
	global_load_lds_dwordx4 v[206:207], off
	v_lshl_add_u64 v[206:207], s[4:5], 0, v[136:137]
	s_mov_b32 m0, s25
	s_nop 0
	global_load_lds_dwordx4 v[206:207], off
	s_mov_b32 m0, s26
	s_nop 0
	global_load_lds_dwordx4 v[220:221], off
	s_waitcnt vmcnt(8)
	s_waitcnt lgkmcnt(0)
	s_setprio 1
	s_barrier
	v_mfma_f32_16x16x32_bf16 v[62:65], v[148:151], v[180:183], v[62:65]
	v_mfma_f32_16x16x32_bf16 v[58:61], v[156:159], v[180:183], v[58:61]
	v_mfma_f32_16x16x32_bf16 v[46:49], v[148:151], v[188:191], v[46:49]
	v_mfma_f32_16x16x32_bf16 v[42:45], v[156:159], v[188:191], v[42:45]
	v_mfma_f32_16x16x32_bf16 v[30:33], v[148:151], v[196:199], v[30:33]
	v_mfma_f32_16x16x32_bf16 v[26:29], v[156:159], v[196:199], v[26:29]
	v_mfma_f32_16x16x32_bf16 v[14:17], v[148:151], v[212:215], v[14:17]
	v_mfma_f32_16x16x32_bf16 v[10:13], v[156:159], v[212:215], v[10:13]
	v_mfma_f32_16x16x32_bf16 v[62:65], v[152:155], v[184:187], v[62:65]
	v_mfma_f32_16x16x32_bf16 v[58:61], v[160:163], v[184:187], v[58:61]
	v_mfma_f32_16x16x32_bf16 v[46:49], v[152:155], v[192:195], v[46:49]
	v_mfma_f32_16x16x32_bf16 v[42:45], v[160:163], v[192:195], v[42:45]
	v_mfma_f32_16x16x32_bf16 v[30:33], v[152:155], v[208:211], v[30:33]
	v_mfma_f32_16x16x32_bf16 v[26:29], v[160:163], v[208:211], v[26:29]
	v_mfma_f32_16x16x32_bf16 v[14:17], v[152:155], v[216:219], v[14:17]
	v_mfma_f32_16x16x32_bf16 v[10:13], v[160:163], v[216:219], v[10:13]
	s_setprio 0
	s_setprio 1
	v_mfma_f32_16x16x32_bf16 v[54:57], v[164:167], v[180:183], v[54:57]
	v_mfma_f32_16x16x32_bf16 v[50:53], v[172:175], v[180:183], v[50:53]
	v_mfma_f32_16x16x32_bf16 v[38:41], v[164:167], v[188:191], v[38:41]
	v_mfma_f32_16x16x32_bf16 v[34:37], v[172:175], v[188:191], v[34:37]
	v_mfma_f32_16x16x32_bf16 v[22:25], v[164:167], v[196:199], v[22:25]
	v_mfma_f32_16x16x32_bf16 v[18:21], v[172:175], v[196:199], v[18:21]
	v_mfma_f32_16x16x32_bf16 v[6:9], v[164:167], v[212:215], v[6:9]
	v_mfma_f32_16x16x32_bf16 v[2:5], v[172:175], v[212:215], v[2:5]
	v_mfma_f32_16x16x32_bf16 v[54:57], v[168:171], v[184:187], v[54:57]
	v_mfma_f32_16x16x32_bf16 v[50:53], v[176:179], v[184:187], v[50:53]
	v_mfma_f32_16x16x32_bf16 v[38:41], v[168:171], v[192:195], v[38:41]
	v_mfma_f32_16x16x32_bf16 v[34:37], v[176:179], v[192:195], v[34:37]
	v_mfma_f32_16x16x32_bf16 v[22:25], v[168:171], v[208:211], v[22:25]
	v_mfma_f32_16x16x32_bf16 v[18:21], v[176:179], v[208:211], v[18:21]
	v_mfma_f32_16x16x32_bf16 v[6:9], v[168:171], v[216:219], v[6:9]
	v_mfma_f32_16x16x32_bf16 v[2:5], v[176:179], v[216:219], v[2:5]
	s_barrier
	s_setprio 0
	s_add_i32 s33, 0, 0x18000
	v_add_u32_e32 v147, s33, v143
	s_add_i32 s55, 0, 0x1c000
	ds_read_b128 v[148:151], v147
	ds_read_b128 v[152:155], v147 offset:1024
	ds_read_b128 v[156:159], v147 offset:2048
	ds_read_b128 v[160:163], v147 offset:3072
	v_add_u32_e32 v147, s55, v143
	ds_read_b128 v[164:167], v147
	ds_read_b128 v[168:171], v147 offset:1024
	ds_read_b128 v[172:175], v147 offset:2048
	ds_read_b128 v[176:179], v147 offset:3072
	s_add_u32 s0, s4, 0x20000
	s_addc_u32 s1, s5, 0
	s_mov_b32 m0, s27
	v_lshl_add_u64 v[222:223], s[0:1], 0, v[136:137]
	ds_read_b128 v[180:183], v146 offset:32768
	ds_read_b128 v[184:187], v146 offset:33792
	ds_read_b128 v[188:191], v146 offset:34816
	ds_read_b128 v[192:195], v146 offset:35840
	ds_read_b128 v[196:199], v146 offset:36864
	ds_read_b128 v[208:211], v146 offset:37888
	ds_read_b128 v[212:215], v146 offset:38912
	ds_read_b128 v[216:219], v146 offset:39936
	global_load_lds_dwordx4 v[222:223], off
	v_lshl_add_u64 v[222:223], s[0:1], 0, v[132:133]
	s_mov_b32 m0, s28
	s_nop 0
	global_load_lds_dwordx4 v[222:223], off
	s_waitcnt vmcnt(8)
	s_waitcnt lgkmcnt(0)
	s_setprio 1
	s_barrier
	v_mfma_f32_16x16x32_bf16 v[126:129], v[148:151], v[180:183], v[126:129]
	v_mfma_f32_16x16x32_bf16 v[122:125], v[156:159], v[180:183], v[122:125]
	v_mfma_f32_16x16x32_bf16 v[110:113], v[148:151], v[188:191], v[110:113]
	v_mfma_f32_16x16x32_bf16 v[106:109], v[156:159], v[188:191], v[106:109]
	v_mfma_f32_16x16x32_bf16 v[94:97], v[148:151], v[196:199], v[94:97]
	v_mfma_f32_16x16x32_bf16 v[90:93], v[156:159], v[196:199], v[90:93]
	v_mfma_f32_16x16x32_bf16 v[78:81], v[148:151], v[212:215], v[78:81]
	v_mfma_f32_16x16x32_bf16 v[74:77], v[156:159], v[212:215], v[74:77]
	v_mfma_f32_16x16x32_bf16 v[126:129], v[152:155], v[184:187], v[126:129]
	v_mfma_f32_16x16x32_bf16 v[122:125], v[160:163], v[184:187], v[122:125]
	v_mfma_f32_16x16x32_bf16 v[110:113], v[152:155], v[192:195], v[110:113]
	v_mfma_f32_16x16x32_bf16 v[106:109], v[160:163], v[192:195], v[106:109]
	v_mfma_f32_16x16x32_bf16 v[94:97], v[152:155], v[208:211], v[94:97]
	v_mfma_f32_16x16x32_bf16 v[90:93], v[160:163], v[208:211], v[90:93]
	v_mfma_f32_16x16x32_bf16 v[78:81], v[152:155], v[216:219], v[78:81]
	v_mfma_f32_16x16x32_bf16 v[74:77], v[160:163], v[216:219], v[74:77]
	s_setprio 0
	s_setprio 1
	v_mfma_f32_16x16x32_bf16 v[118:121], v[164:167], v[180:183], v[118:121]
	v_mfma_f32_16x16x32_bf16 v[114:117], v[172:175], v[180:183], v[114:117]
	v_mfma_f32_16x16x32_bf16 v[102:105], v[164:167], v[188:191], v[102:105]
	v_mfma_f32_16x16x32_bf16 v[98:101], v[172:175], v[188:191], v[98:101]
	v_mfma_f32_16x16x32_bf16 v[86:89], v[164:167], v[196:199], v[86:89]
	v_mfma_f32_16x16x32_bf16 v[82:85], v[172:175], v[196:199], v[82:85]
	v_mfma_f32_16x16x32_bf16 v[70:73], v[164:167], v[212:215], v[70:73]
	v_mfma_f32_16x16x32_bf16 v[66:69], v[172:175], v[212:215], v[66:69]
	v_mfma_f32_16x16x32_bf16 v[118:121], v[168:171], v[184:187], v[118:121]
	v_mfma_f32_16x16x32_bf16 v[114:117], v[176:179], v[184:187], v[114:117]
	v_mfma_f32_16x16x32_bf16 v[102:105], v[168:171], v[192:195], v[102:105]
	v_mfma_f32_16x16x32_bf16 v[98:101], v[176:179], v[192:195], v[98:101]
	v_mfma_f32_16x16x32_bf16 v[86:89], v[168:171], v[208:211], v[86:89]
	v_mfma_f32_16x16x32_bf16 v[82:85], v[176:179], v[208:211], v[82:85]
	v_mfma_f32_16x16x32_bf16 v[70:73], v[168:171], v[216:219], v[70:73]
	v_mfma_f32_16x16x32_bf16 v[66:69], v[176:179], v[216:219], v[66:69]
	s_barrier
	s_setprio 0
	s_add_i32 s0, s33, s24
	v_lshl_add_u64 v[200:201], v[200:201], 0, s[80:81]
	s_mov_b32 m0, s0
	ds_read_b128 v[180:183], v146 offset:49152
	ds_read_b128 v[184:187], v146 offset:50176
	ds_read_b128 v[188:191], v146 offset:51200
	ds_read_b128 v[192:195], v146 offset:52224
	ds_read_b128 v[196:199], v146 offset:53248
	ds_read_b128 v[208:211], v146 offset:54272
	ds_read_b128 v[212:215], v146 offset:55296
	ds_read_b128 v[216:219], v146 offset:56320
	global_load_lds_dwordx4 v[200:201], off
	s_add_i32 m0, s0, 0x2000
	s_add_u32 s0, s2, 0x20080
	v_lshl_add_u64 v[200:201], v[204:205], 0, s[80:81]
	s_addc_u32 s1, s3, 0
	s_add_i32 s2, s55, s24
	global_load_lds_dwordx4 v[200:201], off
	v_lshl_add_u64 v[200:201], s[0:1], 0, v[134:135]
	s_mov_b32 m0, s2
	s_nop 0
	global_load_lds_dwordx4 v[200:201], off
	v_lshl_add_u64 v[200:201], s[0:1], 0, v[130:131]
	s_add_i32 m0, s2, 0x2000
	s_nop 0
	global_load_lds_dwordx4 v[200:201], off
	v_lshl_add_u64 v[200:201], v[206:207], 0, s[80:81]
	s_mov_b32 m0, s29
	s_nop 0
	global_load_lds_dwordx4 v[200:201], off
	v_lshl_add_u64 v[200:201], v[220:221], 0, s[80:81]
	s_mov_b32 m0, s30
	s_nop 0
	global_load_lds_dwordx4 v[200:201], off
	s_waitcnt vmcnt(8)
	s_waitcnt lgkmcnt(0)
	s_setprio 1
	s_barrier
	v_mfma_f32_16x16x32_bf16 v[62:65], v[148:151], v[180:183], v[62:65]
	v_mfma_f32_16x16x32_bf16 v[58:61], v[156:159], v[180:183], v[58:61]
	v_mfma_f32_16x16x32_bf16 v[46:49], v[148:151], v[188:191], v[46:49]
	v_mfma_f32_16x16x32_bf16 v[42:45], v[156:159], v[188:191], v[42:45]
	v_mfma_f32_16x16x32_bf16 v[30:33], v[148:151], v[196:199], v[30:33]
	v_mfma_f32_16x16x32_bf16 v[26:29], v[156:159], v[196:199], v[26:29]
	v_mfma_f32_16x16x32_bf16 v[14:17], v[148:151], v[212:215], v[14:17]
	v_mfma_f32_16x16x32_bf16 v[10:13], v[156:159], v[212:215], v[10:13]
	v_mfma_f32_16x16x32_bf16 v[62:65], v[152:155], v[184:187], v[62:65]
	v_mfma_f32_16x16x32_bf16 v[58:61], v[160:163], v[184:187], v[58:61]
	v_mfma_f32_16x16x32_bf16 v[46:49], v[152:155], v[192:195], v[46:49]
	v_mfma_f32_16x16x32_bf16 v[42:45], v[160:163], v[192:195], v[42:45]
	v_mfma_f32_16x16x32_bf16 v[30:33], v[152:155], v[208:211], v[30:33]
	v_mfma_f32_16x16x32_bf16 v[26:29], v[160:163], v[208:211], v[26:29]
	v_mfma_f32_16x16x32_bf16 v[14:17], v[152:155], v[216:219], v[14:17]
	v_mfma_f32_16x16x32_bf16 v[10:13], v[160:163], v[216:219], v[10:13]
	s_setprio 0
	s_setprio 1
	v_mfma_f32_16x16x32_bf16 v[54:57], v[164:167], v[180:183], v[54:57]
	v_mfma_f32_16x16x32_bf16 v[50:53], v[172:175], v[180:183], v[50:53]
	v_mfma_f32_16x16x32_bf16 v[38:41], v[164:167], v[188:191], v[38:41]
	v_mfma_f32_16x16x32_bf16 v[34:37], v[172:175], v[188:191], v[34:37]
	v_mfma_f32_16x16x32_bf16 v[22:25], v[164:167], v[196:199], v[22:25]
	v_mfma_f32_16x16x32_bf16 v[18:21], v[172:175], v[196:199], v[18:21]
	v_mfma_f32_16x16x32_bf16 v[6:9], v[164:167], v[212:215], v[6:9]
	v_mfma_f32_16x16x32_bf16 v[2:5], v[172:175], v[212:215], v[2:5]
	v_mfma_f32_16x16x32_bf16 v[54:57], v[168:171], v[184:187], v[54:57]
	v_mfma_f32_16x16x32_bf16 v[50:53], v[176:179], v[184:187], v[50:53]
	v_mfma_f32_16x16x32_bf16 v[38:41], v[168:171], v[192:195], v[38:41]
	v_mfma_f32_16x16x32_bf16 v[34:37], v[176:179], v[192:195], v[34:37]
	v_mfma_f32_16x16x32_bf16 v[22:25], v[168:171], v[208:211], v[22:25]
	v_mfma_f32_16x16x32_bf16 v[18:21], v[176:179], v[208:211], v[18:21]
	v_mfma_f32_16x16x32_bf16 v[6:9], v[168:171], v[216:219], v[6:9]
	v_mfma_f32_16x16x32_bf16 v[2:5], v[176:179], v[216:219], v[2:5]
	s_barrier
	s_setprio 0
	s_add_i32 s59, s59, 2
	s_add_u32 s20, s20, 0x100
	s_addc_u32 s21, s21, 0
	s_add_u32 s49, s49, 0x100
	s_addc_u32 s58, s58, 0
	s_cmp_gt_u32 s59, 5
	s_cbranch_scc0 .LBB0_1363
	s_and_b64 vcc, exec, s[14:15]
	s_cbranch_vccz .LBB0_1366
	s_barrier

.LBB0_1428:
	s_add_u32 s0, s26, 0xfff80080
	s_addc_u32 s1, s27, -1
	s_add_i32 s33, 0, 0x10000
	s_cmp_eq_u32 s61, 28
	s_cselect_b32 s5, s17, s1
	s_cselect_b32 s4, s49, s0
	s_cselect_b32 s3, s15, s60
	s_cselect_b32 s2, s58, s59
	s_add_i32 s55, 0, 0x14000
	v_add_u32_e32 v142, s33, v187
	v_add_u32_e32 v158, s55, v187
	ds_read_b128 v[126:129], v142
	ds_read_b128 v[134:137], v142 offset:1024
	ds_read_b128 v[138:141], v142 offset:2048
	ds_read_b128 v[142:145], v142 offset:3072
	ds_read_b128 v[146:149], v158
	ds_read_b128 v[150:153], v158 offset:1024
	ds_read_b128 v[154:157], v158 offset:2048
	ds_read_b128 v[158:161], v158 offset:3072
	v_lshl_add_u64 v[184:185], s[26:27], 0, v[168:169]
	s_add_i32 m0, s23, 0xc000
	ds_read_b128 v[172:175], v189
	ds_read_b128 v[176:179], v189 offset:1024
	ds_read_b128 v[180:183], v189 offset:2048
	ds_read_b128 v[190:193], v189 offset:3072
	ds_read_b128 v[194:197], v189 offset:4096
	ds_read_b128 v[198:201], v189 offset:5120
	ds_read_b128 v[208:211], v189 offset:6144
	ds_read_b128 v[212:215], v189 offset:7168
	global_load_lds_dwordx4 v[184:185], off
	v_lshl_add_u64 v[184:185], s[26:27], 0, v[170:171]
	s_add_i32 m0, s23, 0xe000
	s_nop 0
	global_load_lds_dwordx4 v[184:185], off
	s_waitcnt vmcnt(8)
	s_waitcnt lgkmcnt(0)
	s_setprio 1
	s_barrier
	v_mfma_f32_16x16x32_bf16 v[130:133], v[126:129], v[172:175], v[130:133]
	v_mfma_f32_16x16x32_bf16 v[118:121], v[138:141], v[172:175], v[118:121]
	v_mfma_f32_16x16x32_bf16 v[110:113], v[126:129], v[180:183], v[110:113]
	v_mfma_f32_16x16x32_bf16 v[102:105], v[138:141], v[180:183], v[102:105]
	v_mfma_f32_16x16x32_bf16 v[94:97], v[126:129], v[194:197], v[94:97]
	v_mfma_f32_16x16x32_bf16 v[86:89], v[138:141], v[194:197], v[86:89]
	v_mfma_f32_16x16x32_bf16 v[78:81], v[126:129], v[208:211], v[78:81]
	v_mfma_f32_16x16x32_bf16 v[70:73], v[138:141], v[208:211], v[70:73]
	v_mfma_f32_16x16x32_bf16 v[130:133], v[134:137], v[176:179], v[130:133]
	v_mfma_f32_16x16x32_bf16 v[118:121], v[142:145], v[176:179], v[118:121]
	v_mfma_f32_16x16x32_bf16 v[110:113], v[134:137], v[190:193], v[110:113]
	v_mfma_f32_16x16x32_bf16 v[102:105], v[142:145], v[190:193], v[102:105]
	v_mfma_f32_16x16x32_bf16 v[94:97], v[134:137], v[198:201], v[94:97]
	v_mfma_f32_16x16x32_bf16 v[86:89], v[142:145], v[198:201], v[86:89]
	v_mfma_f32_16x16x32_bf16 v[78:81], v[134:137], v[212:215], v[78:81]
	v_mfma_f32_16x16x32_bf16 v[70:73], v[142:145], v[212:215], v[70:73]
	s_setprio 0
	s_setprio 1
	v_mfma_f32_16x16x32_bf16 v[122:125], v[146:149], v[172:175], v[122:125]
	v_mfma_f32_16x16x32_bf16 v[114:117], v[154:157], v[172:175], v[114:117]
	v_mfma_f32_16x16x32_bf16 v[106:109], v[146:149], v[180:183], v[106:109]
	v_mfma_f32_16x16x32_bf16 v[98:101], v[154:157], v[180:183], v[98:101]
	v_mfma_f32_16x16x32_bf16 v[90:93], v[146:149], v[194:197], v[90:93]
	v_mfma_f32_16x16x32_bf16 v[82:85], v[154:157], v[194:197], v[82:85]
	v_mfma_f32_16x16x32_bf16 v[74:77], v[146:149], v[208:211], v[74:77]
	v_mfma_f32_16x16x32_bf16 v[66:69], v[154:157], v[208:211], v[66:69]
	v_mfma_f32_16x16x32_bf16 v[122:125], v[150:153], v[176:179], v[122:125]
	v_mfma_f32_16x16x32_bf16 v[114:117], v[158:161], v[176:179], v[114:117]
	v_mfma_f32_16x16x32_bf16 v[106:109], v[150:153], v[190:193], v[106:109]
	v_mfma_f32_16x16x32_bf16 v[98:101], v[158:161], v[190:193], v[98:101]
	v_mfma_f32_16x16x32_bf16 v[90:93], v[150:153], v[198:201], v[90:93]
	v_mfma_f32_16x16x32_bf16 v[82:85], v[158:161], v[198:201], v[82:85]
	v_mfma_f32_16x16x32_bf16 v[74:77], v[150:153], v[212:215], v[74:77]
	v_mfma_f32_16x16x32_bf16 v[66:69], v[158:161], v[212:215], v[66:69]
	s_barrier
	s_setprio 0
	s_add_i32 s0, s33, s34
	v_lshl_add_u64 v[184:185], s[2:3], 0, v[202:203]
	s_mov_b32 m0, s0
	ds_read_b128 v[172:175], v189 offset:16384
	ds_read_b128 v[176:179], v189 offset:17408
	ds_read_b128 v[180:183], v189 offset:18432
	ds_read_b128 v[190:193], v189 offset:19456
	ds_read_b128 v[194:197], v189 offset:20480
	ds_read_b128 v[198:201], v189 offset:21504
	ds_read_b128 v[208:211], v189 offset:22528
	ds_read_b128 v[212:215], v189 offset:23552
	global_load_lds_dwordx4 v[184:185], off
	s_add_i32 m0, s0, 0x2000
	s_add_u32 s0, s2, 0x80000
	v_lshl_add_u64 v[204:205], s[2:3], 0, v[162:163]
	s_addc_u32 s1, s3, 0
	s_add_i32 s33, s55, s34
	global_load_lds_dwordx4 v[204:205], off
	v_lshl_add_u64 v[206:207], s[0:1], 0, v[202:203]
	s_mov_b32 m0, s33
	v_lshl_add_u64 v[216:217], s[4:5], 0, v[164:165]
	global_load_lds_dwordx4 v[206:207], off
	v_lshl_add_u64 v[206:207], s[0:1], 0, v[162:163]
	s_add_i32 m0, s33, 0x2000
	s_nop 0
	global_load_lds_dwordx4 v[206:207], off
	v_lshl_add_u64 v[206:207], s[4:5], 0, v[166:167]
	s_mov_b32 m0, s23
	s_nop 0
	global_load_lds_dwordx4 v[206:207], off
	s_mov_b32 m0, s25
	s_nop 0
	global_load_lds_dwordx4 v[216:217], off
	s_waitcnt vmcnt(8)
	s_waitcnt lgkmcnt(0)
	s_setprio 1
	s_barrier
	v_mfma_f32_16x16x32_bf16 v[62:65], v[126:129], v[172:175], v[62:65]
	v_mfma_f32_16x16x32_bf16 v[54:57], v[138:141], v[172:175], v[54:57]
	v_mfma_f32_16x16x32_bf16 v[46:49], v[126:129], v[180:183], v[46:49]
	v_mfma_f32_16x16x32_bf16 v[38:41], v[138:141], v[180:183], v[38:41]
	v_mfma_f32_16x16x32_bf16 v[30:33], v[126:129], v[194:197], v[30:33]
	v_mfma_f32_16x16x32_bf16 v[22:25], v[138:141], v[194:197], v[22:25]
	v_mfma_f32_16x16x32_bf16 v[14:17], v[126:129], v[208:211], v[14:17]
	v_mfma_f32_16x16x32_bf16 v[6:9], v[138:141], v[208:211], v[6:9]
	v_mfma_f32_16x16x32_bf16 v[62:65], v[134:137], v[176:179], v[62:65]
	v_mfma_f32_16x16x32_bf16 v[54:57], v[142:145], v[176:179], v[54:57]
	v_mfma_f32_16x16x32_bf16 v[46:49], v[134:137], v[190:193], v[46:49]
	v_mfma_f32_16x16x32_bf16 v[38:41], v[142:145], v[190:193], v[38:41]
	v_mfma_f32_16x16x32_bf16 v[30:33], v[134:137], v[198:201], v[30:33]
	v_mfma_f32_16x16x32_bf16 v[22:25], v[142:145], v[198:201], v[22:25]
	v_mfma_f32_16x16x32_bf16 v[14:17], v[134:137], v[212:215], v[14:17]
	v_mfma_f32_16x16x32_bf16 v[6:9], v[142:145], v[212:215], v[6:9]
	s_setprio 0
	s_setprio 1
	v_mfma_f32_16x16x32_bf16 v[58:61], v[146:149], v[172:175], v[58:61]
	v_mfma_f32_16x16x32_bf16 v[50:53], v[154:157], v[172:175], v[50:53]
	v_mfma_f32_16x16x32_bf16 v[42:45], v[146:149], v[180:183], v[42:45]
	v_mfma_f32_16x16x32_bf16 v[34:37], v[154:157], v[180:183], v[34:37]
	v_mfma_f32_16x16x32_bf16 v[26:29], v[146:149], v[194:197], v[26:29]
	v_mfma_f32_16x16x32_bf16 v[18:21], v[154:157], v[194:197], v[18:21]
	v_mfma_f32_16x16x32_bf16 v[10:13], v[146:149], v[208:211], v[10:13]
	v_mfma_f32_16x16x32_bf16 v[2:5], v[154:157], v[208:211], v[2:5]
	v_mfma_f32_16x16x32_bf16 v[58:61], v[150:153], v[176:179], v[58:61]
	v_mfma_f32_16x16x32_bf16 v[50:53], v[158:161], v[176:179], v[50:53]
	v_mfma_f32_16x16x32_bf16 v[42:45], v[150:153], v[190:193], v[42:45]
	v_mfma_f32_16x16x32_bf16 v[34:37], v[158:161], v[190:193], v[34:37]
	v_mfma_f32_16x16x32_bf16 v[26:29], v[150:153], v[198:201], v[26:29]
	v_mfma_f32_16x16x32_bf16 v[18:21], v[158:161], v[198:201], v[18:21]
	v_mfma_f32_16x16x32_bf16 v[10:13], v[150:153], v[212:215], v[10:13]
	v_mfma_f32_16x16x32_bf16 v[2:5], v[158:161], v[212:215], v[2:5]
	s_barrier
	s_setprio 0
	s_add_i32 s33, 0, 0x18000
	s_add_i32 s55, 0, 0x1c000
	v_add_u32_e32 v142, s33, v187
	v_add_u32_e32 v158, s55, v187
	ds_read_b128 v[126:129], v142
	ds_read_b128 v[134:137], v142 offset:1024
	ds_read_b128 v[138:141], v142 offset:2048
	ds_read_b128 v[142:145], v142 offset:3072
	ds_read_b128 v[146:149], v158
	ds_read_b128 v[150:153], v158 offset:1024
	ds_read_b128 v[154:157], v158 offset:2048
	ds_read_b128 v[158:161], v158 offset:3072
	s_add_u32 s0, s4, 0x80000
	s_addc_u32 s1, s5, 0
	s_mov_b32 m0, s35
	v_lshl_add_u64 v[218:219], s[0:1], 0, v[166:167]
	ds_read_b128 v[172:175], v189 offset:32768
	ds_read_b128 v[176:179], v189 offset:33792
	ds_read_b128 v[180:183], v189 offset:34816
	ds_read_b128 v[190:193], v189 offset:35840
	ds_read_b128 v[194:197], v189 offset:36864
	ds_read_b128 v[198:201], v189 offset:37888
	ds_read_b128 v[208:211], v189 offset:38912
	ds_read_b128 v[212:215], v189 offset:39936
	global_load_lds_dwordx4 v[218:219], off
	v_lshl_add_u64 v[218:219], s[0:1], 0, v[164:165]
	s_mov_b32 m0, s36
	s_nop 0
	global_load_lds_dwordx4 v[218:219], off
	s_waitcnt vmcnt(8)
	s_waitcnt lgkmcnt(0)
	s_setprio 1
	s_barrier
	v_mfma_f32_16x16x32_bf16 v[130:133], v[126:129], v[172:175], v[130:133]
	v_mfma_f32_16x16x32_bf16 v[118:121], v[138:141], v[172:175], v[118:121]
	v_mfma_f32_16x16x32_bf16 v[110:113], v[126:129], v[180:183], v[110:113]
	v_mfma_f32_16x16x32_bf16 v[102:105], v[138:141], v[180:183], v[102:105]
	v_mfma_f32_16x16x32_bf16 v[94:97], v[126:129], v[194:197], v[94:97]
	v_mfma_f32_16x16x32_bf16 v[86:89], v[138:141], v[194:197], v[86:89]
	v_mfma_f32_16x16x32_bf16 v[78:81], v[126:129], v[208:211], v[78:81]
	v_mfma_f32_16x16x32_bf16 v[70:73], v[138:141], v[208:211], v[70:73]
	v_mfma_f32_16x16x32_bf16 v[130:133], v[134:137], v[176:179], v[130:133]
	v_mfma_f32_16x16x32_bf16 v[118:121], v[142:145], v[176:179], v[118:121]
	v_mfma_f32_16x16x32_bf16 v[110:113], v[134:137], v[190:193], v[110:113]
	v_mfma_f32_16x16x32_bf16 v[102:105], v[142:145], v[190:193], v[102:105]
	v_mfma_f32_16x16x32_bf16 v[94:97], v[134:137], v[198:201], v[94:97]
	v_mfma_f32_16x16x32_bf16 v[86:89], v[142:145], v[198:201], v[86:89]
	v_mfma_f32_16x16x32_bf16 v[78:81], v[134:137], v[212:215], v[78:81]
	v_mfma_f32_16x16x32_bf16 v[70:73], v[142:145], v[212:215], v[70:73]
	s_setprio 0
	s_setprio 1
	v_mfma_f32_16x16x32_bf16 v[122:125], v[146:149], v[172:175], v[122:125]
	v_mfma_f32_16x16x32_bf16 v[114:117], v[154:157], v[172:175], v[114:117]
	v_mfma_f32_16x16x32_bf16 v[106:109], v[146:149], v[180:183], v[106:109]
	v_mfma_f32_16x16x32_bf16 v[98:101], v[154:157], v[180:183], v[98:101]
	v_mfma_f32_16x16x32_bf16 v[90:93], v[146:149], v[194:197], v[90:93]
	v_mfma_f32_16x16x32_bf16 v[82:85], v[154:157], v[194:197], v[82:85]
	v_mfma_f32_16x16x32_bf16 v[74:77], v[146:149], v[208:211], v[74:77]
	v_mfma_f32_16x16x32_bf16 v[66:69], v[154:157], v[208:211], v[66:69]
	v_mfma_f32_16x16x32_bf16 v[122:125], v[150:153], v[176:179], v[122:125]
	v_mfma_f32_16x16x32_bf16 v[114:117], v[158:161], v[176:179], v[114:117]
	v_mfma_f32_16x16x32_bf16 v[106:109], v[150:153], v[190:193], v[106:109]
	v_mfma_f32_16x16x32_bf16 v[98:101], v[158:161], v[190:193], v[98:101]
	v_mfma_f32_16x16x32_bf16 v[90:93], v[150:153], v[198:201], v[90:93]
	v_mfma_f32_16x16x32_bf16 v[82:85], v[158:161], v[198:201], v[82:85]
	v_mfma_f32_16x16x32_bf16 v[74:77], v[150:153], v[212:215], v[74:77]
	v_mfma_f32_16x16x32_bf16 v[66:69], v[158:161], v[212:215], v[66:69]
	s_barrier
	s_setprio 0
	s_add_i32 s0, s33, s34
	v_lshl_add_u64 v[184:185], v[184:185], 0, s[80:81]
	s_mov_b32 m0, s0
	ds_read_b128 v[172:175], v189 offset:49152
	ds_read_b128 v[176:179], v189 offset:50176
	ds_read_b128 v[180:183], v189 offset:51200
	ds_read_b128 v[190:193], v189 offset:52224
	ds_read_b128 v[194:197], v189 offset:53248
	ds_read_b128 v[198:201], v189 offset:54272
	ds_read_b128 v[208:211], v189 offset:55296
	ds_read_b128 v[212:215], v189 offset:56320
	global_load_lds_dwordx4 v[184:185], off
	s_add_i32 m0, s0, 0x2000
	s_add_u32 s0, s2, 0x80080
	v_lshl_add_u64 v[184:185], v[204:205], 0, s[80:81]
	s_addc_u32 s1, s3, 0
	s_add_i32 s2, s55, s34
	global_load_lds_dwordx4 v[184:185], off
	v_lshl_add_u64 v[184:185], s[0:1], 0, v[202:203]
	s_mov_b32 m0, s2
	s_nop 0
	global_load_lds_dwordx4 v[184:185], off
	v_lshl_add_u64 v[184:185], s[0:1], 0, v[162:163]
	s_add_i32 m0, s2, 0x2000
	s_nop 0
	global_load_lds_dwordx4 v[184:185], off
	v_lshl_add_u64 v[184:185], v[206:207], 0, s[80:81]
	s_mov_b32 m0, s39
	s_nop 0
	global_load_lds_dwordx4 v[184:185], off
	v_lshl_add_u64 v[184:185], v[216:217], 0, s[80:81]
	s_mov_b32 m0, s40
	s_nop 0
	global_load_lds_dwordx4 v[184:185], off
	s_waitcnt vmcnt(8)
	s_waitcnt lgkmcnt(0)
	s_setprio 1
	s_barrier
	v_mfma_f32_16x16x32_bf16 v[62:65], v[126:129], v[172:175], v[62:65]
	v_mfma_f32_16x16x32_bf16 v[54:57], v[138:141], v[172:175], v[54:57]
	v_mfma_f32_16x16x32_bf16 v[46:49], v[126:129], v[180:183], v[46:49]
	v_mfma_f32_16x16x32_bf16 v[38:41], v[138:141], v[180:183], v[38:41]
	v_mfma_f32_16x16x32_bf16 v[30:33], v[126:129], v[194:197], v[30:33]
	v_mfma_f32_16x16x32_bf16 v[22:25], v[138:141], v[194:197], v[22:25]
	v_mfma_f32_16x16x32_bf16 v[14:17], v[126:129], v[208:211], v[14:17]
	v_mfma_f32_16x16x32_bf16 v[6:9], v[138:141], v[208:211], v[6:9]
	v_mfma_f32_16x16x32_bf16 v[62:65], v[134:137], v[176:179], v[62:65]
	v_mfma_f32_16x16x32_bf16 v[54:57], v[142:145], v[176:179], v[54:57]
	v_mfma_f32_16x16x32_bf16 v[46:49], v[134:137], v[190:193], v[46:49]
	v_mfma_f32_16x16x32_bf16 v[38:41], v[142:145], v[190:193], v[38:41]
	v_mfma_f32_16x16x32_bf16 v[30:33], v[134:137], v[198:201], v[30:33]
	v_mfma_f32_16x16x32_bf16 v[22:25], v[142:145], v[198:201], v[22:25]
	v_mfma_f32_16x16x32_bf16 v[14:17], v[134:137], v[212:215], v[14:17]
	v_mfma_f32_16x16x32_bf16 v[6:9], v[142:145], v[212:215], v[6:9]
	s_setprio 0
	s_setprio 1
	v_mfma_f32_16x16x32_bf16 v[58:61], v[146:149], v[172:175], v[58:61]
	v_mfma_f32_16x16x32_bf16 v[50:53], v[154:157], v[172:175], v[50:53]
	v_mfma_f32_16x16x32_bf16 v[42:45], v[146:149], v[180:183], v[42:45]
	v_mfma_f32_16x16x32_bf16 v[34:37], v[154:157], v[180:183], v[34:37]
	v_mfma_f32_16x16x32_bf16 v[26:29], v[146:149], v[194:197], v[26:29]
	v_mfma_f32_16x16x32_bf16 v[18:21], v[154:157], v[194:197], v[18:21]
	v_mfma_f32_16x16x32_bf16 v[10:13], v[146:149], v[208:211], v[10:13]
	v_mfma_f32_16x16x32_bf16 v[2:5], v[154:157], v[208:211], v[2:5]
	v_mfma_f32_16x16x32_bf16 v[58:61], v[150:153], v[176:179], v[58:61]
	v_mfma_f32_16x16x32_bf16 v[50:53], v[158:161], v[176:179], v[50:53]
	v_mfma_f32_16x16x32_bf16 v[42:45], v[150:153], v[190:193], v[42:45]
	v_mfma_f32_16x16x32_bf16 v[34:37], v[158:161], v[190:193], v[34:37]
	v_mfma_f32_16x16x32_bf16 v[26:29], v[150:153], v[198:201], v[26:29]
	v_mfma_f32_16x16x32_bf16 v[18:21], v[158:161], v[198:201], v[18:21]
	v_mfma_f32_16x16x32_bf16 v[10:13], v[150:153], v[212:215], v[10:13]
	v_mfma_f32_16x16x32_bf16 v[2:5], v[158:161], v[212:215], v[2:5]
	s_barrier
	s_setprio 0
	s_add_i32 s61, s61, 2
	s_add_u32 s26, s26, 0x100
	s_addc_u32 s27, s27, 0
	s_add_u32 s59, s59, 0x100
	s_addc_u32 s60, s60, 0
	s_cmp_gt_u32 s61, 29
	s_cbranch_scc0 .LBB0_1428
	s_and_b64 vcc, exec, s[10:11]
	s_cbranch_vccz .LBB0_1431
	s_barrier

.LBB0_1594:
	s_add_u32 s0, s28, 0xfff80080
	s_addc_u32 s1, s29, -1
	s_add_i32 s33, 0, 0x10000
	s_cmp_eq_u32 s61, 28
	s_cselect_b32 s5, s19, s1
	s_cselect_b32 s4, s49, s0
	v_add_u32_e32 v140, s33, v143
	s_cselect_b32 s3, s17, s60
	s_cselect_b32 s2, s58, s59
	s_add_i32 s55, 0, 0x14000
	ds_read_b128 v[146:149], v140
	ds_read_b128 v[150:153], v140 offset:1024
	ds_read_b128 v[154:157], v140 offset:2048
	ds_read_b128 v[158:161], v140 offset:3072
	v_add_u32_e32 v140, s55, v143
	ds_read_b128 v[162:165], v140
	ds_read_b128 v[166:169], v140 offset:1024
	ds_read_b128 v[170:173], v140 offset:2048
	ds_read_b128 v[174:177], v140 offset:3072
	v_lshl_add_u64 v[140:141], s[28:29], 0, v[136:137]
	s_add_i32 m0, s25, 0xc000
	ds_read_b128 v[178:181], v145
	ds_read_b128 v[182:185], v145 offset:1024
	ds_read_b128 v[186:189], v145 offset:2048
	ds_read_b128 v[190:193], v145 offset:3072
	ds_read_b128 v[194:197], v145 offset:4096
	ds_read_b128 v[198:201], v145 offset:5120
	ds_read_b128 v[208:211], v145 offset:6144
	ds_read_b128 v[212:215], v145 offset:7168
	global_load_lds_dwordx4 v[140:141], off
	v_lshl_add_u64 v[140:141], s[28:29], 0, v[138:139]
	s_add_i32 m0, s25, 0xe000
	s_nop 0
	global_load_lds_dwordx4 v[140:141], off
	s_waitcnt vmcnt(8)
	s_waitcnt lgkmcnt(0)
	s_setprio 1
	s_barrier
	v_mfma_f32_16x16x32_bf16 v[126:129], v[146:149], v[178:181], v[126:129]
	v_mfma_f32_16x16x32_bf16 v[118:121], v[154:157], v[178:181], v[118:121]
	v_mfma_f32_16x16x32_bf16 v[110:113], v[146:149], v[186:189], v[110:113]
	v_mfma_f32_16x16x32_bf16 v[102:105], v[154:157], v[186:189], v[102:105]
	v_mfma_f32_16x16x32_bf16 v[94:97], v[146:149], v[194:197], v[94:97]
	v_mfma_f32_16x16x32_bf16 v[86:89], v[154:157], v[194:197], v[86:89]
	v_mfma_f32_16x16x32_bf16 v[78:81], v[146:149], v[208:211], v[78:81]
	v_mfma_f32_16x16x32_bf16 v[70:73], v[154:157], v[208:211], v[70:73]
	v_mfma_f32_16x16x32_bf16 v[126:129], v[150:153], v[182:185], v[126:129]
	v_mfma_f32_16x16x32_bf16 v[118:121], v[158:161], v[182:185], v[118:121]
	v_mfma_f32_16x16x32_bf16 v[110:113], v[150:153], v[190:193], v[110:113]
	v_mfma_f32_16x16x32_bf16 v[102:105], v[158:161], v[190:193], v[102:105]
	v_mfma_f32_16x16x32_bf16 v[94:97], v[150:153], v[198:201], v[94:97]
	v_mfma_f32_16x16x32_bf16 v[86:89], v[158:161], v[198:201], v[86:89]
	v_mfma_f32_16x16x32_bf16 v[78:81], v[150:153], v[212:215], v[78:81]
	v_mfma_f32_16x16x32_bf16 v[70:73], v[158:161], v[212:215], v[70:73]
	s_setprio 0
	s_setprio 1
	v_mfma_f32_16x16x32_bf16 v[122:125], v[162:165], v[178:181], v[122:125]
	v_mfma_f32_16x16x32_bf16 v[114:117], v[170:173], v[178:181], v[114:117]
	v_mfma_f32_16x16x32_bf16 v[106:109], v[162:165], v[186:189], v[106:109]
	v_mfma_f32_16x16x32_bf16 v[98:101], v[170:173], v[186:189], v[98:101]
	v_mfma_f32_16x16x32_bf16 v[90:93], v[162:165], v[194:197], v[90:93]
	v_mfma_f32_16x16x32_bf16 v[82:85], v[170:173], v[194:197], v[82:85]
	v_mfma_f32_16x16x32_bf16 v[74:77], v[162:165], v[208:211], v[74:77]
	v_mfma_f32_16x16x32_bf16 v[66:69], v[170:173], v[208:211], v[66:69]
	v_mfma_f32_16x16x32_bf16 v[122:125], v[166:169], v[182:185], v[122:125]
	v_mfma_f32_16x16x32_bf16 v[114:117], v[174:177], v[182:185], v[114:117]
	v_mfma_f32_16x16x32_bf16 v[106:109], v[166:169], v[190:193], v[106:109]
	v_mfma_f32_16x16x32_bf16 v[98:101], v[174:177], v[190:193], v[98:101]
	v_mfma_f32_16x16x32_bf16 v[90:93], v[166:169], v[198:201], v[90:93]
	v_mfma_f32_16x16x32_bf16 v[82:85], v[174:177], v[198:201], v[82:85]
	v_mfma_f32_16x16x32_bf16 v[74:77], v[166:169], v[212:215], v[74:77]
	v_mfma_f32_16x16x32_bf16 v[66:69], v[174:177], v[212:215], v[66:69]
	s_barrier
	s_setprio 0
	s_add_i32 s0, s33, s36
	v_lshl_add_u64 v[140:141], s[2:3], 0, v[202:203]
	s_mov_b32 m0, s0
	ds_read_b128 v[178:181], v145 offset:16384
	ds_read_b128 v[182:185], v145 offset:17408
	ds_read_b128 v[186:189], v145 offset:18432
	ds_read_b128 v[190:193], v145 offset:19456
	ds_read_b128 v[194:197], v145 offset:20480
	ds_read_b128 v[198:201], v145 offset:21504
	ds_read_b128 v[208:211], v145 offset:22528
	ds_read_b128 v[212:215], v145 offset:23552
	global_load_lds_dwordx4 v[140:141], off
	s_add_i32 m0, s0, 0x2000
	s_add_u32 s0, s2, 0x80000
	v_lshl_add_u64 v[204:205], s[2:3], 0, v[130:131]
	s_addc_u32 s1, s3, 0
	s_add_i32 s33, s55, s36
	global_load_lds_dwordx4 v[204:205], off
	v_lshl_add_u64 v[206:207], s[0:1], 0, v[202:203]
	s_mov_b32 m0, s33
	v_lshl_add_u64 v[216:217], s[4:5], 0, v[132:133]
	global_load_lds_dwordx4 v[206:207], off
	v_lshl_add_u64 v[206:207], s[0:1], 0, v[130:131]
	s_add_i32 m0, s33, 0x2000
	s_nop 0
	global_load_lds_dwordx4 v[206:207], off
	v_lshl_add_u64 v[206:207], s[4:5], 0, v[134:135]
	s_mov_b32 m0, s25
	s_nop 0
	global_load_lds_dwordx4 v[206:207], off
	s_mov_b32 m0, s27
	s_nop 0
	global_load_lds_dwordx4 v[216:217], off
	s_waitcnt vmcnt(8)
	s_waitcnt lgkmcnt(0)
	s_setprio 1
	s_barrier
	v_mfma_f32_16x16x32_bf16 v[62:65], v[146:149], v[178:181], v[62:65]
	v_mfma_f32_16x16x32_bf16 v[54:57], v[154:157], v[178:181], v[54:57]
	v_mfma_f32_16x16x32_bf16 v[46:49], v[146:149], v[186:189], v[46:49]
	v_mfma_f32_16x16x32_bf16 v[38:41], v[154:157], v[186:189], v[38:41]
	v_mfma_f32_16x16x32_bf16 v[30:33], v[146:149], v[194:197], v[30:33]
	v_mfma_f32_16x16x32_bf16 v[22:25], v[154:157], v[194:197], v[22:25]
	v_mfma_f32_16x16x32_bf16 v[14:17], v[146:149], v[208:211], v[14:17]
	v_mfma_f32_16x16x32_bf16 v[6:9], v[154:157], v[208:211], v[6:9]
	v_mfma_f32_16x16x32_bf16 v[62:65], v[150:153], v[182:185], v[62:65]
	v_mfma_f32_16x16x32_bf16 v[54:57], v[158:161], v[182:185], v[54:57]
	v_mfma_f32_16x16x32_bf16 v[46:49], v[150:153], v[190:193], v[46:49]
	v_mfma_f32_16x16x32_bf16 v[38:41], v[158:161], v[190:193], v[38:41]
	v_mfma_f32_16x16x32_bf16 v[30:33], v[150:153], v[198:201], v[30:33]
	v_mfma_f32_16x16x32_bf16 v[22:25], v[158:161], v[198:201], v[22:25]
	v_mfma_f32_16x16x32_bf16 v[14:17], v[150:153], v[212:215], v[14:17]
	v_mfma_f32_16x16x32_bf16 v[6:9], v[158:161], v[212:215], v[6:9]
	s_setprio 0
	s_setprio 1
	v_mfma_f32_16x16x32_bf16 v[58:61], v[162:165], v[178:181], v[58:61]
	v_mfma_f32_16x16x32_bf16 v[50:53], v[170:173], v[178:181], v[50:53]
	v_mfma_f32_16x16x32_bf16 v[42:45], v[162:165], v[186:189], v[42:45]
	v_mfma_f32_16x16x32_bf16 v[34:37], v[170:173], v[186:189], v[34:37]
	v_mfma_f32_16x16x32_bf16 v[26:29], v[162:165], v[194:197], v[26:29]
	v_mfma_f32_16x16x32_bf16 v[18:21], v[170:173], v[194:197], v[18:21]
	v_mfma_f32_16x16x32_bf16 v[10:13], v[162:165], v[208:211], v[10:13]
	v_mfma_f32_16x16x32_bf16 v[2:5], v[170:173], v[208:211], v[2:5]
	v_mfma_f32_16x16x32_bf16 v[58:61], v[166:169], v[182:185], v[58:61]
	v_mfma_f32_16x16x32_bf16 v[50:53], v[174:177], v[182:185], v[50:53]
	v_mfma_f32_16x16x32_bf16 v[42:45], v[166:169], v[190:193], v[42:45]
	v_mfma_f32_16x16x32_bf16 v[34:37], v[174:177], v[190:193], v[34:37]
	v_mfma_f32_16x16x32_bf16 v[26:29], v[166:169], v[198:201], v[26:29]
	v_mfma_f32_16x16x32_bf16 v[18:21], v[174:177], v[198:201], v[18:21]
	v_mfma_f32_16x16x32_bf16 v[10:13], v[166:169], v[212:215], v[10:13]
	v_mfma_f32_16x16x32_bf16 v[2:5], v[174:177], v[212:215], v[2:5]
	s_barrier
	s_setprio 0
	s_add_i32 s33, 0, 0x18000
	s_add_i32 s55, 0, 0x1c000
	v_add_u32_e32 v158, s33, v143
	v_add_u32_e32 v174, s55, v143
	ds_read_b128 v[146:149], v158
	ds_read_b128 v[150:153], v158 offset:1024
	ds_read_b128 v[154:157], v158 offset:2048
	ds_read_b128 v[158:161], v158 offset:3072
	ds_read_b128 v[162:165], v174
	ds_read_b128 v[166:169], v174 offset:1024
	ds_read_b128 v[170:173], v174 offset:2048
	ds_read_b128 v[174:177], v174 offset:3072
	s_add_u32 s0, s4, 0x80000
	s_addc_u32 s1, s5, 0
	s_mov_b32 m0, s37
	v_lshl_add_u64 v[218:219], s[0:1], 0, v[134:135]
	ds_read_b128 v[178:181], v145 offset:32768
	ds_read_b128 v[182:185], v145 offset:33792
	ds_read_b128 v[186:189], v145 offset:34816
	ds_read_b128 v[190:193], v145 offset:35840
	ds_read_b128 v[194:197], v145 offset:36864
	ds_read_b128 v[198:201], v145 offset:37888
	ds_read_b128 v[208:211], v145 offset:38912
	ds_read_b128 v[212:215], v145 offset:39936
	global_load_lds_dwordx4 v[218:219], off
	v_lshl_add_u64 v[218:219], s[0:1], 0, v[132:133]
	s_mov_b32 m0, s38
	s_nop 0
	global_load_lds_dwordx4 v[218:219], off
	s_waitcnt vmcnt(8)
	s_waitcnt lgkmcnt(0)
	s_setprio 1
	s_barrier
	v_mfma_f32_16x16x32_bf16 v[126:129], v[146:149], v[178:181], v[126:129]
	v_mfma_f32_16x16x32_bf16 v[118:121], v[154:157], v[178:181], v[118:121]
	v_mfma_f32_16x16x32_bf16 v[110:113], v[146:149], v[186:189], v[110:113]
	v_mfma_f32_16x16x32_bf16 v[102:105], v[154:157], v[186:189], v[102:105]
	v_mfma_f32_16x16x32_bf16 v[94:97], v[146:149], v[194:197], v[94:97]
	v_mfma_f32_16x16x32_bf16 v[86:89], v[154:157], v[194:197], v[86:89]
	v_mfma_f32_16x16x32_bf16 v[78:81], v[146:149], v[208:211], v[78:81]
	v_mfma_f32_16x16x32_bf16 v[70:73], v[154:157], v[208:211], v[70:73]
	v_mfma_f32_16x16x32_bf16 v[126:129], v[150:153], v[182:185], v[126:129]
	v_mfma_f32_16x16x32_bf16 v[118:121], v[158:161], v[182:185], v[118:121]
	v_mfma_f32_16x16x32_bf16 v[110:113], v[150:153], v[190:193], v[110:113]
	v_mfma_f32_16x16x32_bf16 v[102:105], v[158:161], v[190:193], v[102:105]
	v_mfma_f32_16x16x32_bf16 v[94:97], v[150:153], v[198:201], v[94:97]
	v_mfma_f32_16x16x32_bf16 v[86:89], v[158:161], v[198:201], v[86:89]
	v_mfma_f32_16x16x32_bf16 v[78:81], v[150:153], v[212:215], v[78:81]
	v_mfma_f32_16x16x32_bf16 v[70:73], v[158:161], v[212:215], v[70:73]
	s_setprio 0
	s_setprio 1
	v_mfma_f32_16x16x32_bf16 v[122:125], v[162:165], v[178:181], v[122:125]
	v_mfma_f32_16x16x32_bf16 v[114:117], v[170:173], v[178:181], v[114:117]
	v_mfma_f32_16x16x32_bf16 v[106:109], v[162:165], v[186:189], v[106:109]
	v_mfma_f32_16x16x32_bf16 v[98:101], v[170:173], v[186:189], v[98:101]
	v_mfma_f32_16x16x32_bf16 v[90:93], v[162:165], v[194:197], v[90:93]
	v_mfma_f32_16x16x32_bf16 v[82:85], v[170:173], v[194:197], v[82:85]
	v_mfma_f32_16x16x32_bf16 v[74:77], v[162:165], v[208:211], v[74:77]
	v_mfma_f32_16x16x32_bf16 v[66:69], v[170:173], v[208:211], v[66:69]
	v_mfma_f32_16x16x32_bf16 v[122:125], v[166:169], v[182:185], v[122:125]
	v_mfma_f32_16x16x32_bf16 v[114:117], v[174:177], v[182:185], v[114:117]
	v_mfma_f32_16x16x32_bf16 v[106:109], v[166:169], v[190:193], v[106:109]
	v_mfma_f32_16x16x32_bf16 v[98:101], v[174:177], v[190:193], v[98:101]
	v_mfma_f32_16x16x32_bf16 v[90:93], v[166:169], v[198:201], v[90:93]
	v_mfma_f32_16x16x32_bf16 v[82:85], v[174:177], v[198:201], v[82:85]
	v_mfma_f32_16x16x32_bf16 v[74:77], v[166:169], v[212:215], v[74:77]
	v_mfma_f32_16x16x32_bf16 v[66:69], v[174:177], v[212:215], v[66:69]
	s_barrier
	s_setprio 0
	s_add_i32 s0, s33, s36
	v_lshl_add_u64 v[140:141], v[140:141], 0, s[80:81]
	s_mov_b32 m0, s0
	ds_read_b128 v[178:181], v145 offset:49152
	ds_read_b128 v[182:185], v145 offset:50176
	ds_read_b128 v[186:189], v145 offset:51200
	ds_read_b128 v[190:193], v145 offset:52224
	ds_read_b128 v[194:197], v145 offset:53248
	ds_read_b128 v[198:201], v145 offset:54272
	ds_read_b128 v[208:211], v145 offset:55296
	ds_read_b128 v[212:215], v145 offset:56320
	global_load_lds_dwordx4 v[140:141], off
	s_add_i32 m0, s0, 0x2000
	s_add_u32 s0, s2, 0x80080
	v_lshl_add_u64 v[140:141], v[204:205], 0, s[80:81]
	s_addc_u32 s1, s3, 0
	s_add_i32 s2, s55, s36
	global_load_lds_dwordx4 v[140:141], off
	v_lshl_add_u64 v[140:141], s[0:1], 0, v[202:203]
	s_mov_b32 m0, s2
	s_nop 0
	global_load_lds_dwordx4 v[140:141], off
	v_lshl_add_u64 v[140:141], s[0:1], 0, v[130:131]
	s_add_i32 m0, s2, 0x2000
	s_nop 0
	global_load_lds_dwordx4 v[140:141], off
	v_lshl_add_u64 v[140:141], v[206:207], 0, s[80:81]
	s_mov_b32 m0, s39
	s_nop 0
	global_load_lds_dwordx4 v[140:141], off
	v_lshl_add_u64 v[140:141], v[216:217], 0, s[80:81]
	s_mov_b32 m0, s40
	s_nop 0
	global_load_lds_dwordx4 v[140:141], off
	s_waitcnt vmcnt(8)
	s_waitcnt lgkmcnt(0)
	s_setprio 1
	s_barrier
	v_mfma_f32_16x16x32_bf16 v[62:65], v[146:149], v[178:181], v[62:65]
	v_mfma_f32_16x16x32_bf16 v[54:57], v[154:157], v[178:181], v[54:57]
	v_mfma_f32_16x16x32_bf16 v[46:49], v[146:149], v[186:189], v[46:49]
	v_mfma_f32_16x16x32_bf16 v[38:41], v[154:157], v[186:189], v[38:41]
	v_mfma_f32_16x16x32_bf16 v[30:33], v[146:149], v[194:197], v[30:33]
	v_mfma_f32_16x16x32_bf16 v[22:25], v[154:157], v[194:197], v[22:25]
	v_mfma_f32_16x16x32_bf16 v[14:17], v[146:149], v[208:211], v[14:17]
	v_mfma_f32_16x16x32_bf16 v[6:9], v[154:157], v[208:211], v[6:9]
	v_mfma_f32_16x16x32_bf16 v[62:65], v[150:153], v[182:185], v[62:65]
	v_mfma_f32_16x16x32_bf16 v[54:57], v[158:161], v[182:185], v[54:57]
	v_mfma_f32_16x16x32_bf16 v[46:49], v[150:153], v[190:193], v[46:49]
	v_mfma_f32_16x16x32_bf16 v[38:41], v[158:161], v[190:193], v[38:41]
	v_mfma_f32_16x16x32_bf16 v[30:33], v[150:153], v[198:201], v[30:33]
	v_mfma_f32_16x16x32_bf16 v[22:25], v[158:161], v[198:201], v[22:25]
	v_mfma_f32_16x16x32_bf16 v[14:17], v[150:153], v[212:215], v[14:17]
	v_mfma_f32_16x16x32_bf16 v[6:9], v[158:161], v[212:215], v[6:9]
	s_setprio 0
	s_setprio 1
	v_mfma_f32_16x16x32_bf16 v[58:61], v[162:165], v[178:181], v[58:61]
	v_mfma_f32_16x16x32_bf16 v[50:53], v[170:173], v[178:181], v[50:53]
	v_mfma_f32_16x16x32_bf16 v[42:45], v[162:165], v[186:189], v[42:45]
	v_mfma_f32_16x16x32_bf16 v[34:37], v[170:173], v[186:189], v[34:37]
	v_mfma_f32_16x16x32_bf16 v[26:29], v[162:165], v[194:197], v[26:29]
	v_mfma_f32_16x16x32_bf16 v[18:21], v[170:173], v[194:197], v[18:21]
	v_mfma_f32_16x16x32_bf16 v[10:13], v[162:165], v[208:211], v[10:13]
	v_mfma_f32_16x16x32_bf16 v[2:5], v[170:173], v[208:211], v[2:5]
	v_mfma_f32_16x16x32_bf16 v[58:61], v[166:169], v[182:185], v[58:61]
	v_mfma_f32_16x16x32_bf16 v[50:53], v[174:177], v[182:185], v[50:53]
	v_mfma_f32_16x16x32_bf16 v[42:45], v[166:169], v[190:193], v[42:45]
	v_mfma_f32_16x16x32_bf16 v[34:37], v[174:177], v[190:193], v[34:37]
	v_mfma_f32_16x16x32_bf16 v[26:29], v[166:169], v[198:201], v[26:29]
	v_mfma_f32_16x16x32_bf16 v[18:21], v[174:177], v[198:201], v[18:21]
	v_mfma_f32_16x16x32_bf16 v[10:13], v[166:169], v[212:215], v[10:13]
	v_mfma_f32_16x16x32_bf16 v[2:5], v[174:177], v[212:215], v[2:5]
	s_barrier
	s_setprio 0
	s_add_i32 s61, s61, 2
	s_add_u32 s28, s28, 0x100
	s_addc_u32 s29, s29, 0
	s_add_u32 s59, s59, 0x100
	s_addc_u32 s60, s60, 0
	s_cmp_gt_u32 s61, 29
	s_cbranch_scc0 .LBB0_1594
	s_and_b64 vcc, exec, s[14:15]
	s_cbranch_vccz .LBB0_1597
	s_barrier

.LBB0_1718:
	s_add_u32 s18, s4, 0x100
	s_addc_u32 s19, s5, 0
	s_add_i32 s0, 0, 0x10000
	s_cmpk_eq_i32 s59, 0x54
	s_cselect_b32 s23, s9, s19
	s_cselect_b32 s22, s8, s18
	s_cselect_b32 s21, s17, s58
	s_cselect_b32 s20, s16, s49
	s_add_i32 s33, 0, 0x14000
	v_add_u32_e32 v98, s0, v205
	v_add_u32_e32 v134, s33, v205
	ds_read_b128 v[78:81], v98
	ds_read_b128 v[82:85], v98 offset:1024
	ds_read_b128 v[94:97], v98 offset:2048
	ds_read_b128 v[98:101], v98 offset:3072
	ds_read_b128 v[106:109], v134
	ds_read_b128 v[110:113], v134 offset:1024
	ds_read_b128 v[126:129], v134 offset:2048
	ds_read_b128 v[134:137], v134 offset:3072
	v_lshl_add_u64 v[194:195], s[4:5], 0, v[214:215]
	s_add_i32 m0, s27, 0xc000
	ds_read_b128 v[146:149], v239
	ds_read_b128 v[158:161], v239 offset:1024
	ds_read_b128 v[166:169], v239 offset:2048
	ds_read_b128 v[174:177], v239 offset:3072
	ds_read_b128 v[178:181], v239 offset:4096
	ds_read_b128 v[182:185], v239 offset:5120
	ds_read_b128 v[186:189], v239 offset:6144
	ds_read_b128 v[190:193], v239 offset:7168
	global_load_lds_dwordx4 v[194:195], off
	v_lshl_add_u64 v[194:195], s[4:5], 0, v[216:217]
	s_add_i32 m0, s27, 0xe000
	s_nop 0
	global_load_lds_dwordx4 v[194:195], off
	s_waitcnt vmcnt(8)
	s_waitcnt lgkmcnt(0)
	s_setprio 1
	s_barrier
	v_mfma_f32_16x16x32_bf16 v[170:173], v[78:81], v[146:149], v[170:173]
	v_mfma_f32_16x16x32_bf16 v[162:165], v[94:97], v[146:149], v[162:165]
	v_mfma_f32_16x16x32_bf16 v[142:145], v[78:81], v[166:169], v[142:145]
	v_mfma_f32_16x16x32_bf16 v[138:141], v[94:97], v[166:169], v[138:141]
	v_mfma_f32_16x16x32_bf16 v[118:121], v[78:81], v[178:181], v[118:121]
	v_mfma_f32_16x16x32_bf16 v[114:117], v[94:97], v[178:181], v[114:117]
	v_mfma_f32_16x16x32_bf16 v[86:89], v[78:81], v[186:189], v[86:89]
	v_mfma_f32_16x16x32_bf16 v[74:77], v[94:97], v[186:189], v[74:77]
	v_mfma_f32_16x16x32_bf16 v[170:173], v[82:85], v[158:161], v[170:173]
	v_mfma_f32_16x16x32_bf16 v[162:165], v[98:101], v[158:161], v[162:165]
	v_mfma_f32_16x16x32_bf16 v[142:145], v[82:85], v[174:177], v[142:145]
	v_mfma_f32_16x16x32_bf16 v[138:141], v[98:101], v[174:177], v[138:141]
	v_mfma_f32_16x16x32_bf16 v[118:121], v[82:85], v[182:185], v[118:121]
	v_mfma_f32_16x16x32_bf16 v[114:117], v[98:101], v[182:185], v[114:117]
	v_mfma_f32_16x16x32_bf16 v[86:89], v[82:85], v[190:193], v[86:89]
	v_mfma_f32_16x16x32_bf16 v[74:77], v[98:101], v[190:193], v[74:77]
	s_setprio 0
	s_setprio 1
	v_mfma_f32_16x16x32_bf16 v[154:157], v[106:109], v[146:149], v[154:157]
	v_mfma_f32_16x16x32_bf16 v[130:133], v[106:109], v[166:169], v[130:133]
	v_mfma_f32_16x16x32_bf16 v[122:125], v[126:129], v[166:169], v[122:125]
	v_mfma_f32_16x16x32_bf16 v[102:105], v[106:109], v[178:181], v[102:105]
	v_mfma_f32_16x16x32_bf16 v[90:93], v[126:129], v[178:181], v[90:93]
	v_mfma_f32_16x16x32_bf16 v[70:73], v[106:109], v[186:189], v[70:73]
	v_mfma_f32_16x16x32_bf16 v[66:69], v[126:129], v[186:189], v[66:69]
	v_mfma_f32_16x16x32_bf16 v[154:157], v[110:113], v[158:161], v[154:157]
	v_mfma_f32_16x16x32_bf16 v[146:149], v[126:129], v[146:149], v[150:153]
	v_mfma_f32_16x16x32_bf16 v[130:133], v[110:113], v[174:177], v[130:133]
	v_mfma_f32_16x16x32_bf16 v[122:125], v[134:137], v[174:177], v[122:125]
	v_mfma_f32_16x16x32_bf16 v[102:105], v[110:113], v[182:185], v[102:105]
	v_mfma_f32_16x16x32_bf16 v[90:93], v[134:137], v[182:185], v[90:93]
	v_mfma_f32_16x16x32_bf16 v[70:73], v[110:113], v[190:193], v[70:73]
	v_mfma_f32_16x16x32_bf16 v[66:69], v[134:137], v[190:193], v[66:69]
	v_mfma_f32_16x16x32_bf16 v[146:149], v[134:137], v[158:161], v[146:149]
	s_barrier
	s_setprio 0
	s_add_i32 s0, s0, s26
	v_lshl_add_u64 v[194:195], s[20:21], 0, v[202:203]
	s_mov_b32 m0, s0
	ds_read_b128 v[150:153], v239 offset:16384
	ds_read_b128 v[158:161], v239 offset:17408
	ds_read_b128 v[166:169], v239 offset:18432
	ds_read_b128 v[174:177], v239 offset:19456
	ds_read_b128 v[178:181], v239 offset:20480
	ds_read_b128 v[182:185], v239 offset:21504
	ds_read_b128 v[186:189], v239 offset:22528
	ds_read_b128 v[190:193], v239 offset:23552
	global_load_lds_dwordx4 v[194:195], off
	s_add_i32 m0, s0, 0x2000
	s_add_u32 s0, s20, 0x160000
	v_lshl_add_u64 v[196:197], s[20:21], 0, v[208:209]
	s_addc_u32 s1, s21, 0
	s_add_i32 s4, s33, s26
	global_load_lds_dwordx4 v[196:197], off
	v_lshl_add_u64 v[198:199], s[0:1], 0, v[202:203]
	s_mov_b32 m0, s4
	v_lshl_add_u64 v[200:201], s[22:23], 0, v[210:211]
	global_load_lds_dwordx4 v[198:199], off
	v_lshl_add_u64 v[198:199], s[0:1], 0, v[208:209]
	s_add_i32 m0, s4, 0x2000
	s_nop 0
	global_load_lds_dwordx4 v[198:199], off
	v_lshl_add_u64 v[198:199], s[22:23], 0, v[212:213]
	s_mov_b32 m0, s27
	s_nop 0
	global_load_lds_dwordx4 v[198:199], off
	s_mov_b32 m0, s28
	s_nop 0
	global_load_lds_dwordx4 v[200:201], off
	s_waitcnt vmcnt(8)
	s_waitcnt lgkmcnt(0)
	s_setprio 1
	s_barrier
	v_mfma_f32_16x16x32_bf16 v[62:65], v[78:81], v[150:153], v[62:65]
	v_mfma_f32_16x16x32_bf16 v[58:61], v[94:97], v[150:153], v[58:61]
	v_mfma_f32_16x16x32_bf16 v[46:49], v[78:81], v[166:169], v[46:49]
	v_mfma_f32_16x16x32_bf16 v[42:45], v[94:97], v[166:169], v[42:45]
	v_mfma_f32_16x16x32_bf16 v[30:33], v[78:81], v[178:181], v[30:33]
	v_mfma_f32_16x16x32_bf16 v[26:29], v[94:97], v[178:181], v[26:29]
	v_mfma_f32_16x16x32_bf16 v[14:17], v[78:81], v[186:189], v[14:17]
	v_mfma_f32_16x16x32_bf16 v[10:13], v[94:97], v[186:189], v[10:13]
	v_mfma_f32_16x16x32_bf16 v[62:65], v[82:85], v[158:161], v[62:65]
	v_mfma_f32_16x16x32_bf16 v[58:61], v[98:101], v[158:161], v[58:61]
	v_mfma_f32_16x16x32_bf16 v[46:49], v[82:85], v[174:177], v[46:49]
	v_mfma_f32_16x16x32_bf16 v[42:45], v[98:101], v[174:177], v[42:45]
	v_mfma_f32_16x16x32_bf16 v[30:33], v[82:85], v[182:185], v[30:33]
	v_mfma_f32_16x16x32_bf16 v[26:29], v[98:101], v[182:185], v[26:29]
	v_mfma_f32_16x16x32_bf16 v[14:17], v[82:85], v[190:193], v[14:17]
	v_mfma_f32_16x16x32_bf16 v[10:13], v[98:101], v[190:193], v[10:13]
	s_setprio 0
	s_setprio 1
	v_mfma_f32_16x16x32_bf16 v[54:57], v[106:109], v[150:153], v[54:57]
	v_mfma_f32_16x16x32_bf16 v[50:53], v[126:129], v[150:153], v[50:53]
	v_mfma_f32_16x16x32_bf16 v[38:41], v[106:109], v[166:169], v[38:41]
	v_mfma_f32_16x16x32_bf16 v[34:37], v[126:129], v[166:169], v[34:37]
	v_mfma_f32_16x16x32_bf16 v[22:25], v[106:109], v[178:181], v[22:25]
	v_mfma_f32_16x16x32_bf16 v[18:21], v[126:129], v[178:181], v[18:21]
	v_mfma_f32_16x16x32_bf16 v[6:9], v[106:109], v[186:189], v[6:9]
	v_mfma_f32_16x16x32_bf16 v[2:5], v[126:129], v[186:189], v[2:5]
	v_mfma_f32_16x16x32_bf16 v[54:57], v[110:113], v[158:161], v[54:57]
	v_mfma_f32_16x16x32_bf16 v[50:53], v[134:137], v[158:161], v[50:53]
	v_mfma_f32_16x16x32_bf16 v[38:41], v[110:113], v[174:177], v[38:41]
	v_mfma_f32_16x16x32_bf16 v[34:37], v[134:137], v[174:177], v[34:37]
	v_mfma_f32_16x16x32_bf16 v[22:25], v[110:113], v[182:185], v[22:25]
	v_mfma_f32_16x16x32_bf16 v[18:21], v[134:137], v[182:185], v[18:21]
	v_mfma_f32_16x16x32_bf16 v[6:9], v[110:113], v[190:193], v[6:9]
	v_mfma_f32_16x16x32_bf16 v[2:5], v[134:137], v[190:193], v[2:5]
	s_barrier
	s_setprio 0
	s_add_i32 s4, 0, 0x18000
	s_add_i32 s5, 0, 0x1c000
	v_add_u32_e32 v98, s4, v205
	v_add_u32_e32 v134, s5, v205
	ds_read_b128 v[78:81], v98
	ds_read_b128 v[82:85], v98 offset:1024
	ds_read_b128 v[94:97], v98 offset:2048
	ds_read_b128 v[98:101], v98 offset:3072
	ds_read_b128 v[106:109], v134
	ds_read_b128 v[110:113], v134 offset:1024
	ds_read_b128 v[126:129], v134 offset:2048
	ds_read_b128 v[134:137], v134 offset:3072
	s_add_u32 s0, s22, 0x160000
	s_addc_u32 s1, s23, 0
	s_mov_b32 m0, s29
	v_lshl_add_u64 v[206:207], s[0:1], 0, v[212:213]
	ds_read_b128 v[150:153], v239 offset:32768
	ds_read_b128 v[158:161], v239 offset:33792
	ds_read_b128 v[166:169], v239 offset:34816
	ds_read_b128 v[174:177], v239 offset:35840
	ds_read_b128 v[178:181], v239 offset:36864
	ds_read_b128 v[182:185], v239 offset:37888
	ds_read_b128 v[186:189], v239 offset:38912
	ds_read_b128 v[190:193], v239 offset:39936
	global_load_lds_dwordx4 v[206:207], off
	v_lshl_add_u64 v[206:207], s[0:1], 0, v[210:211]
	s_mov_b32 m0, s30
	s_nop 0
	global_load_lds_dwordx4 v[206:207], off
	s_waitcnt vmcnt(8)
	s_waitcnt lgkmcnt(0)
	s_setprio 1
	s_barrier
	v_mfma_f32_16x16x32_bf16 v[170:173], v[78:81], v[150:153], v[170:173]
	v_mfma_f32_16x16x32_bf16 v[162:165], v[94:97], v[150:153], v[162:165]
	v_mfma_f32_16x16x32_bf16 v[142:145], v[78:81], v[166:169], v[142:145]
	v_mfma_f32_16x16x32_bf16 v[138:141], v[94:97], v[166:169], v[138:141]
	v_mfma_f32_16x16x32_bf16 v[118:121], v[78:81], v[178:181], v[118:121]
	v_mfma_f32_16x16x32_bf16 v[114:117], v[94:97], v[178:181], v[114:117]
	v_mfma_f32_16x16x32_bf16 v[86:89], v[78:81], v[186:189], v[86:89]
	v_mfma_f32_16x16x32_bf16 v[74:77], v[94:97], v[186:189], v[74:77]
	v_mfma_f32_16x16x32_bf16 v[170:173], v[82:85], v[158:161], v[170:173]
	v_mfma_f32_16x16x32_bf16 v[162:165], v[98:101], v[158:161], v[162:165]
	v_mfma_f32_16x16x32_bf16 v[142:145], v[82:85], v[174:177], v[142:145]
	v_mfma_f32_16x16x32_bf16 v[138:141], v[98:101], v[174:177], v[138:141]
	v_mfma_f32_16x16x32_bf16 v[118:121], v[82:85], v[182:185], v[118:121]
	v_mfma_f32_16x16x32_bf16 v[114:117], v[98:101], v[182:185], v[114:117]
	v_mfma_f32_16x16x32_bf16 v[86:89], v[82:85], v[190:193], v[86:89]
	v_mfma_f32_16x16x32_bf16 v[74:77], v[98:101], v[190:193], v[74:77]
	s_setprio 0
	s_setprio 1
	v_mfma_f32_16x16x32_bf16 v[154:157], v[106:109], v[150:153], v[154:157]
	v_mfma_f32_16x16x32_bf16 v[146:149], v[126:129], v[150:153], v[146:149]
	v_mfma_f32_16x16x32_bf16 v[130:133], v[106:109], v[166:169], v[130:133]
	v_mfma_f32_16x16x32_bf16 v[122:125], v[126:129], v[166:169], v[122:125]
	v_mfma_f32_16x16x32_bf16 v[102:105], v[106:109], v[178:181], v[102:105]
	v_mfma_f32_16x16x32_bf16 v[90:93], v[126:129], v[178:181], v[90:93]
	v_mfma_f32_16x16x32_bf16 v[70:73], v[106:109], v[186:189], v[70:73]
	v_mfma_f32_16x16x32_bf16 v[66:69], v[126:129], v[186:189], v[66:69]
	v_mfma_f32_16x16x32_bf16 v[154:157], v[110:113], v[158:161], v[154:157]
	v_mfma_f32_16x16x32_bf16 v[150:153], v[134:137], v[158:161], v[146:149]
	v_mfma_f32_16x16x32_bf16 v[130:133], v[110:113], v[174:177], v[130:133]
	v_mfma_f32_16x16x32_bf16 v[122:125], v[134:137], v[174:177], v[122:125]
	v_mfma_f32_16x16x32_bf16 v[102:105], v[110:113], v[182:185], v[102:105]
	v_mfma_f32_16x16x32_bf16 v[90:93], v[134:137], v[182:185], v[90:93]
	v_mfma_f32_16x16x32_bf16 v[70:73], v[110:113], v[190:193], v[70:73]
	v_mfma_f32_16x16x32_bf16 v[66:69], v[134:137], v[190:193], v[66:69]
	s_barrier
	s_setprio 0
	s_add_i32 s0, s4, s26
	v_lshl_add_u64 v[194:195], v[194:195], 0, s[80:81]
	s_mov_b32 m0, s0
	ds_read_b128 v[146:149], v239 offset:49152
	ds_read_b128 v[158:161], v239 offset:50176
	ds_read_b128 v[166:169], v239 offset:51200
	ds_read_b128 v[174:177], v239 offset:52224
	ds_read_b128 v[178:181], v239 offset:53248
	ds_read_b128 v[182:185], v239 offset:54272
	ds_read_b128 v[186:189], v239 offset:55296
	ds_read_b128 v[190:193], v239 offset:56320
	global_load_lds_dwordx4 v[194:195], off
	s_add_i32 m0, s0, 0x2000
	s_add_u32 s0, s20, 0x160080
	v_lshl_add_u64 v[194:195], v[196:197], 0, s[80:81]
	s_addc_u32 s1, s21, 0
	s_add_i32 s4, s5, s26
	global_load_lds_dwordx4 v[194:195], off
	v_lshl_add_u64 v[194:195], s[0:1], 0, v[202:203]
	s_mov_b32 m0, s4
	s_nop 0
	global_load_lds_dwordx4 v[194:195], off
	v_lshl_add_u64 v[194:195], s[0:1], 0, v[208:209]
	s_add_i32 m0, s4, 0x2000
	s_nop 0
	global_load_lds_dwordx4 v[194:195], off
	v_lshl_add_u64 v[194:195], v[198:199], 0, s[80:81]
	s_mov_b32 m0, s35
	s_nop 0
	global_load_lds_dwordx4 v[194:195], off
	v_lshl_add_u64 v[194:195], v[200:201], 0, s[80:81]
	s_mov_b32 m0, s36
	s_nop 0
	global_load_lds_dwordx4 v[194:195], off
	s_waitcnt vmcnt(8)
	s_waitcnt lgkmcnt(0)
	s_setprio 1
	s_barrier
	v_mfma_f32_16x16x32_bf16 v[62:65], v[78:81], v[146:149], v[62:65]
	v_mfma_f32_16x16x32_bf16 v[58:61], v[94:97], v[146:149], v[58:61]
	v_mfma_f32_16x16x32_bf16 v[46:49], v[78:81], v[166:169], v[46:49]
	v_mfma_f32_16x16x32_bf16 v[42:45], v[94:97], v[166:169], v[42:45]
	v_mfma_f32_16x16x32_bf16 v[30:33], v[78:81], v[178:181], v[30:33]
	v_mfma_f32_16x16x32_bf16 v[26:29], v[94:97], v[178:181], v[26:29]
	v_mfma_f32_16x16x32_bf16 v[14:17], v[78:81], v[186:189], v[14:17]
	v_mfma_f32_16x16x32_bf16 v[10:13], v[94:97], v[186:189], v[10:13]
	v_mfma_f32_16x16x32_bf16 v[62:65], v[82:85], v[158:161], v[62:65]
	v_mfma_f32_16x16x32_bf16 v[58:61], v[98:101], v[158:161], v[58:61]
	v_mfma_f32_16x16x32_bf16 v[46:49], v[82:85], v[174:177], v[46:49]
	v_mfma_f32_16x16x32_bf16 v[42:45], v[98:101], v[174:177], v[42:45]
	v_mfma_f32_16x16x32_bf16 v[30:33], v[82:85], v[182:185], v[30:33]
	v_mfma_f32_16x16x32_bf16 v[26:29], v[98:101], v[182:185], v[26:29]
	v_mfma_f32_16x16x32_bf16 v[14:17], v[82:85], v[190:193], v[14:17]
	v_mfma_f32_16x16x32_bf16 v[10:13], v[98:101], v[190:193], v[10:13]
	s_setprio 0
	s_setprio 1
	v_mfma_f32_16x16x32_bf16 v[54:57], v[106:109], v[146:149], v[54:57]
	v_mfma_f32_16x16x32_bf16 v[50:53], v[126:129], v[146:149], v[50:53]
	v_mfma_f32_16x16x32_bf16 v[38:41], v[106:109], v[166:169], v[38:41]
	v_mfma_f32_16x16x32_bf16 v[34:37], v[126:129], v[166:169], v[34:37]
	v_mfma_f32_16x16x32_bf16 v[22:25], v[106:109], v[178:181], v[22:25]
	v_mfma_f32_16x16x32_bf16 v[18:21], v[126:129], v[178:181], v[18:21]
	v_mfma_f32_16x16x32_bf16 v[6:9], v[106:109], v[186:189], v[6:9]
	v_mfma_f32_16x16x32_bf16 v[2:5], v[126:129], v[186:189], v[2:5]
	v_mfma_f32_16x16x32_bf16 v[54:57], v[110:113], v[158:161], v[54:57]
	v_mfma_f32_16x16x32_bf16 v[50:53], v[134:137], v[158:161], v[50:53]
	v_mfma_f32_16x16x32_bf16 v[38:41], v[110:113], v[174:177], v[38:41]
	v_mfma_f32_16x16x32_bf16 v[34:37], v[134:137], v[174:177], v[34:37]
	v_mfma_f32_16x16x32_bf16 v[22:25], v[110:113], v[182:185], v[22:25]
	v_mfma_f32_16x16x32_bf16 v[18:21], v[134:137], v[182:185], v[18:21]
	v_mfma_f32_16x16x32_bf16 v[6:9], v[110:113], v[190:193], v[6:9]
	v_mfma_f32_16x16x32_bf16 v[2:5], v[134:137], v[190:193], v[2:5]
	s_barrier
	s_setprio 0
	s_add_i32 s59, s59, 2
	s_add_u32 s49, s49, 0x100
	s_addc_u32 s58, s58, 0
	s_cmpk_gt_u32 s59, 0x55
	s_mov_b64 s[4:5], s[18:19]
	s_cbranch_scc0 .LBB0_1718
	s_and_b64 vcc, exec, s[14:15]
	s_cbranch_vccz .LBB0_1721
	s_barrier

.LBB0_1739:
	s_add_u32 s16, s14, 0x100
	s_addc_u32 s17, s15, 0
	s_add_i32 s0, 0, 0x10000
	s_cmp_eq_u32 s49, 4
	s_cselect_b32 s21, s9, s17
	s_cselect_b32 s20, s8, s16
	s_cselect_b32 s19, s11, s41
	s_cselect_b32 s18, s10, s40
	s_add_i32 s33, 0, 0x14000
	v_add_u32_e32 v152, s0, v136
	v_add_u32_e32 v168, s33, v136
	ds_read_b128 v[140:143], v152
	ds_read_b128 v[144:147], v152 offset:1024
	ds_read_b128 v[148:151], v152 offset:2048
	ds_read_b128 v[152:155], v152 offset:3072
	ds_read_b128 v[156:159], v168
	ds_read_b128 v[160:163], v168 offset:1024
	ds_read_b128 v[164:167], v168 offset:2048
	ds_read_b128 v[168:171], v168 offset:3072
	v_lshl_add_u64 v[200:201], s[14:15], 0, v[132:133]
	s_add_i32 m0, s23, 0xc000
	ds_read_b128 v[172:175], v139
	ds_read_b128 v[176:179], v139 offset:1024
	ds_read_b128 v[180:183], v139 offset:2048
	ds_read_b128 v[184:187], v139 offset:3072
	ds_read_b128 v[188:191], v139 offset:4096
	ds_read_b128 v[192:195], v139 offset:5120
	ds_read_b128 v[196:199], v139 offset:6144
	ds_read_b128 v[208:211], v139 offset:7168
	global_load_lds_dwordx4 v[200:201], off
	v_lshl_add_u64 v[200:201], s[14:15], 0, v[134:135]
	s_add_i32 m0, s23, 0xe000
	s_nop 0
	global_load_lds_dwordx4 v[200:201], off
	s_waitcnt vmcnt(8)
	s_waitcnt lgkmcnt(0)
	s_setprio 1
	s_barrier
	v_mfma_f32_16x16x32_bf16 v[126:129], v[140:143], v[172:175], v[126:129]
	v_mfma_f32_16x16x32_bf16 v[122:125], v[148:151], v[172:175], v[122:125]
	v_mfma_f32_16x16x32_bf16 v[118:121], v[140:143], v[180:183], v[118:121]
	v_mfma_f32_16x16x32_bf16 v[114:117], v[148:151], v[180:183], v[114:117]
	v_mfma_f32_16x16x32_bf16 v[106:109], v[140:143], v[188:191], v[106:109]
	v_mfma_f32_16x16x32_bf16 v[98:101], v[148:151], v[188:191], v[98:101]
	v_mfma_f32_16x16x32_bf16 v[90:93], v[140:143], v[196:199], v[90:93]
	v_mfma_f32_16x16x32_bf16 v[82:85], v[148:151], v[196:199], v[82:85]
	v_mfma_f32_16x16x32_bf16 v[126:129], v[144:147], v[176:179], v[126:129]
	v_mfma_f32_16x16x32_bf16 v[122:125], v[152:155], v[176:179], v[122:125]
	v_mfma_f32_16x16x32_bf16 v[118:121], v[144:147], v[184:187], v[118:121]
	v_mfma_f32_16x16x32_bf16 v[114:117], v[152:155], v[184:187], v[114:117]
	v_mfma_f32_16x16x32_bf16 v[106:109], v[144:147], v[192:195], v[106:109]
	v_mfma_f32_16x16x32_bf16 v[98:101], v[152:155], v[192:195], v[98:101]
	v_mfma_f32_16x16x32_bf16 v[90:93], v[144:147], v[208:211], v[90:93]
	v_mfma_f32_16x16x32_bf16 v[82:85], v[152:155], v[208:211], v[82:85]
	s_setprio 0
	s_setprio 1
	v_mfma_f32_16x16x32_bf16 v[110:113], v[156:159], v[172:175], v[110:113]
	v_mfma_f32_16x16x32_bf16 v[102:105], v[164:167], v[172:175], v[102:105]
	v_mfma_f32_16x16x32_bf16 v[94:97], v[156:159], v[180:183], v[94:97]
	v_mfma_f32_16x16x32_bf16 v[86:89], v[164:167], v[180:183], v[86:89]
	v_mfma_f32_16x16x32_bf16 v[78:81], v[156:159], v[188:191], v[78:81]
	v_mfma_f32_16x16x32_bf16 v[74:77], v[164:167], v[188:191], v[74:77]
	v_mfma_f32_16x16x32_bf16 v[70:73], v[156:159], v[196:199], v[70:73]
	v_mfma_f32_16x16x32_bf16 v[66:69], v[164:167], v[196:199], v[66:69]
	v_mfma_f32_16x16x32_bf16 v[110:113], v[160:163], v[176:179], v[110:113]
	v_mfma_f32_16x16x32_bf16 v[102:105], v[168:171], v[176:179], v[102:105]
	v_mfma_f32_16x16x32_bf16 v[94:97], v[160:163], v[184:187], v[94:97]
	v_mfma_f32_16x16x32_bf16 v[86:89], v[168:171], v[184:187], v[86:89]
	v_mfma_f32_16x16x32_bf16 v[78:81], v[160:163], v[192:195], v[78:81]
	v_mfma_f32_16x16x32_bf16 v[74:77], v[168:171], v[192:195], v[74:77]
	v_mfma_f32_16x16x32_bf16 v[70:73], v[160:163], v[208:211], v[70:73]
	v_mfma_f32_16x16x32_bf16 v[66:69], v[168:171], v[208:211], v[66:69]
	s_barrier
	s_setprio 0
	s_add_i32 s0, s0, s22
	v_lshl_add_u64 v[200:201], s[18:19], 0, v[202:203]
	s_mov_b32 m0, s0
	ds_read_b128 v[172:175], v139 offset:16384
	ds_read_b128 v[176:179], v139 offset:17408
	ds_read_b128 v[180:183], v139 offset:18432
	ds_read_b128 v[184:187], v139 offset:19456
	ds_read_b128 v[188:191], v139 offset:20480
	ds_read_b128 v[192:195], v139 offset:21504
	ds_read_b128 v[196:199], v139 offset:22528
	ds_read_b128 v[208:211], v139 offset:23552
	global_load_lds_dwordx4 v[200:201], off
	s_add_i32 m0, s0, 0x2000
	s_add_u32 s0, s18, 0x160000
	v_lshl_add_u64 v[204:205], s[18:19], 0, v[130:131]
	s_addc_u32 s1, s19, 0
	s_add_i32 s14, s33, s22
	global_load_lds_dwordx4 v[204:205], off
	v_lshl_add_u64 v[206:207], s[0:1], 0, v[202:203]
	s_mov_b32 m0, s14
	v_lshl_add_u64 v[212:213], s[20:21], 0, v[130:131]
	global_load_lds_dwordx4 v[206:207], off
	v_lshl_add_u64 v[206:207], s[0:1], 0, v[130:131]
	s_add_i32 m0, s14, 0x2000
	s_nop 0
	global_load_lds_dwordx4 v[206:207], off
	v_lshl_add_u64 v[206:207], s[20:21], 0, v[202:203]
	s_mov_b32 m0, s23
	s_nop 0
	global_load_lds_dwordx4 v[206:207], off
	s_mov_b32 m0, s26
	s_nop 0
	global_load_lds_dwordx4 v[212:213], off
	s_waitcnt vmcnt(8)
	s_waitcnt lgkmcnt(0)
	s_setprio 1
	s_barrier
	v_mfma_f32_16x16x32_bf16 v[62:65], v[140:143], v[172:175], v[62:65]
	v_mfma_f32_16x16x32_bf16 v[58:61], v[148:151], v[172:175], v[58:61]
	v_mfma_f32_16x16x32_bf16 v[54:57], v[140:143], v[180:183], v[54:57]
	v_mfma_f32_16x16x32_bf16 v[50:53], v[148:151], v[180:183], v[50:53]
	v_mfma_f32_16x16x32_bf16 v[38:41], v[140:143], v[188:191], v[38:41]
	v_mfma_f32_16x16x32_bf16 v[34:37], v[148:151], v[188:191], v[34:37]
	v_mfma_f32_16x16x32_bf16 v[22:25], v[140:143], v[196:199], v[22:25]
	v_mfma_f32_16x16x32_bf16 v[18:21], v[148:151], v[196:199], v[18:21]
	v_mfma_f32_16x16x32_bf16 v[62:65], v[144:147], v[176:179], v[62:65]
	v_mfma_f32_16x16x32_bf16 v[58:61], v[152:155], v[176:179], v[58:61]
	v_mfma_f32_16x16x32_bf16 v[54:57], v[144:147], v[184:187], v[54:57]
	v_mfma_f32_16x16x32_bf16 v[50:53], v[152:155], v[184:187], v[50:53]
	v_mfma_f32_16x16x32_bf16 v[38:41], v[144:147], v[192:195], v[38:41]
	v_mfma_f32_16x16x32_bf16 v[34:37], v[152:155], v[192:195], v[34:37]
	v_mfma_f32_16x16x32_bf16 v[22:25], v[144:147], v[208:211], v[22:25]
	v_mfma_f32_16x16x32_bf16 v[18:21], v[152:155], v[208:211], v[18:21]
	s_setprio 0
	s_setprio 1
	v_mfma_f32_16x16x32_bf16 v[46:49], v[156:159], v[172:175], v[46:49]
	v_mfma_f32_16x16x32_bf16 v[42:45], v[164:167], v[172:175], v[42:45]
	v_mfma_f32_16x16x32_bf16 v[30:33], v[156:159], v[180:183], v[30:33]
	v_mfma_f32_16x16x32_bf16 v[26:29], v[164:167], v[180:183], v[26:29]
	v_mfma_f32_16x16x32_bf16 v[14:17], v[156:159], v[188:191], v[14:17]
	v_mfma_f32_16x16x32_bf16 v[10:13], v[164:167], v[188:191], v[10:13]
	v_mfma_f32_16x16x32_bf16 v[6:9], v[156:159], v[196:199], v[6:9]
	v_mfma_f32_16x16x32_bf16 v[2:5], v[164:167], v[196:199], v[2:5]
	v_mfma_f32_16x16x32_bf16 v[46:49], v[160:163], v[176:179], v[46:49]
	v_mfma_f32_16x16x32_bf16 v[42:45], v[168:171], v[176:179], v[42:45]
	v_mfma_f32_16x16x32_bf16 v[30:33], v[160:163], v[184:187], v[30:33]
	v_mfma_f32_16x16x32_bf16 v[26:29], v[168:171], v[184:187], v[26:29]
	v_mfma_f32_16x16x32_bf16 v[14:17], v[160:163], v[192:195], v[14:17]
	v_mfma_f32_16x16x32_bf16 v[10:13], v[168:171], v[192:195], v[10:13]
	v_mfma_f32_16x16x32_bf16 v[6:9], v[160:163], v[208:211], v[6:9]
	v_mfma_f32_16x16x32_bf16 v[2:5], v[168:171], v[208:211], v[2:5]
	s_barrier
	s_setprio 0
	s_add_i32 s14, 0, 0x18000
	s_add_i32 s15, 0, 0x1c000
	v_add_u32_e32 v152, s14, v136
	v_add_u32_e32 v168, s15, v136
	ds_read_b128 v[140:143], v152
	ds_read_b128 v[144:147], v152 offset:1024
	ds_read_b128 v[148:151], v152 offset:2048
	ds_read_b128 v[152:155], v152 offset:3072
	ds_read_b128 v[156:159], v168
	ds_read_b128 v[160:163], v168 offset:1024
	ds_read_b128 v[164:167], v168 offset:2048
	ds_read_b128 v[168:171], v168 offset:3072
	s_add_u32 s0, s20, 0x160000
	s_addc_u32 s1, s21, 0
	s_mov_b32 m0, s27
	v_lshl_add_u64 v[214:215], s[0:1], 0, v[202:203]
	ds_read_b128 v[172:175], v139 offset:32768
	ds_read_b128 v[176:179], v139 offset:33792
	ds_read_b128 v[180:183], v139 offset:34816
	ds_read_b128 v[184:187], v139 offset:35840
	ds_read_b128 v[188:191], v139 offset:36864
	ds_read_b128 v[192:195], v139 offset:37888
	ds_read_b128 v[196:199], v139 offset:38912
	ds_read_b128 v[208:211], v139 offset:39936
	global_load_lds_dwordx4 v[214:215], off
	v_lshl_add_u64 v[214:215], s[0:1], 0, v[130:131]
	s_mov_b32 m0, s28
	s_nop 0
	global_load_lds_dwordx4 v[214:215], off
	s_waitcnt vmcnt(8)
	s_waitcnt lgkmcnt(0)
	s_setprio 1
	s_barrier
	v_mfma_f32_16x16x32_bf16 v[126:129], v[140:143], v[172:175], v[126:129]
	v_mfma_f32_16x16x32_bf16 v[122:125], v[148:151], v[172:175], v[122:125]
	v_mfma_f32_16x16x32_bf16 v[118:121], v[140:143], v[180:183], v[118:121]
	v_mfma_f32_16x16x32_bf16 v[114:117], v[148:151], v[180:183], v[114:117]
	v_mfma_f32_16x16x32_bf16 v[106:109], v[140:143], v[188:191], v[106:109]
	v_mfma_f32_16x16x32_bf16 v[98:101], v[148:151], v[188:191], v[98:101]
	v_mfma_f32_16x16x32_bf16 v[90:93], v[140:143], v[196:199], v[90:93]
	v_mfma_f32_16x16x32_bf16 v[82:85], v[148:151], v[196:199], v[82:85]
	v_mfma_f32_16x16x32_bf16 v[126:129], v[144:147], v[176:179], v[126:129]
	v_mfma_f32_16x16x32_bf16 v[122:125], v[152:155], v[176:179], v[122:125]
	v_mfma_f32_16x16x32_bf16 v[118:121], v[144:147], v[184:187], v[118:121]
	v_mfma_f32_16x16x32_bf16 v[114:117], v[152:155], v[184:187], v[114:117]
	v_mfma_f32_16x16x32_bf16 v[106:109], v[144:147], v[192:195], v[106:109]
	v_mfma_f32_16x16x32_bf16 v[98:101], v[152:155], v[192:195], v[98:101]
	v_mfma_f32_16x16x32_bf16 v[90:93], v[144:147], v[208:211], v[90:93]
	v_mfma_f32_16x16x32_bf16 v[82:85], v[152:155], v[208:211], v[82:85]
	s_setprio 0
	s_setprio 1
	v_mfma_f32_16x16x32_bf16 v[110:113], v[156:159], v[172:175], v[110:113]
	v_mfma_f32_16x16x32_bf16 v[102:105], v[164:167], v[172:175], v[102:105]
	v_mfma_f32_16x16x32_bf16 v[94:97], v[156:159], v[180:183], v[94:97]
	v_mfma_f32_16x16x32_bf16 v[86:89], v[164:167], v[180:183], v[86:89]
	v_mfma_f32_16x16x32_bf16 v[78:81], v[156:159], v[188:191], v[78:81]
	v_mfma_f32_16x16x32_bf16 v[74:77], v[164:167], v[188:191], v[74:77]
	v_mfma_f32_16x16x32_bf16 v[70:73], v[156:159], v[196:199], v[70:73]
	v_mfma_f32_16x16x32_bf16 v[66:69], v[164:167], v[196:199], v[66:69]
	v_mfma_f32_16x16x32_bf16 v[110:113], v[160:163], v[176:179], v[110:113]
	v_mfma_f32_16x16x32_bf16 v[102:105], v[168:171], v[176:179], v[102:105]
	v_mfma_f32_16x16x32_bf16 v[94:97], v[160:163], v[184:187], v[94:97]
	v_mfma_f32_16x16x32_bf16 v[86:89], v[168:171], v[184:187], v[86:89]
	v_mfma_f32_16x16x32_bf16 v[78:81], v[160:163], v[192:195], v[78:81]
	v_mfma_f32_16x16x32_bf16 v[74:77], v[168:171], v[192:195], v[74:77]
	v_mfma_f32_16x16x32_bf16 v[70:73], v[160:163], v[208:211], v[70:73]
	v_mfma_f32_16x16x32_bf16 v[66:69], v[168:171], v[208:211], v[66:69]
	s_barrier
	s_setprio 0
	s_add_i32 s0, s14, s22
	v_lshl_add_u64 v[200:201], v[200:201], 0, s[80:81]
	s_mov_b32 m0, s0
	ds_read_b128 v[172:175], v139 offset:49152
	ds_read_b128 v[176:179], v139 offset:50176
	ds_read_b128 v[180:183], v139 offset:51200
	ds_read_b128 v[184:187], v139 offset:52224
	ds_read_b128 v[188:191], v139 offset:53248
	ds_read_b128 v[192:195], v139 offset:54272
	ds_read_b128 v[196:199], v139 offset:55296
	ds_read_b128 v[208:211], v139 offset:56320
	global_load_lds_dwordx4 v[200:201], off
	s_add_i32 m0, s0, 0x2000
	s_add_u32 s0, s18, 0x160080
	v_lshl_add_u64 v[200:201], v[204:205], 0, s[80:81]
	s_addc_u32 s1, s19, 0
	s_add_i32 s14, s15, s22
	global_load_lds_dwordx4 v[200:201], off
	v_lshl_add_u64 v[200:201], s[0:1], 0, v[202:203]
	s_mov_b32 m0, s14
	s_nop 0
	global_load_lds_dwordx4 v[200:201], off
	v_lshl_add_u64 v[200:201], s[0:1], 0, v[130:131]
	s_add_i32 m0, s14, 0x2000
	s_nop 0
	global_load_lds_dwordx4 v[200:201], off
	v_lshl_add_u64 v[200:201], v[206:207], 0, s[80:81]
	s_mov_b32 m0, s29
	s_nop 0
	global_load_lds_dwordx4 v[200:201], off
	v_lshl_add_u64 v[200:201], v[212:213], 0, s[80:81]
	s_mov_b32 m0, s30
	s_nop 0
	global_load_lds_dwordx4 v[200:201], off
	s_waitcnt vmcnt(8)
	s_waitcnt lgkmcnt(0)
	s_setprio 1
	s_barrier
	v_mfma_f32_16x16x32_bf16 v[62:65], v[140:143], v[172:175], v[62:65]
	v_mfma_f32_16x16x32_bf16 v[58:61], v[148:151], v[172:175], v[58:61]
	v_mfma_f32_16x16x32_bf16 v[54:57], v[140:143], v[180:183], v[54:57]
	v_mfma_f32_16x16x32_bf16 v[50:53], v[148:151], v[180:183], v[50:53]
	v_mfma_f32_16x16x32_bf16 v[38:41], v[140:143], v[188:191], v[38:41]
	v_mfma_f32_16x16x32_bf16 v[34:37], v[148:151], v[188:191], v[34:37]
	v_mfma_f32_16x16x32_bf16 v[22:25], v[140:143], v[196:199], v[22:25]
	v_mfma_f32_16x16x32_bf16 v[18:21], v[148:151], v[196:199], v[18:21]
	v_mfma_f32_16x16x32_bf16 v[62:65], v[144:147], v[176:179], v[62:65]
	v_mfma_f32_16x16x32_bf16 v[58:61], v[152:155], v[176:179], v[58:61]
	v_mfma_f32_16x16x32_bf16 v[54:57], v[144:147], v[184:187], v[54:57]
	v_mfma_f32_16x16x32_bf16 v[50:53], v[152:155], v[184:187], v[50:53]
	v_mfma_f32_16x16x32_bf16 v[38:41], v[144:147], v[192:195], v[38:41]
	v_mfma_f32_16x16x32_bf16 v[34:37], v[152:155], v[192:195], v[34:37]
	v_mfma_f32_16x16x32_bf16 v[22:25], v[144:147], v[208:211], v[22:25]
	v_mfma_f32_16x16x32_bf16 v[18:21], v[152:155], v[208:211], v[18:21]
	s_setprio 0
	s_setprio 1
	v_mfma_f32_16x16x32_bf16 v[46:49], v[156:159], v[172:175], v[46:49]
	v_mfma_f32_16x16x32_bf16 v[42:45], v[164:167], v[172:175], v[42:45]
	v_mfma_f32_16x16x32_bf16 v[30:33], v[156:159], v[180:183], v[30:33]
	v_mfma_f32_16x16x32_bf16 v[26:29], v[164:167], v[180:183], v[26:29]
	v_mfma_f32_16x16x32_bf16 v[14:17], v[156:159], v[188:191], v[14:17]
	v_mfma_f32_16x16x32_bf16 v[10:13], v[164:167], v[188:191], v[10:13]
	v_mfma_f32_16x16x32_bf16 v[6:9], v[156:159], v[196:199], v[6:9]
	v_mfma_f32_16x16x32_bf16 v[2:5], v[164:167], v[196:199], v[2:5]
	v_mfma_f32_16x16x32_bf16 v[46:49], v[160:163], v[176:179], v[46:49]
	v_mfma_f32_16x16x32_bf16 v[42:45], v[168:171], v[176:179], v[42:45]
	v_mfma_f32_16x16x32_bf16 v[30:33], v[160:163], v[184:187], v[30:33]
	v_mfma_f32_16x16x32_bf16 v[26:29], v[168:171], v[184:187], v[26:29]
	v_mfma_f32_16x16x32_bf16 v[14:17], v[160:163], v[192:195], v[14:17]
	v_mfma_f32_16x16x32_bf16 v[10:13], v[168:171], v[192:195], v[10:13]
	v_mfma_f32_16x16x32_bf16 v[6:9], v[160:163], v[208:211], v[6:9]
	v_mfma_f32_16x16x32_bf16 v[2:5], v[168:171], v[208:211], v[2:5]
	s_barrier
	s_setprio 0
	s_add_i32 s49, s49, 2
	s_add_u32 s40, s40, 0x100
	s_addc_u32 s41, s41, 0
	s_cmp_gt_u32 s49, 5
	s_mov_b64 s[14:15], s[16:17]
	s_cbranch_scc0 .LBB0_1739
	s_and_b64 vcc, exec, s[6:7]
	s_cbranch_vccz .LBB0_1742
	s_barrier
